# MFMA order: serpentine path where consecutive MFMAs share the accumulator or one operand register (half the accumulators take k-steps reversed); rest of stack unchanged
# baseline (speedup 1.0000x reference)
.LBB0_243:
	s_lshl_b32 s24, s12, 20
	s_and_b32 s24, s24, 0xff00000
	v_readlane_b32 s36, v248, 22
	v_readlane_b32 s37, v248, 23
	s_add_u32 s24, s36, s24
	s_addc_u32 s35, s37, 0
	s_lshr_b32 s36, s12, 13
	s_and_b32 s36, s36, 0x7ff80
	s_add_u32 s54, s24, s36
	s_addc_u32 s55, s35, 0
	s_lshl_b32 s24, s12, 12
	s_and_b32 s24, s24, 0xff00000
	v_readlane_b32 s38, v248, 24
	v_readlane_b32 s39, v248, 25
	s_add_u32 s24, s38, s24
	s_addc_u32 s35, s39, 0
	s_add_u32 s70, s24, s36
	s_addc_u32 s71, s35, 0
	s_cmp_lt_i32 s1, 1
	v_cmp_gt_i64_e64 s[72:73], s[12:13], -1
	s_cbranch_scc1 .LBB0_253
	s_and_b64 s[12:13], s[72:73], exec
	s_cselect_b32 s24, s55, s5
	s_cselect_b32 s35, s54, s4
	s_cselect_b32 s36, s71, s3
	s_cselect_b32 s37, s70, s2
	s_add_i32 s38, s1, -2
	s_add_u32 s4, s4, 0x80080
	s_addc_u32 s5, s5, 0
	s_add_u32 s39, s2, 0x100
	s_addc_u32 s40, s3, 0
	s_mov_b32 s2, 0
	v_add_u32_e32 v138, s29, v183
	ds_read_b128 v[144:147], v138
	ds_read_b128 v[148:151], v138 offset:1024
	ds_read_b128 v[152:155], v138 offset:2048
	ds_read_b128 v[156:159], v138 offset:3072
	v_add_u32_e32 v138, s34, v183
	ds_read_b128 v[160:163], v138
	ds_read_b128 v[164:167], v138 offset:1024
	ds_read_b128 v[186:189], v138 offset:2048
	ds_read_b128 v[190:193], v138 offset:3072
	s_add_i32 s41, s2, 2
	s_add_u32 s3, s4, 0xfff80080
	s_addc_u32 s12, s5, -1
	s_cmp_eq_u32 s38, s2
	s_cselect_b32 s2, s37, s39
	s_cselect_b32 s13, s24, s12
	s_cselect_b32 s12, s35, s3
	s_cselect_b32 s3, s36, s40
	v_lshl_add_u64 v[228:229], s[4:5], 0, v[140:141]
	s_add_i32 m0, s17, 0xc000
	ds_read_b128 v[194:197], v185
	ds_read_b128 v[198:201], v185 offset:1024
	ds_read_b128 v[202:205], v185 offset:2048
	ds_read_b128 v[208:211], v185 offset:3072
	ds_read_b128 v[212:215], v185 offset:4096
	ds_read_b128 v[216:219], v185 offset:5120
	ds_read_b128 v[220:223], v185 offset:6144
	ds_read_b128 v[224:227], v185 offset:7168
	global_load_lds_dwordx4 v[228:229], off
	v_lshl_add_u64 v[228:229], s[4:5], 0, v[142:143]
	s_add_i32 m0, s17, 0xe000
	s_nop 0
	global_load_lds_dwordx4 v[228:229], off
	s_waitcnt vmcnt(8)
	s_waitcnt lgkmcnt(0)
	s_barrier
	s_setprio 1
	s_waitcnt lgkmcnt(0)
	v_mfma_i32_16x16x64_i8 v[126:129], v[144:147], v[194:197], 0
	v_mfma_i32_16x16x64_i8 v[126:129], v[148:151], v[198:201], v[126:129]
	v_mfma_i32_16x16x64_i8 v[122:125], v[156:159], v[198:201], 0
	v_mfma_i32_16x16x64_i8 v[122:125], v[152:155], v[194:197], v[122:125]
	v_mfma_i32_16x16x64_i8 v[114:117], v[152:155], v[202:205], 0
	v_mfma_i32_16x16x64_i8 v[114:117], v[156:159], v[208:211], v[114:117]
	v_mfma_i32_16x16x64_i8 v[118:121], v[148:151], v[208:211], 0
	v_mfma_i32_16x16x64_i8 v[118:121], v[144:147], v[202:205], v[118:121]
	v_mfma_i32_16x16x64_i8 v[110:113], v[144:147], v[212:215], 0
	v_mfma_i32_16x16x64_i8 v[110:113], v[148:151], v[216:219], v[110:113]
	v_mfma_i32_16x16x64_i8 v[106:109], v[156:159], v[216:219], 0
	v_mfma_i32_16x16x64_i8 v[106:109], v[152:155], v[212:215], v[106:109]
	v_mfma_i32_16x16x64_i8 v[98:101], v[152:155], v[220:223], 0
	v_mfma_i32_16x16x64_i8 v[98:101], v[156:159], v[224:227], v[98:101]
	v_mfma_i32_16x16x64_i8 v[102:105], v[148:151], v[224:227], 0
	v_mfma_i32_16x16x64_i8 v[102:105], v[144:147], v[220:223], v[102:105]
	s_setprio 0
	s_setprio 1
	v_mfma_i32_16x16x64_i8 v[94:97], v[160:163], v[194:197], 0
	v_mfma_i32_16x16x64_i8 v[94:97], v[164:167], v[198:201], v[94:97]
	v_mfma_i32_16x16x64_i8 v[90:93], v[190:193], v[198:201], 0
	v_mfma_i32_16x16x64_i8 v[90:93], v[186:189], v[194:197], v[90:93]
	v_mfma_i32_16x16x64_i8 v[82:85], v[186:189], v[202:205], 0
	v_mfma_i32_16x16x64_i8 v[82:85], v[190:193], v[208:211], v[82:85]
	v_mfma_i32_16x16x64_i8 v[86:89], v[164:167], v[208:211], 0
	v_mfma_i32_16x16x64_i8 v[86:89], v[160:163], v[202:205], v[86:89]
	v_mfma_i32_16x16x64_i8 v[78:81], v[160:163], v[212:215], 0
	v_mfma_i32_16x16x64_i8 v[78:81], v[164:167], v[216:219], v[78:81]
	v_mfma_i32_16x16x64_i8 v[74:77], v[190:193], v[216:219], 0
	v_mfma_i32_16x16x64_i8 v[74:77], v[186:189], v[212:215], v[74:77]
	v_mfma_i32_16x16x64_i8 v[66:69], v[186:189], v[220:223], 0
	v_mfma_i32_16x16x64_i8 v[66:69], v[190:193], v[224:227], v[66:69]
	v_mfma_i32_16x16x64_i8 v[70:73], v[164:167], v[224:227], 0
	v_mfma_i32_16x16x64_i8 v[70:73], v[160:163], v[220:223], v[70:73]
	s_setprio 0
	s_barrier
	s_add_i32 s42, s29, s16
	v_lshl_add_u64 v[228:229], s[2:3], 0, v[132:133]
	s_mov_b32 m0, s42
	ds_read_b128 v[194:197], v185 offset:16384
	ds_read_b128 v[198:201], v185 offset:17408
	ds_read_b128 v[202:205], v185 offset:18432
	ds_read_b128 v[208:211], v185 offset:19456
	ds_read_b128 v[212:215], v185 offset:20480
	ds_read_b128 v[216:219], v185 offset:21504
	ds_read_b128 v[220:223], v185 offset:22528
	ds_read_b128 v[224:227], v185 offset:23552
	global_load_lds_dwordx4 v[228:229], off
	s_add_i32 m0, s42, 0x2000
	s_add_u32 s42, s2, 0x80000
	v_lshl_add_u64 v[230:231], s[2:3], 0, v[136:137]
	s_addc_u32 s43, s3, 0
	s_add_i32 s44, s34, s16
	global_load_lds_dwordx4 v[230:231], off
	v_lshl_add_u64 v[232:233], s[42:43], 0, v[132:133]
	s_mov_b32 m0, s44
	v_lshl_add_u64 v[234:235], s[12:13], 0, v[134:135]
	global_load_lds_dwordx4 v[232:233], off
	v_lshl_add_u64 v[232:233], s[42:43], 0, v[136:137]
	s_add_i32 m0, s44, 0x2000
	s_nop 0
	global_load_lds_dwordx4 v[232:233], off
	v_lshl_add_u64 v[232:233], s[12:13], 0, v[130:131]
	s_mov_b32 m0, s17
	s_nop 0
	global_load_lds_dwordx4 v[232:233], off
	s_mov_b32 m0, s18
	s_nop 0
	global_load_lds_dwordx4 v[234:235], off
	s_waitcnt vmcnt(8)
	s_waitcnt lgkmcnt(0)
	s_barrier
	s_setprio 1
	s_waitcnt lgkmcnt(0)
	v_mfma_i32_16x16x64_i8 v[62:65], v[144:147], v[194:197], 0
	v_mfma_i32_16x16x64_i8 v[62:65], v[148:151], v[198:201], v[62:65]
	v_mfma_i32_16x16x64_i8 v[58:61], v[156:159], v[198:201], 0
	v_mfma_i32_16x16x64_i8 v[58:61], v[152:155], v[194:197], v[58:61]
	v_mfma_i32_16x16x64_i8 v[50:53], v[152:155], v[202:205], 0
	v_mfma_i32_16x16x64_i8 v[50:53], v[156:159], v[208:211], v[50:53]
	v_mfma_i32_16x16x64_i8 v[54:57], v[148:151], v[208:211], 0
	v_mfma_i32_16x16x64_i8 v[54:57], v[144:147], v[202:205], v[54:57]
	v_mfma_i32_16x16x64_i8 v[46:49], v[144:147], v[212:215], 0
	v_mfma_i32_16x16x64_i8 v[46:49], v[148:151], v[216:219], v[46:49]
	v_mfma_i32_16x16x64_i8 v[42:45], v[156:159], v[216:219], 0
	v_mfma_i32_16x16x64_i8 v[42:45], v[152:155], v[212:215], v[42:45]
	v_mfma_i32_16x16x64_i8 v[34:37], v[152:155], v[220:223], 0
	v_mfma_i32_16x16x64_i8 v[34:37], v[156:159], v[224:227], v[34:37]
	v_mfma_i32_16x16x64_i8 v[38:41], v[148:151], v[224:227], 0
	v_mfma_i32_16x16x64_i8 v[38:41], v[144:147], v[220:223], v[38:41]
	s_setprio 0
	s_setprio 1
	v_mfma_i32_16x16x64_i8 v[30:33], v[160:163], v[194:197], 0
	v_mfma_i32_16x16x64_i8 v[30:33], v[164:167], v[198:201], v[30:33]
	v_mfma_i32_16x16x64_i8 v[26:29], v[190:193], v[198:201], 0
	v_mfma_i32_16x16x64_i8 v[26:29], v[186:189], v[194:197], v[26:29]
	v_mfma_i32_16x16x64_i8 v[18:21], v[186:189], v[202:205], 0
	v_mfma_i32_16x16x64_i8 v[18:21], v[190:193], v[208:211], v[18:21]
	v_mfma_i32_16x16x64_i8 v[22:25], v[164:167], v[208:211], 0
	v_mfma_i32_16x16x64_i8 v[22:25], v[160:163], v[202:205], v[22:25]
	v_mfma_i32_16x16x64_i8 v[14:17], v[160:163], v[212:215], 0
	v_mfma_i32_16x16x64_i8 v[14:17], v[164:167], v[216:219], v[14:17]
	v_mfma_i32_16x16x64_i8 v[10:13], v[190:193], v[216:219], 0
	v_mfma_i32_16x16x64_i8 v[10:13], v[186:189], v[212:215], v[10:13]
	v_mfma_i32_16x16x64_i8 v[2:5], v[186:189], v[220:223], 0
	v_mfma_i32_16x16x64_i8 v[2:5], v[190:193], v[224:227], v[2:5]
	v_mfma_i32_16x16x64_i8 v[6:9], v[164:167], v[224:227], 0
	v_mfma_i32_16x16x64_i8 v[6:9], v[160:163], v[220:223], v[6:9]
	s_setprio 0
	s_barrier
	s_add_i32 s42, 0, 0x18000
	v_add_u32_e32 v138, s42, v183
	s_add_i32 s43, 0, 0x1c000
	ds_read_b128 v[144:147], v138
	ds_read_b128 v[148:151], v138 offset:1024
	ds_read_b128 v[152:155], v138 offset:2048
	ds_read_b128 v[156:159], v138 offset:3072
	v_add_u32_e32 v138, s43, v183
	ds_read_b128 v[160:163], v138
	ds_read_b128 v[164:167], v138 offset:1024
	ds_read_b128 v[186:189], v138 offset:2048
	ds_read_b128 v[190:193], v138 offset:3072
	s_add_u32 s12, s12, 0x80000
	s_addc_u32 s13, s13, 0
	s_mov_b32 m0, s19
	v_lshl_add_u64 v[236:237], s[12:13], 0, v[130:131]
	ds_read_b128 v[194:197], v185 offset:32768
	ds_read_b128 v[198:201], v185 offset:33792
	ds_read_b128 v[202:205], v185 offset:34816
	ds_read_b128 v[208:211], v185 offset:35840
	ds_read_b128 v[212:215], v185 offset:36864
	ds_read_b128 v[216:219], v185 offset:37888
	ds_read_b128 v[220:223], v185 offset:38912
	ds_read_b128 v[224:227], v185 offset:39936
	global_load_lds_dwordx4 v[236:237], off
	v_lshl_add_u64 v[236:237], s[12:13], 0, v[134:135]
	s_mov_b32 m0, s20
	s_nop 0
	global_load_lds_dwordx4 v[236:237], off
	s_waitcnt vmcnt(8)
	s_waitcnt lgkmcnt(0)
	s_barrier
	s_setprio 1
	s_waitcnt lgkmcnt(0)
	v_mfma_i32_16x16x64_i8 v[126:129], v[144:147], v[194:197], v[126:129]
	v_mfma_i32_16x16x64_i8 v[126:129], v[148:151], v[198:201], v[126:129]
	v_mfma_i32_16x16x64_i8 v[122:125], v[156:159], v[198:201], v[122:125]
	v_mfma_i32_16x16x64_i8 v[122:125], v[152:155], v[194:197], v[122:125]
	v_mfma_i32_16x16x64_i8 v[114:117], v[152:155], v[202:205], v[114:117]
	v_mfma_i32_16x16x64_i8 v[114:117], v[156:159], v[208:211], v[114:117]
	v_mfma_i32_16x16x64_i8 v[118:121], v[148:151], v[208:211], v[118:121]
	v_mfma_i32_16x16x64_i8 v[118:121], v[144:147], v[202:205], v[118:121]
	v_mfma_i32_16x16x64_i8 v[110:113], v[144:147], v[212:215], v[110:113]
	v_mfma_i32_16x16x64_i8 v[110:113], v[148:151], v[216:219], v[110:113]
	v_mfma_i32_16x16x64_i8 v[106:109], v[156:159], v[216:219], v[106:109]
	v_mfma_i32_16x16x64_i8 v[106:109], v[152:155], v[212:215], v[106:109]
	v_mfma_i32_16x16x64_i8 v[98:101], v[152:155], v[220:223], v[98:101]
	v_mfma_i32_16x16x64_i8 v[98:101], v[156:159], v[224:227], v[98:101]
	v_mfma_i32_16x16x64_i8 v[102:105], v[148:151], v[224:227], v[102:105]
	v_mfma_i32_16x16x64_i8 v[102:105], v[144:147], v[220:223], v[102:105]
	s_setprio 0
	s_setprio 1
	v_mfma_i32_16x16x64_i8 v[94:97], v[160:163], v[194:197], v[94:97]
	v_mfma_i32_16x16x64_i8 v[94:97], v[164:167], v[198:201], v[94:97]
	v_mfma_i32_16x16x64_i8 v[90:93], v[190:193], v[198:201], v[90:93]
	v_mfma_i32_16x16x64_i8 v[90:93], v[186:189], v[194:197], v[90:93]
	v_mfma_i32_16x16x64_i8 v[82:85], v[186:189], v[202:205], v[82:85]
	v_mfma_i32_16x16x64_i8 v[82:85], v[190:193], v[208:211], v[82:85]
	v_mfma_i32_16x16x64_i8 v[86:89], v[164:167], v[208:211], v[86:89]
	v_mfma_i32_16x16x64_i8 v[86:89], v[160:163], v[202:205], v[86:89]
	v_mfma_i32_16x16x64_i8 v[78:81], v[160:163], v[212:215], v[78:81]
	v_mfma_i32_16x16x64_i8 v[78:81], v[164:167], v[216:219], v[78:81]
	v_mfma_i32_16x16x64_i8 v[74:77], v[190:193], v[216:219], v[74:77]
	v_mfma_i32_16x16x64_i8 v[74:77], v[186:189], v[212:215], v[74:77]
	v_mfma_i32_16x16x64_i8 v[66:69], v[186:189], v[220:223], v[66:69]
	v_mfma_i32_16x16x64_i8 v[66:69], v[190:193], v[224:227], v[66:69]
	v_mfma_i32_16x16x64_i8 v[70:73], v[164:167], v[224:227], v[70:73]
	v_mfma_i32_16x16x64_i8 v[70:73], v[160:163], v[220:223], v[70:73]
	s_setprio 0
	s_barrier
	s_add_i32 s12, s42, s16
	v_lshl_add_u64 v[228:229], v[228:229], 0, s[10:11]
	s_mov_b32 m0, s12
	ds_read_b128 v[194:197], v185 offset:49152
	ds_read_b128 v[198:201], v185 offset:50176
	ds_read_b128 v[202:205], v185 offset:51200
	ds_read_b128 v[208:211], v185 offset:52224
	ds_read_b128 v[212:215], v185 offset:53248
	ds_read_b128 v[216:219], v185 offset:54272
	ds_read_b128 v[220:223], v185 offset:55296
	ds_read_b128 v[224:227], v185 offset:56320
	global_load_lds_dwordx4 v[228:229], off
	s_add_i32 m0, s12, 0x2000
	s_add_u32 s2, s2, 0x80080
	v_lshl_add_u64 v[228:229], v[230:231], 0, s[10:11]
	s_addc_u32 s3, s3, 0
	s_add_i32 s12, s43, s16
	global_load_lds_dwordx4 v[228:229], off
	v_lshl_add_u64 v[228:229], s[2:3], 0, v[132:133]
	s_mov_b32 m0, s12
	s_nop 0
	global_load_lds_dwordx4 v[228:229], off
	v_lshl_add_u64 v[228:229], s[2:3], 0, v[136:137]
	s_add_i32 m0, s12, 0x2000
	s_nop 0
	global_load_lds_dwordx4 v[228:229], off
	v_lshl_add_u64 v[228:229], v[232:233], 0, s[10:11]
	s_mov_b32 m0, s22
	s_nop 0
	global_load_lds_dwordx4 v[228:229], off
	v_lshl_add_u64 v[228:229], v[234:235], 0, s[10:11]
	s_mov_b32 m0, s23
	s_nop 0
	global_load_lds_dwordx4 v[228:229], off
	s_waitcnt vmcnt(8)
	s_waitcnt lgkmcnt(0)
	s_barrier
	s_setprio 1
	s_waitcnt lgkmcnt(0)
	v_mfma_i32_16x16x64_i8 v[62:65], v[144:147], v[194:197], v[62:65]
	v_mfma_i32_16x16x64_i8 v[62:65], v[148:151], v[198:201], v[62:65]
	v_mfma_i32_16x16x64_i8 v[58:61], v[156:159], v[198:201], v[58:61]
	v_mfma_i32_16x16x64_i8 v[58:61], v[152:155], v[194:197], v[58:61]
	v_mfma_i32_16x16x64_i8 v[50:53], v[152:155], v[202:205], v[50:53]
	v_mfma_i32_16x16x64_i8 v[50:53], v[156:159], v[208:211], v[50:53]
	v_mfma_i32_16x16x64_i8 v[54:57], v[148:151], v[208:211], v[54:57]
	v_mfma_i32_16x16x64_i8 v[54:57], v[144:147], v[202:205], v[54:57]
	v_mfma_i32_16x16x64_i8 v[46:49], v[144:147], v[212:215], v[46:49]
	v_mfma_i32_16x16x64_i8 v[46:49], v[148:151], v[216:219], v[46:49]
	v_mfma_i32_16x16x64_i8 v[42:45], v[156:159], v[216:219], v[42:45]
	v_mfma_i32_16x16x64_i8 v[42:45], v[152:155], v[212:215], v[42:45]
	v_mfma_i32_16x16x64_i8 v[34:37], v[152:155], v[220:223], v[34:37]
	v_mfma_i32_16x16x64_i8 v[34:37], v[156:159], v[224:227], v[34:37]
	v_mfma_i32_16x16x64_i8 v[38:41], v[148:151], v[224:227], v[38:41]
	v_mfma_i32_16x16x64_i8 v[38:41], v[144:147], v[220:223], v[38:41]
	s_setprio 0
	s_setprio 1
	v_mfma_i32_16x16x64_i8 v[30:33], v[160:163], v[194:197], v[30:33]
	v_mfma_i32_16x16x64_i8 v[30:33], v[164:167], v[198:201], v[30:33]
	v_mfma_i32_16x16x64_i8 v[26:29], v[190:193], v[198:201], v[26:29]
	v_mfma_i32_16x16x64_i8 v[26:29], v[186:189], v[194:197], v[26:29]
	v_mfma_i32_16x16x64_i8 v[18:21], v[186:189], v[202:205], v[18:21]
	v_mfma_i32_16x16x64_i8 v[18:21], v[190:193], v[208:211], v[18:21]
	v_mfma_i32_16x16x64_i8 v[22:25], v[164:167], v[208:211], v[22:25]
	v_mfma_i32_16x16x64_i8 v[22:25], v[160:163], v[202:205], v[22:25]
	v_mfma_i32_16x16x64_i8 v[14:17], v[160:163], v[212:215], v[14:17]
	v_mfma_i32_16x16x64_i8 v[14:17], v[164:167], v[216:219], v[14:17]
	v_mfma_i32_16x16x64_i8 v[10:13], v[190:193], v[216:219], v[10:13]
	v_mfma_i32_16x16x64_i8 v[10:13], v[186:189], v[212:215], v[10:13]
	v_mfma_i32_16x16x64_i8 v[2:5], v[186:189], v[220:223], v[2:5]
	v_mfma_i32_16x16x64_i8 v[2:5], v[190:193], v[224:227], v[2:5]
	v_mfma_i32_16x16x64_i8 v[6:9], v[164:167], v[224:227], v[6:9]
	v_mfma_i32_16x16x64_i8 v[6:9], v[160:163], v[220:223], v[6:9]
	s_setprio 0
	s_barrier
	s_add_u32 s4, s4, 0x100
	s_addc_u32 s5, s5, 0
	s_add_u32 s39, s39, 0x100
	s_addc_u32 s40, s40, 0
	s_cmp_ge_i32 s41, s1
	s_mov_b32 s2, s41
	s_cbranch_scc1 .Lkpeel_exit_0
.LBB0_245:
	v_add_u32_e32 v138, s29, v183
	ds_read_b128 v[144:147], v138
	ds_read_b128 v[148:151], v138 offset:1024
	ds_read_b128 v[152:155], v138 offset:2048
	ds_read_b128 v[156:159], v138 offset:3072
	v_add_u32_e32 v138, s34, v183
	ds_read_b128 v[160:163], v138
	ds_read_b128 v[164:167], v138 offset:1024
	ds_read_b128 v[186:189], v138 offset:2048
	ds_read_b128 v[190:193], v138 offset:3072
	s_add_i32 s41, s2, 2
	s_add_u32 s3, s4, 0xfff80080
	s_addc_u32 s12, s5, -1
	s_cmp_eq_u32 s38, s2
	s_cselect_b32 s2, s37, s39
	s_cselect_b32 s13, s24, s12
	s_cselect_b32 s12, s35, s3
	s_cselect_b32 s3, s36, s40
	v_lshl_add_u64 v[228:229], s[4:5], 0, v[140:141]
	s_add_i32 m0, s17, 0xc000
	ds_read_b128 v[194:197], v185
	ds_read_b128 v[198:201], v185 offset:1024
	ds_read_b128 v[202:205], v185 offset:2048
	ds_read_b128 v[208:211], v185 offset:3072
	ds_read_b128 v[212:215], v185 offset:4096
	ds_read_b128 v[216:219], v185 offset:5120
	ds_read_b128 v[220:223], v185 offset:6144
	ds_read_b128 v[224:227], v185 offset:7168
	global_load_lds_dwordx4 v[228:229], off
	v_lshl_add_u64 v[228:229], s[4:5], 0, v[142:143]
	s_add_i32 m0, s17, 0xe000
	s_nop 0
	global_load_lds_dwordx4 v[228:229], off
	s_waitcnt vmcnt(8)
	s_waitcnt lgkmcnt(0)
	s_barrier
	s_setprio 1
	s_waitcnt lgkmcnt(0)
	v_mfma_i32_16x16x64_i8 v[126:129], v[144:147], v[194:197], v[126:129]
	v_mfma_i32_16x16x64_i8 v[126:129], v[148:151], v[198:201], v[126:129]
	v_mfma_i32_16x16x64_i8 v[122:125], v[156:159], v[198:201], v[122:125]
	v_mfma_i32_16x16x64_i8 v[122:125], v[152:155], v[194:197], v[122:125]
	v_mfma_i32_16x16x64_i8 v[114:117], v[152:155], v[202:205], v[114:117]
	v_mfma_i32_16x16x64_i8 v[114:117], v[156:159], v[208:211], v[114:117]
	v_mfma_i32_16x16x64_i8 v[118:121], v[148:151], v[208:211], v[118:121]
	v_mfma_i32_16x16x64_i8 v[118:121], v[144:147], v[202:205], v[118:121]
	v_mfma_i32_16x16x64_i8 v[110:113], v[144:147], v[212:215], v[110:113]
	v_mfma_i32_16x16x64_i8 v[110:113], v[148:151], v[216:219], v[110:113]
	v_mfma_i32_16x16x64_i8 v[106:109], v[156:159], v[216:219], v[106:109]
	v_mfma_i32_16x16x64_i8 v[106:109], v[152:155], v[212:215], v[106:109]
	v_mfma_i32_16x16x64_i8 v[98:101], v[152:155], v[220:223], v[98:101]
	v_mfma_i32_16x16x64_i8 v[98:101], v[156:159], v[224:227], v[98:101]
	v_mfma_i32_16x16x64_i8 v[102:105], v[148:151], v[224:227], v[102:105]
	v_mfma_i32_16x16x64_i8 v[102:105], v[144:147], v[220:223], v[102:105]
	s_setprio 0
	s_setprio 1
	v_mfma_i32_16x16x64_i8 v[94:97], v[160:163], v[194:197], v[94:97]
	v_mfma_i32_16x16x64_i8 v[94:97], v[164:167], v[198:201], v[94:97]
	v_mfma_i32_16x16x64_i8 v[90:93], v[190:193], v[198:201], v[90:93]
	v_mfma_i32_16x16x64_i8 v[90:93], v[186:189], v[194:197], v[90:93]
	v_mfma_i32_16x16x64_i8 v[82:85], v[186:189], v[202:205], v[82:85]
	v_mfma_i32_16x16x64_i8 v[82:85], v[190:193], v[208:211], v[82:85]
	v_mfma_i32_16x16x64_i8 v[86:89], v[164:167], v[208:211], v[86:89]
	v_mfma_i32_16x16x64_i8 v[86:89], v[160:163], v[202:205], v[86:89]
	v_mfma_i32_16x16x64_i8 v[78:81], v[160:163], v[212:215], v[78:81]
	v_mfma_i32_16x16x64_i8 v[78:81], v[164:167], v[216:219], v[78:81]
	v_mfma_i32_16x16x64_i8 v[74:77], v[190:193], v[216:219], v[74:77]
	v_mfma_i32_16x16x64_i8 v[74:77], v[186:189], v[212:215], v[74:77]
	v_mfma_i32_16x16x64_i8 v[66:69], v[186:189], v[220:223], v[66:69]
	v_mfma_i32_16x16x64_i8 v[66:69], v[190:193], v[224:227], v[66:69]
	v_mfma_i32_16x16x64_i8 v[70:73], v[164:167], v[224:227], v[70:73]
	v_mfma_i32_16x16x64_i8 v[70:73], v[160:163], v[220:223], v[70:73]
	s_setprio 0
	s_barrier
	s_add_i32 s42, s29, s16
	v_lshl_add_u64 v[228:229], s[2:3], 0, v[132:133]
	s_mov_b32 m0, s42
	ds_read_b128 v[194:197], v185 offset:16384
	ds_read_b128 v[198:201], v185 offset:17408
	ds_read_b128 v[202:205], v185 offset:18432
	ds_read_b128 v[208:211], v185 offset:19456
	ds_read_b128 v[212:215], v185 offset:20480
	ds_read_b128 v[216:219], v185 offset:21504
	ds_read_b128 v[220:223], v185 offset:22528
	ds_read_b128 v[224:227], v185 offset:23552
	global_load_lds_dwordx4 v[228:229], off
	s_add_i32 m0, s42, 0x2000
	s_add_u32 s42, s2, 0x80000
	v_lshl_add_u64 v[230:231], s[2:3], 0, v[136:137]
	s_addc_u32 s43, s3, 0
	s_add_i32 s44, s34, s16
	global_load_lds_dwordx4 v[230:231], off
	v_lshl_add_u64 v[232:233], s[42:43], 0, v[132:133]
	s_mov_b32 m0, s44
	v_lshl_add_u64 v[234:235], s[12:13], 0, v[134:135]
	global_load_lds_dwordx4 v[232:233], off
	v_lshl_add_u64 v[232:233], s[42:43], 0, v[136:137]
	s_add_i32 m0, s44, 0x2000
	s_nop 0
	global_load_lds_dwordx4 v[232:233], off
	v_lshl_add_u64 v[232:233], s[12:13], 0, v[130:131]
	s_mov_b32 m0, s17
	s_nop 0
	global_load_lds_dwordx4 v[232:233], off
	s_mov_b32 m0, s18
	s_nop 0
	global_load_lds_dwordx4 v[234:235], off
	s_waitcnt vmcnt(8)
	s_waitcnt lgkmcnt(0)
	s_barrier
	s_setprio 1
	s_waitcnt lgkmcnt(0)
	v_mfma_i32_16x16x64_i8 v[62:65], v[144:147], v[194:197], v[62:65]
	v_mfma_i32_16x16x64_i8 v[62:65], v[148:151], v[198:201], v[62:65]
	v_mfma_i32_16x16x64_i8 v[58:61], v[156:159], v[198:201], v[58:61]
	v_mfma_i32_16x16x64_i8 v[58:61], v[152:155], v[194:197], v[58:61]
	v_mfma_i32_16x16x64_i8 v[50:53], v[152:155], v[202:205], v[50:53]
	v_mfma_i32_16x16x64_i8 v[50:53], v[156:159], v[208:211], v[50:53]
	v_mfma_i32_16x16x64_i8 v[54:57], v[148:151], v[208:211], v[54:57]
	v_mfma_i32_16x16x64_i8 v[54:57], v[144:147], v[202:205], v[54:57]
	v_mfma_i32_16x16x64_i8 v[46:49], v[144:147], v[212:215], v[46:49]
	v_mfma_i32_16x16x64_i8 v[46:49], v[148:151], v[216:219], v[46:49]
	v_mfma_i32_16x16x64_i8 v[42:45], v[156:159], v[216:219], v[42:45]
	v_mfma_i32_16x16x64_i8 v[42:45], v[152:155], v[212:215], v[42:45]
	v_mfma_i32_16x16x64_i8 v[34:37], v[152:155], v[220:223], v[34:37]
	v_mfma_i32_16x16x64_i8 v[34:37], v[156:159], v[224:227], v[34:37]
	v_mfma_i32_16x16x64_i8 v[38:41], v[148:151], v[224:227], v[38:41]
	v_mfma_i32_16x16x64_i8 v[38:41], v[144:147], v[220:223], v[38:41]
	s_setprio 0
	s_setprio 1
	v_mfma_i32_16x16x64_i8 v[30:33], v[160:163], v[194:197], v[30:33]
	v_mfma_i32_16x16x64_i8 v[30:33], v[164:167], v[198:201], v[30:33]
	v_mfma_i32_16x16x64_i8 v[26:29], v[190:193], v[198:201], v[26:29]
	v_mfma_i32_16x16x64_i8 v[26:29], v[186:189], v[194:197], v[26:29]
	v_mfma_i32_16x16x64_i8 v[18:21], v[186:189], v[202:205], v[18:21]
	v_mfma_i32_16x16x64_i8 v[18:21], v[190:193], v[208:211], v[18:21]
	v_mfma_i32_16x16x64_i8 v[22:25], v[164:167], v[208:211], v[22:25]
	v_mfma_i32_16x16x64_i8 v[22:25], v[160:163], v[202:205], v[22:25]
	v_mfma_i32_16x16x64_i8 v[14:17], v[160:163], v[212:215], v[14:17]
	v_mfma_i32_16x16x64_i8 v[14:17], v[164:167], v[216:219], v[14:17]
	v_mfma_i32_16x16x64_i8 v[10:13], v[190:193], v[216:219], v[10:13]
	v_mfma_i32_16x16x64_i8 v[10:13], v[186:189], v[212:215], v[10:13]
	v_mfma_i32_16x16x64_i8 v[2:5], v[186:189], v[220:223], v[2:5]
	v_mfma_i32_16x16x64_i8 v[2:5], v[190:193], v[224:227], v[2:5]
	v_mfma_i32_16x16x64_i8 v[6:9], v[164:167], v[224:227], v[6:9]
	v_mfma_i32_16x16x64_i8 v[6:9], v[160:163], v[220:223], v[6:9]
	s_setprio 0
	s_barrier
	s_add_i32 s42, 0, 0x18000
	v_add_u32_e32 v138, s42, v183
	s_add_i32 s43, 0, 0x1c000
	ds_read_b128 v[144:147], v138
	ds_read_b128 v[148:151], v138 offset:1024
	ds_read_b128 v[152:155], v138 offset:2048
	ds_read_b128 v[156:159], v138 offset:3072
	v_add_u32_e32 v138, s43, v183
	ds_read_b128 v[160:163], v138
	ds_read_b128 v[164:167], v138 offset:1024
	ds_read_b128 v[186:189], v138 offset:2048
	ds_read_b128 v[190:193], v138 offset:3072
	s_add_u32 s12, s12, 0x80000
	s_addc_u32 s13, s13, 0
	s_mov_b32 m0, s19
	v_lshl_add_u64 v[236:237], s[12:13], 0, v[130:131]
	ds_read_b128 v[194:197], v185 offset:32768
	ds_read_b128 v[198:201], v185 offset:33792
	ds_read_b128 v[202:205], v185 offset:34816
	ds_read_b128 v[208:211], v185 offset:35840
	ds_read_b128 v[212:215], v185 offset:36864
	ds_read_b128 v[216:219], v185 offset:37888
	ds_read_b128 v[220:223], v185 offset:38912
	ds_read_b128 v[224:227], v185 offset:39936
	global_load_lds_dwordx4 v[236:237], off
	v_lshl_add_u64 v[236:237], s[12:13], 0, v[134:135]
	s_mov_b32 m0, s20
	s_nop 0
	global_load_lds_dwordx4 v[236:237], off
	s_waitcnt vmcnt(8)
	s_waitcnt lgkmcnt(0)
	s_barrier
	s_setprio 1
	s_waitcnt lgkmcnt(0)
	v_mfma_i32_16x16x64_i8 v[126:129], v[144:147], v[194:197], v[126:129]
	v_mfma_i32_16x16x64_i8 v[126:129], v[148:151], v[198:201], v[126:129]
	v_mfma_i32_16x16x64_i8 v[122:125], v[156:159], v[198:201], v[122:125]
	v_mfma_i32_16x16x64_i8 v[122:125], v[152:155], v[194:197], v[122:125]
	v_mfma_i32_16x16x64_i8 v[114:117], v[152:155], v[202:205], v[114:117]
	v_mfma_i32_16x16x64_i8 v[114:117], v[156:159], v[208:211], v[114:117]
	v_mfma_i32_16x16x64_i8 v[118:121], v[148:151], v[208:211], v[118:121]
	v_mfma_i32_16x16x64_i8 v[118:121], v[144:147], v[202:205], v[118:121]
	v_mfma_i32_16x16x64_i8 v[110:113], v[144:147], v[212:215], v[110:113]
	v_mfma_i32_16x16x64_i8 v[110:113], v[148:151], v[216:219], v[110:113]
	v_mfma_i32_16x16x64_i8 v[106:109], v[156:159], v[216:219], v[106:109]
	v_mfma_i32_16x16x64_i8 v[106:109], v[152:155], v[212:215], v[106:109]
	v_mfma_i32_16x16x64_i8 v[98:101], v[152:155], v[220:223], v[98:101]
	v_mfma_i32_16x16x64_i8 v[98:101], v[156:159], v[224:227], v[98:101]
	v_mfma_i32_16x16x64_i8 v[102:105], v[148:151], v[224:227], v[102:105]
	v_mfma_i32_16x16x64_i8 v[102:105], v[144:147], v[220:223], v[102:105]
	s_setprio 0
	s_setprio 1
	v_mfma_i32_16x16x64_i8 v[94:97], v[160:163], v[194:197], v[94:97]
	v_mfma_i32_16x16x64_i8 v[94:97], v[164:167], v[198:201], v[94:97]
	v_mfma_i32_16x16x64_i8 v[90:93], v[190:193], v[198:201], v[90:93]
	v_mfma_i32_16x16x64_i8 v[90:93], v[186:189], v[194:197], v[90:93]
	v_mfma_i32_16x16x64_i8 v[82:85], v[186:189], v[202:205], v[82:85]
	v_mfma_i32_16x16x64_i8 v[82:85], v[190:193], v[208:211], v[82:85]
	v_mfma_i32_16x16x64_i8 v[86:89], v[164:167], v[208:211], v[86:89]
	v_mfma_i32_16x16x64_i8 v[86:89], v[160:163], v[202:205], v[86:89]
	v_mfma_i32_16x16x64_i8 v[78:81], v[160:163], v[212:215], v[78:81]
	v_mfma_i32_16x16x64_i8 v[78:81], v[164:167], v[216:219], v[78:81]
	v_mfma_i32_16x16x64_i8 v[74:77], v[190:193], v[216:219], v[74:77]
	v_mfma_i32_16x16x64_i8 v[74:77], v[186:189], v[212:215], v[74:77]
	v_mfma_i32_16x16x64_i8 v[66:69], v[186:189], v[220:223], v[66:69]
	v_mfma_i32_16x16x64_i8 v[66:69], v[190:193], v[224:227], v[66:69]
	v_mfma_i32_16x16x64_i8 v[70:73], v[164:167], v[224:227], v[70:73]
	v_mfma_i32_16x16x64_i8 v[70:73], v[160:163], v[220:223], v[70:73]
	s_setprio 0
	s_barrier
	s_add_i32 s12, s42, s16
	v_lshl_add_u64 v[228:229], v[228:229], 0, s[10:11]
	s_mov_b32 m0, s12
	ds_read_b128 v[194:197], v185 offset:49152
	ds_read_b128 v[198:201], v185 offset:50176
	ds_read_b128 v[202:205], v185 offset:51200
	ds_read_b128 v[208:211], v185 offset:52224
	ds_read_b128 v[212:215], v185 offset:53248
	ds_read_b128 v[216:219], v185 offset:54272
	ds_read_b128 v[220:223], v185 offset:55296
	ds_read_b128 v[224:227], v185 offset:56320
	global_load_lds_dwordx4 v[228:229], off
	s_add_i32 m0, s12, 0x2000
	s_add_u32 s2, s2, 0x80080
	v_lshl_add_u64 v[228:229], v[230:231], 0, s[10:11]
	s_addc_u32 s3, s3, 0
	s_add_i32 s12, s43, s16
	global_load_lds_dwordx4 v[228:229], off
	v_lshl_add_u64 v[228:229], s[2:3], 0, v[132:133]
	s_mov_b32 m0, s12
	s_nop 0
	global_load_lds_dwordx4 v[228:229], off
	v_lshl_add_u64 v[228:229], s[2:3], 0, v[136:137]
	s_add_i32 m0, s12, 0x2000
	s_nop 0
	global_load_lds_dwordx4 v[228:229], off
	v_lshl_add_u64 v[228:229], v[232:233], 0, s[10:11]
	s_mov_b32 m0, s22
	s_nop 0
	global_load_lds_dwordx4 v[228:229], off
	v_lshl_add_u64 v[228:229], v[234:235], 0, s[10:11]
	s_mov_b32 m0, s23
	s_nop 0
	global_load_lds_dwordx4 v[228:229], off
	s_waitcnt vmcnt(8)
	s_waitcnt lgkmcnt(0)
	s_barrier
	s_setprio 1
	s_waitcnt lgkmcnt(0)
	v_mfma_i32_16x16x64_i8 v[62:65], v[144:147], v[194:197], v[62:65]
	v_mfma_i32_16x16x64_i8 v[62:65], v[148:151], v[198:201], v[62:65]
	v_mfma_i32_16x16x64_i8 v[58:61], v[156:159], v[198:201], v[58:61]
	v_mfma_i32_16x16x64_i8 v[58:61], v[152:155], v[194:197], v[58:61]
	v_mfma_i32_16x16x64_i8 v[50:53], v[152:155], v[202:205], v[50:53]
	v_mfma_i32_16x16x64_i8 v[50:53], v[156:159], v[208:211], v[50:53]
	v_mfma_i32_16x16x64_i8 v[54:57], v[148:151], v[208:211], v[54:57]
	v_mfma_i32_16x16x64_i8 v[54:57], v[144:147], v[202:205], v[54:57]
	v_mfma_i32_16x16x64_i8 v[46:49], v[144:147], v[212:215], v[46:49]
	v_mfma_i32_16x16x64_i8 v[46:49], v[148:151], v[216:219], v[46:49]
	v_mfma_i32_16x16x64_i8 v[42:45], v[156:159], v[216:219], v[42:45]
	v_mfma_i32_16x16x64_i8 v[42:45], v[152:155], v[212:215], v[42:45]
	v_mfma_i32_16x16x64_i8 v[34:37], v[152:155], v[220:223], v[34:37]
	v_mfma_i32_16x16x64_i8 v[34:37], v[156:159], v[224:227], v[34:37]
	v_mfma_i32_16x16x64_i8 v[38:41], v[148:151], v[224:227], v[38:41]
	v_mfma_i32_16x16x64_i8 v[38:41], v[144:147], v[220:223], v[38:41]
	s_setprio 0
	s_setprio 1
	v_mfma_i32_16x16x64_i8 v[30:33], v[160:163], v[194:197], v[30:33]
	v_mfma_i32_16x16x64_i8 v[30:33], v[164:167], v[198:201], v[30:33]
	v_mfma_i32_16x16x64_i8 v[26:29], v[190:193], v[198:201], v[26:29]
	v_mfma_i32_16x16x64_i8 v[26:29], v[186:189], v[194:197], v[26:29]
	v_mfma_i32_16x16x64_i8 v[18:21], v[186:189], v[202:205], v[18:21]
	v_mfma_i32_16x16x64_i8 v[18:21], v[190:193], v[208:211], v[18:21]
	v_mfma_i32_16x16x64_i8 v[22:25], v[164:167], v[208:211], v[22:25]
	v_mfma_i32_16x16x64_i8 v[22:25], v[160:163], v[202:205], v[22:25]
	v_mfma_i32_16x16x64_i8 v[14:17], v[160:163], v[212:215], v[14:17]
	v_mfma_i32_16x16x64_i8 v[14:17], v[164:167], v[216:219], v[14:17]
	v_mfma_i32_16x16x64_i8 v[10:13], v[190:193], v[216:219], v[10:13]
	v_mfma_i32_16x16x64_i8 v[10:13], v[186:189], v[212:215], v[10:13]
	v_mfma_i32_16x16x64_i8 v[2:5], v[186:189], v[220:223], v[2:5]
	v_mfma_i32_16x16x64_i8 v[2:5], v[190:193], v[224:227], v[2:5]
	v_mfma_i32_16x16x64_i8 v[6:9], v[164:167], v[224:227], v[6:9]
	v_mfma_i32_16x16x64_i8 v[6:9], v[160:163], v[220:223], v[6:9]
	s_setprio 0
	s_barrier
	s_add_u32 s4, s4, 0x100
	s_addc_u32 s5, s5, 0
	s_add_u32 s39, s39, 0x100
	s_addc_u32 s40, s40, 0
	s_cmp_ge_i32 s41, s1
	s_mov_b32 s2, s41
	s_cbranch_scc0 .LBB0_245

.LBB0_265:
	s_lshl_b32 s10, s8, 21
	s_and_b32 s10, s10, 0x1fe00000
	v_readlane_b32 s40, v248, 20
	v_readlane_b32 s41, v248, 21
	s_add_u32 s10, s40, s10
	s_addc_u32 s33, s41, 0
	s_lshr_b32 s39, s8, 13
	s_and_b32 s39, s39, 0x7ff80
	s_add_u32 s70, s10, s39
	s_addc_u32 s71, s33, 0
	s_lshl_b32 s10, s8, 13
	s_and_b32 s10, s10, 0x1fe00000
	v_readlane_b32 s40, v248, 18
	v_readlane_b32 s41, v248, 19
	s_add_u32 s10, s40, s10
	s_addc_u32 s33, s41, 0
	s_add_u32 s72, s10, s39
	s_addc_u32 s73, s33, 0
	s_cmp_lt_i32 s1, 1
	v_cmp_gt_i64_e64 s[74:75], s[8:9], -1
	s_cbranch_scc1 .LBB0_324
	s_and_b64 s[8:9], s[74:75], exec
	s_cselect_b32 s10, s71, s5
	s_cselect_b32 s33, s70, s4
	s_cselect_b32 s39, s73, s3
	s_cselect_b32 s40, s72, s2
	s_add_i32 s41, s1, -2
	s_add_u32 s4, s4, 0x100080
	s_addc_u32 s5, s5, 0
	s_add_u32 s42, s2, 0x100
	s_addc_u32 s43, s3, 0
	s_mov_b32 s2, 0
	ds_read_b128 v[148:151], v145
	ds_read_b128 v[152:155], v145 offset:1024
	ds_read_b128 v[156:159], v145 offset:2048
	ds_read_b128 v[160:163], v145 offset:3072
	ds_read_b128 v[164:167], v146
	ds_read_b128 v[168:171], v146 offset:1024
	ds_read_b128 v[172:175], v146 offset:2048
	ds_read_b128 v[176:179], v146 offset:3072
	s_add_i32 s44, s2, 2
	s_add_u32 s3, s4, 0xfff00080
	s_addc_u32 s8, s5, -1
	s_cmp_eq_u32 s41, s2
	s_cselect_b32 s2, s40, s42
	s_cselect_b32 s9, s10, s8
	s_cselect_b32 s8, s33, s3
	s_cselect_b32 s3, s39, s43
	v_lshl_add_u64 v[204:205], s[4:5], 0, v[138:139]
	s_add_i32 m0, s16, 0xc000
	ds_read_b128 v[180:183], v147
	ds_read_b128 v[184:187], v147 offset:1024
	ds_read_b128 v[188:191], v147 offset:2048
	ds_read_b128 v[192:195], v147 offset:3072
	ds_read_b128 v[196:199], v147 offset:4096
	ds_read_b128 v[200:203], v147 offset:5120
	ds_read_b128 v[208:211], v147 offset:6144
	ds_read_b128 v[212:215], v147 offset:7168
	global_load_lds_dwordx4 v[204:205], off
	v_lshl_add_u64 v[204:205], s[4:5], 0, v[140:141]
	s_add_i32 m0, s16, 0xe000
	s_nop 0
	global_load_lds_dwordx4 v[204:205], off
	s_waitcnt vmcnt(8)
	s_waitcnt lgkmcnt(0)
	s_barrier
	s_setprio 1
	s_waitcnt lgkmcnt(0)
	v_mfma_f32_16x16x32_bf16 v[122:125], v[148:151], v[180:183], 0
	v_mfma_f32_16x16x32_bf16 v[122:125], v[152:155], v[184:187], v[122:125]
	v_mfma_f32_16x16x32_bf16 v[118:121], v[160:163], v[184:187], 0
	v_mfma_f32_16x16x32_bf16 v[118:121], v[156:159], v[180:183], v[118:121]
	v_mfma_f32_16x16x32_bf16 v[102:105], v[156:159], v[188:191], 0
	v_mfma_f32_16x16x32_bf16 v[102:105], v[160:163], v[192:195], v[102:105]
	v_mfma_f32_16x16x32_bf16 v[110:113], v[152:155], v[192:195], 0
	v_mfma_f32_16x16x32_bf16 v[110:113], v[148:151], v[188:191], v[110:113]
	v_mfma_f32_16x16x32_bf16 v[94:97], v[148:151], v[196:199], 0
	v_mfma_f32_16x16x32_bf16 v[94:97], v[152:155], v[200:203], v[94:97]
	v_mfma_f32_16x16x32_bf16 v[86:89], v[160:163], v[200:203], 0
	v_mfma_f32_16x16x32_bf16 v[86:89], v[156:159], v[196:199], v[86:89]
	v_mfma_f32_16x16x32_bf16 v[70:73], v[156:159], v[208:211], 0
	v_mfma_f32_16x16x32_bf16 v[70:73], v[160:163], v[212:215], v[70:73]
	v_mfma_f32_16x16x32_bf16 v[78:81], v[152:155], v[212:215], 0
	v_mfma_f32_16x16x32_bf16 v[78:81], v[148:151], v[208:211], v[78:81]
	s_setprio 0
	s_setprio 1
	v_mfma_f32_16x16x32_bf16 v[126:129], v[164:167], v[180:183], 0
	v_mfma_f32_16x16x32_bf16 v[126:129], v[168:171], v[184:187], v[126:129]
	v_mfma_f32_16x16x32_bf16 v[114:117], v[176:179], v[184:187], 0
	v_mfma_f32_16x16x32_bf16 v[114:117], v[172:175], v[180:183], v[114:117]
	v_mfma_f32_16x16x32_bf16 v[98:101], v[172:175], v[188:191], 0
	v_mfma_f32_16x16x32_bf16 v[98:101], v[176:179], v[192:195], v[98:101]
	v_mfma_f32_16x16x32_bf16 v[106:109], v[168:171], v[192:195], 0
	v_mfma_f32_16x16x32_bf16 v[106:109], v[164:167], v[188:191], v[106:109]
	v_mfma_f32_16x16x32_bf16 v[90:93], v[164:167], v[196:199], 0
	v_mfma_f32_16x16x32_bf16 v[90:93], v[168:171], v[200:203], v[90:93]
	v_mfma_f32_16x16x32_bf16 v[82:85], v[176:179], v[200:203], 0
	v_mfma_f32_16x16x32_bf16 v[82:85], v[172:175], v[196:199], v[82:85]
	v_mfma_f32_16x16x32_bf16 v[66:69], v[172:175], v[208:211], 0
	v_mfma_f32_16x16x32_bf16 v[66:69], v[176:179], v[212:215], v[66:69]
	v_mfma_f32_16x16x32_bf16 v[74:77], v[168:171], v[212:215], 0
	v_mfma_f32_16x16x32_bf16 v[74:77], v[164:167], v[208:211], v[74:77]
	s_setprio 0
	s_barrier
	s_add_i32 s45, s36, s13
	v_lshl_add_u64 v[204:205], s[2:3], 0, v[132:133]
	s_mov_b32 m0, s45
	ds_read_b128 v[180:183], v147 offset:16384
	ds_read_b128 v[184:187], v147 offset:17408
	ds_read_b128 v[188:191], v147 offset:18432
	ds_read_b128 v[192:195], v147 offset:19456
	ds_read_b128 v[196:199], v147 offset:20480
	ds_read_b128 v[200:203], v147 offset:21504
	ds_read_b128 v[208:211], v147 offset:22528
	ds_read_b128 v[212:215], v147 offset:23552
	global_load_lds_dwordx4 v[204:205], off
	s_add_i32 m0, s45, 0x2000
	s_add_u32 s46, s2, 0x100000
	v_lshl_add_u64 v[216:217], s[2:3], 0, v[136:137]
	s_addc_u32 s47, s3, 0
	s_add_i32 s45, s37, s13
	global_load_lds_dwordx4 v[216:217], off
	v_lshl_add_u64 v[218:219], s[46:47], 0, v[132:133]
	s_mov_b32 m0, s45
	v_lshl_add_u64 v[220:221], s[8:9], 0, v[134:135]
	global_load_lds_dwordx4 v[218:219], off
	v_lshl_add_u64 v[218:219], s[46:47], 0, v[136:137]
	s_add_i32 m0, s45, 0x2000
	s_nop 0
	global_load_lds_dwordx4 v[218:219], off
	v_lshl_add_u64 v[218:219], s[8:9], 0, v[130:131]
	s_mov_b32 m0, s16
	s_nop 0
	global_load_lds_dwordx4 v[218:219], off
	s_mov_b32 m0, s17
	s_nop 0
	global_load_lds_dwordx4 v[220:221], off
	s_waitcnt vmcnt(8)
	s_waitcnt lgkmcnt(0)
	s_barrier
	s_setprio 1
	s_waitcnt lgkmcnt(0)
	v_mfma_f32_16x16x32_bf16 v[62:65], v[148:151], v[180:183], 0
	v_mfma_f32_16x16x32_bf16 v[62:65], v[152:155], v[184:187], v[62:65]
	v_mfma_f32_16x16x32_bf16 v[54:57], v[160:163], v[184:187], 0
	v_mfma_f32_16x16x32_bf16 v[54:57], v[156:159], v[180:183], v[54:57]
	v_mfma_f32_16x16x32_bf16 v[38:41], v[156:159], v[188:191], 0
	v_mfma_f32_16x16x32_bf16 v[38:41], v[160:163], v[192:195], v[38:41]
	v_mfma_f32_16x16x32_bf16 v[46:49], v[152:155], v[192:195], 0
	v_mfma_f32_16x16x32_bf16 v[46:49], v[148:151], v[188:191], v[46:49]
	v_mfma_f32_16x16x32_bf16 v[30:33], v[148:151], v[196:199], 0
	v_mfma_f32_16x16x32_bf16 v[30:33], v[152:155], v[200:203], v[30:33]
	v_mfma_f32_16x16x32_bf16 v[22:25], v[160:163], v[200:203], 0
	v_mfma_f32_16x16x32_bf16 v[22:25], v[156:159], v[196:199], v[22:25]
	v_mfma_f32_16x16x32_bf16 v[6:9], v[156:159], v[208:211], 0
	v_mfma_f32_16x16x32_bf16 v[6:9], v[160:163], v[212:215], v[6:9]
	v_mfma_f32_16x16x32_bf16 v[14:17], v[152:155], v[212:215], 0
	v_mfma_f32_16x16x32_bf16 v[14:17], v[148:151], v[208:211], v[14:17]
	s_setprio 0
	s_setprio 1
	v_mfma_f32_16x16x32_bf16 v[58:61], v[164:167], v[180:183], 0
	v_mfma_f32_16x16x32_bf16 v[58:61], v[168:171], v[184:187], v[58:61]
	v_mfma_f32_16x16x32_bf16 v[50:53], v[176:179], v[184:187], 0
	v_mfma_f32_16x16x32_bf16 v[50:53], v[172:175], v[180:183], v[50:53]
	v_mfma_f32_16x16x32_bf16 v[34:37], v[172:175], v[188:191], 0
	v_mfma_f32_16x16x32_bf16 v[34:37], v[176:179], v[192:195], v[34:37]
	v_mfma_f32_16x16x32_bf16 v[42:45], v[168:171], v[192:195], 0
	v_mfma_f32_16x16x32_bf16 v[42:45], v[164:167], v[188:191], v[42:45]
	v_mfma_f32_16x16x32_bf16 v[26:29], v[164:167], v[196:199], 0
	v_mfma_f32_16x16x32_bf16 v[26:29], v[168:171], v[200:203], v[26:29]
	v_mfma_f32_16x16x32_bf16 v[18:21], v[176:179], v[200:203], 0
	v_mfma_f32_16x16x32_bf16 v[18:21], v[172:175], v[196:199], v[18:21]
	v_mfma_f32_16x16x32_bf16 v[2:5], v[172:175], v[208:211], 0
	v_mfma_f32_16x16x32_bf16 v[2:5], v[176:179], v[212:215], v[2:5]
	v_mfma_f32_16x16x32_bf16 v[10:13], v[168:171], v[212:215], 0
	v_mfma_f32_16x16x32_bf16 v[10:13], v[164:167], v[208:211], v[10:13]
	s_setprio 0
	s_barrier
	s_add_i32 s45, 0, 0x18000
	s_add_i32 s46, 0, 0x1c000
	v_add_u32_e32 v160, s45, v1
	v_add_u32_e32 v176, s46, v1
	ds_read_b128 v[148:151], v160
	ds_read_b128 v[152:155], v160 offset:1024
	ds_read_b128 v[156:159], v160 offset:2048
	ds_read_b128 v[160:163], v160 offset:3072
	ds_read_b128 v[164:167], v176
	ds_read_b128 v[168:171], v176 offset:1024
	ds_read_b128 v[172:175], v176 offset:2048
	ds_read_b128 v[176:179], v176 offset:3072
	s_add_u32 s8, s8, 0x100000
	s_addc_u32 s9, s9, 0
	s_mov_b32 m0, s18
	v_lshl_add_u64 v[222:223], s[8:9], 0, v[130:131]
	ds_read_b128 v[180:183], v147 offset:32768
	ds_read_b128 v[184:187], v147 offset:33792
	ds_read_b128 v[188:191], v147 offset:34816
	ds_read_b128 v[192:195], v147 offset:35840
	ds_read_b128 v[196:199], v147 offset:36864
	ds_read_b128 v[200:203], v147 offset:37888
	ds_read_b128 v[208:211], v147 offset:38912
	ds_read_b128 v[212:215], v147 offset:39936
	global_load_lds_dwordx4 v[222:223], off
	v_lshl_add_u64 v[222:223], s[8:9], 0, v[134:135]
	s_mov_b32 m0, s19
	s_nop 0
	global_load_lds_dwordx4 v[222:223], off
	s_waitcnt vmcnt(8)
	s_waitcnt lgkmcnt(0)
	s_barrier
	s_setprio 1
	s_waitcnt lgkmcnt(0)
	v_mfma_f32_16x16x32_bf16 v[122:125], v[148:151], v[180:183], v[122:125]
	v_mfma_f32_16x16x32_bf16 v[122:125], v[152:155], v[184:187], v[122:125]
	v_mfma_f32_16x16x32_bf16 v[118:121], v[160:163], v[184:187], v[118:121]
	v_mfma_f32_16x16x32_bf16 v[118:121], v[156:159], v[180:183], v[118:121]
	v_mfma_f32_16x16x32_bf16 v[102:105], v[156:159], v[188:191], v[102:105]
	v_mfma_f32_16x16x32_bf16 v[102:105], v[160:163], v[192:195], v[102:105]
	v_mfma_f32_16x16x32_bf16 v[110:113], v[152:155], v[192:195], v[110:113]
	v_mfma_f32_16x16x32_bf16 v[110:113], v[148:151], v[188:191], v[110:113]
	v_mfma_f32_16x16x32_bf16 v[94:97], v[148:151], v[196:199], v[94:97]
	v_mfma_f32_16x16x32_bf16 v[94:97], v[152:155], v[200:203], v[94:97]
	v_mfma_f32_16x16x32_bf16 v[86:89], v[160:163], v[200:203], v[86:89]
	v_mfma_f32_16x16x32_bf16 v[86:89], v[156:159], v[196:199], v[86:89]
	v_mfma_f32_16x16x32_bf16 v[70:73], v[156:159], v[208:211], v[70:73]
	v_mfma_f32_16x16x32_bf16 v[70:73], v[160:163], v[212:215], v[70:73]
	v_mfma_f32_16x16x32_bf16 v[78:81], v[152:155], v[212:215], v[78:81]
	v_mfma_f32_16x16x32_bf16 v[78:81], v[148:151], v[208:211], v[78:81]
	s_setprio 0
	s_setprio 1
	v_mfma_f32_16x16x32_bf16 v[126:129], v[164:167], v[180:183], v[126:129]
	v_mfma_f32_16x16x32_bf16 v[126:129], v[168:171], v[184:187], v[126:129]
	v_mfma_f32_16x16x32_bf16 v[114:117], v[176:179], v[184:187], v[114:117]
	v_mfma_f32_16x16x32_bf16 v[114:117], v[172:175], v[180:183], v[114:117]
	v_mfma_f32_16x16x32_bf16 v[98:101], v[172:175], v[188:191], v[98:101]
	v_mfma_f32_16x16x32_bf16 v[98:101], v[176:179], v[192:195], v[98:101]
	v_mfma_f32_16x16x32_bf16 v[106:109], v[168:171], v[192:195], v[106:109]
	v_mfma_f32_16x16x32_bf16 v[106:109], v[164:167], v[188:191], v[106:109]
	v_mfma_f32_16x16x32_bf16 v[90:93], v[164:167], v[196:199], v[90:93]
	v_mfma_f32_16x16x32_bf16 v[90:93], v[168:171], v[200:203], v[90:93]
	v_mfma_f32_16x16x32_bf16 v[82:85], v[176:179], v[200:203], v[82:85]
	v_mfma_f32_16x16x32_bf16 v[82:85], v[172:175], v[196:199], v[82:85]
	v_mfma_f32_16x16x32_bf16 v[66:69], v[172:175], v[208:211], v[66:69]
	v_mfma_f32_16x16x32_bf16 v[66:69], v[176:179], v[212:215], v[66:69]
	v_mfma_f32_16x16x32_bf16 v[74:77], v[168:171], v[212:215], v[74:77]
	v_mfma_f32_16x16x32_bf16 v[74:77], v[164:167], v[208:211], v[74:77]
	s_setprio 0
	s_barrier
	s_add_i32 s8, s45, s13
	v_lshl_add_u64 v[204:205], v[204:205], 0, s[24:25]
	s_mov_b32 m0, s8
	ds_read_b128 v[180:183], v147 offset:49152
	ds_read_b128 v[184:187], v147 offset:50176
	ds_read_b128 v[188:191], v147 offset:51200
	ds_read_b128 v[192:195], v147 offset:52224
	ds_read_b128 v[196:199], v147 offset:53248
	ds_read_b128 v[200:203], v147 offset:54272
	ds_read_b128 v[208:211], v147 offset:55296
	ds_read_b128 v[212:215], v147 offset:56320
	global_load_lds_dwordx4 v[204:205], off
	s_add_i32 m0, s8, 0x2000
	s_add_u32 s2, s2, 0x100080
	v_lshl_add_u64 v[204:205], v[216:217], 0, s[24:25]
	s_addc_u32 s3, s3, 0
	s_add_i32 s8, s46, s13
	global_load_lds_dwordx4 v[204:205], off
	v_lshl_add_u64 v[204:205], s[2:3], 0, v[132:133]
	s_mov_b32 m0, s8
	s_nop 0
	global_load_lds_dwordx4 v[204:205], off
	v_lshl_add_u64 v[204:205], s[2:3], 0, v[136:137]
	s_add_i32 m0, s8, 0x2000
	s_nop 0
	global_load_lds_dwordx4 v[204:205], off
	v_lshl_add_u64 v[204:205], v[218:219], 0, s[24:25]
	s_mov_b32 m0, s29
	s_nop 0
	global_load_lds_dwordx4 v[204:205], off
	v_lshl_add_u64 v[204:205], v[220:221], 0, s[24:25]
	s_mov_b32 m0, s34
	s_nop 0
	global_load_lds_dwordx4 v[204:205], off
	s_waitcnt vmcnt(8)
	s_waitcnt lgkmcnt(0)
	s_barrier
	s_setprio 1
	s_waitcnt lgkmcnt(0)
	v_mfma_f32_16x16x32_bf16 v[62:65], v[148:151], v[180:183], v[62:65]
	v_mfma_f32_16x16x32_bf16 v[62:65], v[152:155], v[184:187], v[62:65]
	v_mfma_f32_16x16x32_bf16 v[54:57], v[160:163], v[184:187], v[54:57]
	v_mfma_f32_16x16x32_bf16 v[54:57], v[156:159], v[180:183], v[54:57]
	v_mfma_f32_16x16x32_bf16 v[38:41], v[156:159], v[188:191], v[38:41]
	v_mfma_f32_16x16x32_bf16 v[38:41], v[160:163], v[192:195], v[38:41]
	v_mfma_f32_16x16x32_bf16 v[46:49], v[152:155], v[192:195], v[46:49]
	v_mfma_f32_16x16x32_bf16 v[46:49], v[148:151], v[188:191], v[46:49]
	v_mfma_f32_16x16x32_bf16 v[30:33], v[148:151], v[196:199], v[30:33]
	v_mfma_f32_16x16x32_bf16 v[30:33], v[152:155], v[200:203], v[30:33]
	v_mfma_f32_16x16x32_bf16 v[22:25], v[160:163], v[200:203], v[22:25]
	v_mfma_f32_16x16x32_bf16 v[22:25], v[156:159], v[196:199], v[22:25]
	v_mfma_f32_16x16x32_bf16 v[6:9], v[156:159], v[208:211], v[6:9]
	v_mfma_f32_16x16x32_bf16 v[6:9], v[160:163], v[212:215], v[6:9]
	v_mfma_f32_16x16x32_bf16 v[14:17], v[152:155], v[212:215], v[14:17]
	v_mfma_f32_16x16x32_bf16 v[14:17], v[148:151], v[208:211], v[14:17]
	s_setprio 0
	s_setprio 1
	v_mfma_f32_16x16x32_bf16 v[58:61], v[164:167], v[180:183], v[58:61]
	v_mfma_f32_16x16x32_bf16 v[58:61], v[168:171], v[184:187], v[58:61]
	v_mfma_f32_16x16x32_bf16 v[50:53], v[176:179], v[184:187], v[50:53]
	v_mfma_f32_16x16x32_bf16 v[50:53], v[172:175], v[180:183], v[50:53]
	v_mfma_f32_16x16x32_bf16 v[34:37], v[172:175], v[188:191], v[34:37]
	v_mfma_f32_16x16x32_bf16 v[34:37], v[176:179], v[192:195], v[34:37]
	v_mfma_f32_16x16x32_bf16 v[42:45], v[168:171], v[192:195], v[42:45]
	v_mfma_f32_16x16x32_bf16 v[42:45], v[164:167], v[188:191], v[42:45]
	v_mfma_f32_16x16x32_bf16 v[26:29], v[164:167], v[196:199], v[26:29]
	v_mfma_f32_16x16x32_bf16 v[26:29], v[168:171], v[200:203], v[26:29]
	v_mfma_f32_16x16x32_bf16 v[18:21], v[176:179], v[200:203], v[18:21]
	v_mfma_f32_16x16x32_bf16 v[18:21], v[172:175], v[196:199], v[18:21]
	v_mfma_f32_16x16x32_bf16 v[2:5], v[172:175], v[208:211], v[2:5]
	v_mfma_f32_16x16x32_bf16 v[2:5], v[176:179], v[212:215], v[2:5]
	v_mfma_f32_16x16x32_bf16 v[10:13], v[168:171], v[212:215], v[10:13]
	v_mfma_f32_16x16x32_bf16 v[10:13], v[164:167], v[208:211], v[10:13]
	s_setprio 0
	s_barrier
	s_add_u32 s4, s4, 0x100
	s_addc_u32 s5, s5, 0
	s_add_u32 s42, s42, 0x100
	s_addc_u32 s43, s43, 0
	s_cmp_ge_i32 s44, s1
	s_mov_b32 s2, s44
	s_cbranch_scc1 .Lkpeel_exit_1
.LBB0_267:
	ds_read_b128 v[148:151], v145
	ds_read_b128 v[152:155], v145 offset:1024
	ds_read_b128 v[156:159], v145 offset:2048
	ds_read_b128 v[160:163], v145 offset:3072
	ds_read_b128 v[164:167], v146
	ds_read_b128 v[168:171], v146 offset:1024
	ds_read_b128 v[172:175], v146 offset:2048
	ds_read_b128 v[176:179], v146 offset:3072
	s_add_i32 s44, s2, 2
	s_add_u32 s3, s4, 0xfff00080
	s_addc_u32 s8, s5, -1
	s_cmp_eq_u32 s41, s2
	s_cselect_b32 s2, s40, s42
	s_cselect_b32 s9, s10, s8
	s_cselect_b32 s8, s33, s3
	s_cselect_b32 s3, s39, s43
	v_lshl_add_u64 v[204:205], s[4:5], 0, v[138:139]
	s_add_i32 m0, s16, 0xc000
	ds_read_b128 v[180:183], v147
	ds_read_b128 v[184:187], v147 offset:1024
	ds_read_b128 v[188:191], v147 offset:2048
	ds_read_b128 v[192:195], v147 offset:3072
	ds_read_b128 v[196:199], v147 offset:4096
	ds_read_b128 v[200:203], v147 offset:5120
	ds_read_b128 v[208:211], v147 offset:6144
	ds_read_b128 v[212:215], v147 offset:7168
	global_load_lds_dwordx4 v[204:205], off
	v_lshl_add_u64 v[204:205], s[4:5], 0, v[140:141]
	s_add_i32 m0, s16, 0xe000
	s_nop 0
	global_load_lds_dwordx4 v[204:205], off
	s_waitcnt vmcnt(8)
	s_waitcnt lgkmcnt(0)
	s_barrier
	s_setprio 1
	s_waitcnt lgkmcnt(0)
	v_mfma_f32_16x16x32_bf16 v[122:125], v[148:151], v[180:183], v[122:125]
	v_mfma_f32_16x16x32_bf16 v[122:125], v[152:155], v[184:187], v[122:125]
	v_mfma_f32_16x16x32_bf16 v[118:121], v[160:163], v[184:187], v[118:121]
	v_mfma_f32_16x16x32_bf16 v[118:121], v[156:159], v[180:183], v[118:121]
	v_mfma_f32_16x16x32_bf16 v[102:105], v[156:159], v[188:191], v[102:105]
	v_mfma_f32_16x16x32_bf16 v[102:105], v[160:163], v[192:195], v[102:105]
	v_mfma_f32_16x16x32_bf16 v[110:113], v[152:155], v[192:195], v[110:113]
	v_mfma_f32_16x16x32_bf16 v[110:113], v[148:151], v[188:191], v[110:113]
	v_mfma_f32_16x16x32_bf16 v[94:97], v[148:151], v[196:199], v[94:97]
	v_mfma_f32_16x16x32_bf16 v[94:97], v[152:155], v[200:203], v[94:97]
	v_mfma_f32_16x16x32_bf16 v[86:89], v[160:163], v[200:203], v[86:89]
	v_mfma_f32_16x16x32_bf16 v[86:89], v[156:159], v[196:199], v[86:89]
	v_mfma_f32_16x16x32_bf16 v[70:73], v[156:159], v[208:211], v[70:73]
	v_mfma_f32_16x16x32_bf16 v[70:73], v[160:163], v[212:215], v[70:73]
	v_mfma_f32_16x16x32_bf16 v[78:81], v[152:155], v[212:215], v[78:81]
	v_mfma_f32_16x16x32_bf16 v[78:81], v[148:151], v[208:211], v[78:81]
	s_setprio 0
	s_setprio 1
	v_mfma_f32_16x16x32_bf16 v[126:129], v[164:167], v[180:183], v[126:129]
	v_mfma_f32_16x16x32_bf16 v[126:129], v[168:171], v[184:187], v[126:129]
	v_mfma_f32_16x16x32_bf16 v[114:117], v[176:179], v[184:187], v[114:117]
	v_mfma_f32_16x16x32_bf16 v[114:117], v[172:175], v[180:183], v[114:117]
	v_mfma_f32_16x16x32_bf16 v[98:101], v[172:175], v[188:191], v[98:101]
	v_mfma_f32_16x16x32_bf16 v[98:101], v[176:179], v[192:195], v[98:101]
	v_mfma_f32_16x16x32_bf16 v[106:109], v[168:171], v[192:195], v[106:109]
	v_mfma_f32_16x16x32_bf16 v[106:109], v[164:167], v[188:191], v[106:109]
	v_mfma_f32_16x16x32_bf16 v[90:93], v[164:167], v[196:199], v[90:93]
	v_mfma_f32_16x16x32_bf16 v[90:93], v[168:171], v[200:203], v[90:93]
	v_mfma_f32_16x16x32_bf16 v[82:85], v[176:179], v[200:203], v[82:85]
	v_mfma_f32_16x16x32_bf16 v[82:85], v[172:175], v[196:199], v[82:85]
	v_mfma_f32_16x16x32_bf16 v[66:69], v[172:175], v[208:211], v[66:69]
	v_mfma_f32_16x16x32_bf16 v[66:69], v[176:179], v[212:215], v[66:69]
	v_mfma_f32_16x16x32_bf16 v[74:77], v[168:171], v[212:215], v[74:77]
	v_mfma_f32_16x16x32_bf16 v[74:77], v[164:167], v[208:211], v[74:77]
	s_setprio 0
	s_barrier
	s_add_i32 s45, s36, s13
	v_lshl_add_u64 v[204:205], s[2:3], 0, v[132:133]
	s_mov_b32 m0, s45
	ds_read_b128 v[180:183], v147 offset:16384
	ds_read_b128 v[184:187], v147 offset:17408
	ds_read_b128 v[188:191], v147 offset:18432
	ds_read_b128 v[192:195], v147 offset:19456
	ds_read_b128 v[196:199], v147 offset:20480
	ds_read_b128 v[200:203], v147 offset:21504
	ds_read_b128 v[208:211], v147 offset:22528
	ds_read_b128 v[212:215], v147 offset:23552
	global_load_lds_dwordx4 v[204:205], off
	s_add_i32 m0, s45, 0x2000
	s_add_u32 s46, s2, 0x100000
	v_lshl_add_u64 v[216:217], s[2:3], 0, v[136:137]
	s_addc_u32 s47, s3, 0
	s_add_i32 s45, s37, s13
	global_load_lds_dwordx4 v[216:217], off
	v_lshl_add_u64 v[218:219], s[46:47], 0, v[132:133]
	s_mov_b32 m0, s45
	v_lshl_add_u64 v[220:221], s[8:9], 0, v[134:135]
	global_load_lds_dwordx4 v[218:219], off
	v_lshl_add_u64 v[218:219], s[46:47], 0, v[136:137]
	s_add_i32 m0, s45, 0x2000
	s_nop 0
	global_load_lds_dwordx4 v[218:219], off
	v_lshl_add_u64 v[218:219], s[8:9], 0, v[130:131]
	s_mov_b32 m0, s16
	s_nop 0
	global_load_lds_dwordx4 v[218:219], off
	s_mov_b32 m0, s17
	s_nop 0
	global_load_lds_dwordx4 v[220:221], off
	s_waitcnt vmcnt(8)
	s_waitcnt lgkmcnt(0)
	s_barrier
	s_setprio 1
	s_waitcnt lgkmcnt(0)
	v_mfma_f32_16x16x32_bf16 v[62:65], v[148:151], v[180:183], v[62:65]
	v_mfma_f32_16x16x32_bf16 v[62:65], v[152:155], v[184:187], v[62:65]
	v_mfma_f32_16x16x32_bf16 v[54:57], v[160:163], v[184:187], v[54:57]
	v_mfma_f32_16x16x32_bf16 v[54:57], v[156:159], v[180:183], v[54:57]
	v_mfma_f32_16x16x32_bf16 v[38:41], v[156:159], v[188:191], v[38:41]
	v_mfma_f32_16x16x32_bf16 v[38:41], v[160:163], v[192:195], v[38:41]
	v_mfma_f32_16x16x32_bf16 v[46:49], v[152:155], v[192:195], v[46:49]
	v_mfma_f32_16x16x32_bf16 v[46:49], v[148:151], v[188:191], v[46:49]
	v_mfma_f32_16x16x32_bf16 v[30:33], v[148:151], v[196:199], v[30:33]
	v_mfma_f32_16x16x32_bf16 v[30:33], v[152:155], v[200:203], v[30:33]
	v_mfma_f32_16x16x32_bf16 v[22:25], v[160:163], v[200:203], v[22:25]
	v_mfma_f32_16x16x32_bf16 v[22:25], v[156:159], v[196:199], v[22:25]
	v_mfma_f32_16x16x32_bf16 v[6:9], v[156:159], v[208:211], v[6:9]
	v_mfma_f32_16x16x32_bf16 v[6:9], v[160:163], v[212:215], v[6:9]
	v_mfma_f32_16x16x32_bf16 v[14:17], v[152:155], v[212:215], v[14:17]
	v_mfma_f32_16x16x32_bf16 v[14:17], v[148:151], v[208:211], v[14:17]
	s_setprio 0
	s_setprio 1
	v_mfma_f32_16x16x32_bf16 v[58:61], v[164:167], v[180:183], v[58:61]
	v_mfma_f32_16x16x32_bf16 v[58:61], v[168:171], v[184:187], v[58:61]
	v_mfma_f32_16x16x32_bf16 v[50:53], v[176:179], v[184:187], v[50:53]
	v_mfma_f32_16x16x32_bf16 v[50:53], v[172:175], v[180:183], v[50:53]
	v_mfma_f32_16x16x32_bf16 v[34:37], v[172:175], v[188:191], v[34:37]
	v_mfma_f32_16x16x32_bf16 v[34:37], v[176:179], v[192:195], v[34:37]
	v_mfma_f32_16x16x32_bf16 v[42:45], v[168:171], v[192:195], v[42:45]
	v_mfma_f32_16x16x32_bf16 v[42:45], v[164:167], v[188:191], v[42:45]
	v_mfma_f32_16x16x32_bf16 v[26:29], v[164:167], v[196:199], v[26:29]
	v_mfma_f32_16x16x32_bf16 v[26:29], v[168:171], v[200:203], v[26:29]
	v_mfma_f32_16x16x32_bf16 v[18:21], v[176:179], v[200:203], v[18:21]
	v_mfma_f32_16x16x32_bf16 v[18:21], v[172:175], v[196:199], v[18:21]
	v_mfma_f32_16x16x32_bf16 v[2:5], v[172:175], v[208:211], v[2:5]
	v_mfma_f32_16x16x32_bf16 v[2:5], v[176:179], v[212:215], v[2:5]
	v_mfma_f32_16x16x32_bf16 v[10:13], v[168:171], v[212:215], v[10:13]
	v_mfma_f32_16x16x32_bf16 v[10:13], v[164:167], v[208:211], v[10:13]
	s_setprio 0
	s_barrier
	s_add_i32 s45, 0, 0x18000
	s_add_i32 s46, 0, 0x1c000
	v_add_u32_e32 v160, s45, v1
	v_add_u32_e32 v176, s46, v1
	ds_read_b128 v[148:151], v160
	ds_read_b128 v[152:155], v160 offset:1024
	ds_read_b128 v[156:159], v160 offset:2048
	ds_read_b128 v[160:163], v160 offset:3072
	ds_read_b128 v[164:167], v176
	ds_read_b128 v[168:171], v176 offset:1024
	ds_read_b128 v[172:175], v176 offset:2048
	ds_read_b128 v[176:179], v176 offset:3072
	s_add_u32 s8, s8, 0x100000
	s_addc_u32 s9, s9, 0
	s_mov_b32 m0, s18
	v_lshl_add_u64 v[222:223], s[8:9], 0, v[130:131]
	ds_read_b128 v[180:183], v147 offset:32768
	ds_read_b128 v[184:187], v147 offset:33792
	ds_read_b128 v[188:191], v147 offset:34816
	ds_read_b128 v[192:195], v147 offset:35840
	ds_read_b128 v[196:199], v147 offset:36864
	ds_read_b128 v[200:203], v147 offset:37888
	ds_read_b128 v[208:211], v147 offset:38912
	ds_read_b128 v[212:215], v147 offset:39936
	global_load_lds_dwordx4 v[222:223], off
	v_lshl_add_u64 v[222:223], s[8:9], 0, v[134:135]
	s_mov_b32 m0, s19
	s_nop 0
	global_load_lds_dwordx4 v[222:223], off
	s_waitcnt vmcnt(8)
	s_waitcnt lgkmcnt(0)
	s_barrier
	s_setprio 1
	s_waitcnt lgkmcnt(0)
	v_mfma_f32_16x16x32_bf16 v[122:125], v[148:151], v[180:183], v[122:125]
	v_mfma_f32_16x16x32_bf16 v[122:125], v[152:155], v[184:187], v[122:125]
	v_mfma_f32_16x16x32_bf16 v[118:121], v[160:163], v[184:187], v[118:121]
	v_mfma_f32_16x16x32_bf16 v[118:121], v[156:159], v[180:183], v[118:121]
	v_mfma_f32_16x16x32_bf16 v[102:105], v[156:159], v[188:191], v[102:105]
	v_mfma_f32_16x16x32_bf16 v[102:105], v[160:163], v[192:195], v[102:105]
	v_mfma_f32_16x16x32_bf16 v[110:113], v[152:155], v[192:195], v[110:113]
	v_mfma_f32_16x16x32_bf16 v[110:113], v[148:151], v[188:191], v[110:113]
	v_mfma_f32_16x16x32_bf16 v[94:97], v[148:151], v[196:199], v[94:97]
	v_mfma_f32_16x16x32_bf16 v[94:97], v[152:155], v[200:203], v[94:97]
	v_mfma_f32_16x16x32_bf16 v[86:89], v[160:163], v[200:203], v[86:89]
	v_mfma_f32_16x16x32_bf16 v[86:89], v[156:159], v[196:199], v[86:89]
	v_mfma_f32_16x16x32_bf16 v[70:73], v[156:159], v[208:211], v[70:73]
	v_mfma_f32_16x16x32_bf16 v[70:73], v[160:163], v[212:215], v[70:73]
	v_mfma_f32_16x16x32_bf16 v[78:81], v[152:155], v[212:215], v[78:81]
	v_mfma_f32_16x16x32_bf16 v[78:81], v[148:151], v[208:211], v[78:81]
	s_setprio 0
	s_setprio 1
	v_mfma_f32_16x16x32_bf16 v[126:129], v[164:167], v[180:183], v[126:129]
	v_mfma_f32_16x16x32_bf16 v[126:129], v[168:171], v[184:187], v[126:129]
	v_mfma_f32_16x16x32_bf16 v[114:117], v[176:179], v[184:187], v[114:117]
	v_mfma_f32_16x16x32_bf16 v[114:117], v[172:175], v[180:183], v[114:117]
	v_mfma_f32_16x16x32_bf16 v[98:101], v[172:175], v[188:191], v[98:101]
	v_mfma_f32_16x16x32_bf16 v[98:101], v[176:179], v[192:195], v[98:101]
	v_mfma_f32_16x16x32_bf16 v[106:109], v[168:171], v[192:195], v[106:109]
	v_mfma_f32_16x16x32_bf16 v[106:109], v[164:167], v[188:191], v[106:109]
	v_mfma_f32_16x16x32_bf16 v[90:93], v[164:167], v[196:199], v[90:93]
	v_mfma_f32_16x16x32_bf16 v[90:93], v[168:171], v[200:203], v[90:93]
	v_mfma_f32_16x16x32_bf16 v[82:85], v[176:179], v[200:203], v[82:85]
	v_mfma_f32_16x16x32_bf16 v[82:85], v[172:175], v[196:199], v[82:85]
	v_mfma_f32_16x16x32_bf16 v[66:69], v[172:175], v[208:211], v[66:69]
	v_mfma_f32_16x16x32_bf16 v[66:69], v[176:179], v[212:215], v[66:69]
	v_mfma_f32_16x16x32_bf16 v[74:77], v[168:171], v[212:215], v[74:77]
	v_mfma_f32_16x16x32_bf16 v[74:77], v[164:167], v[208:211], v[74:77]
	s_setprio 0
	s_barrier
	s_add_i32 s8, s45, s13
	v_lshl_add_u64 v[204:205], v[204:205], 0, s[24:25]
	s_mov_b32 m0, s8
	ds_read_b128 v[180:183], v147 offset:49152
	ds_read_b128 v[184:187], v147 offset:50176
	ds_read_b128 v[188:191], v147 offset:51200
	ds_read_b128 v[192:195], v147 offset:52224
	ds_read_b128 v[196:199], v147 offset:53248
	ds_read_b128 v[200:203], v147 offset:54272
	ds_read_b128 v[208:211], v147 offset:55296
	ds_read_b128 v[212:215], v147 offset:56320
	global_load_lds_dwordx4 v[204:205], off
	s_add_i32 m0, s8, 0x2000
	s_add_u32 s2, s2, 0x100080
	v_lshl_add_u64 v[204:205], v[216:217], 0, s[24:25]
	s_addc_u32 s3, s3, 0
	s_add_i32 s8, s46, s13
	global_load_lds_dwordx4 v[204:205], off
	v_lshl_add_u64 v[204:205], s[2:3], 0, v[132:133]
	s_mov_b32 m0, s8
	s_nop 0
	global_load_lds_dwordx4 v[204:205], off
	v_lshl_add_u64 v[204:205], s[2:3], 0, v[136:137]
	s_add_i32 m0, s8, 0x2000
	s_nop 0
	global_load_lds_dwordx4 v[204:205], off
	v_lshl_add_u64 v[204:205], v[218:219], 0, s[24:25]
	s_mov_b32 m0, s29
	s_nop 0
	global_load_lds_dwordx4 v[204:205], off
	v_lshl_add_u64 v[204:205], v[220:221], 0, s[24:25]
	s_mov_b32 m0, s34
	s_nop 0
	global_load_lds_dwordx4 v[204:205], off
	s_waitcnt vmcnt(8)
	s_waitcnt lgkmcnt(0)
	s_barrier
	s_setprio 1
	s_waitcnt lgkmcnt(0)
	v_mfma_f32_16x16x32_bf16 v[62:65], v[148:151], v[180:183], v[62:65]
	v_mfma_f32_16x16x32_bf16 v[62:65], v[152:155], v[184:187], v[62:65]
	v_mfma_f32_16x16x32_bf16 v[54:57], v[160:163], v[184:187], v[54:57]
	v_mfma_f32_16x16x32_bf16 v[54:57], v[156:159], v[180:183], v[54:57]
	v_mfma_f32_16x16x32_bf16 v[38:41], v[156:159], v[188:191], v[38:41]
	v_mfma_f32_16x16x32_bf16 v[38:41], v[160:163], v[192:195], v[38:41]
	v_mfma_f32_16x16x32_bf16 v[46:49], v[152:155], v[192:195], v[46:49]
	v_mfma_f32_16x16x32_bf16 v[46:49], v[148:151], v[188:191], v[46:49]
	v_mfma_f32_16x16x32_bf16 v[30:33], v[148:151], v[196:199], v[30:33]
	v_mfma_f32_16x16x32_bf16 v[30:33], v[152:155], v[200:203], v[30:33]
	v_mfma_f32_16x16x32_bf16 v[22:25], v[160:163], v[200:203], v[22:25]
	v_mfma_f32_16x16x32_bf16 v[22:25], v[156:159], v[196:199], v[22:25]
	v_mfma_f32_16x16x32_bf16 v[6:9], v[156:159], v[208:211], v[6:9]
	v_mfma_f32_16x16x32_bf16 v[6:9], v[160:163], v[212:215], v[6:9]
	v_mfma_f32_16x16x32_bf16 v[14:17], v[152:155], v[212:215], v[14:17]
	v_mfma_f32_16x16x32_bf16 v[14:17], v[148:151], v[208:211], v[14:17]
	s_setprio 0
	s_setprio 1
	v_mfma_f32_16x16x32_bf16 v[58:61], v[164:167], v[180:183], v[58:61]
	v_mfma_f32_16x16x32_bf16 v[58:61], v[168:171], v[184:187], v[58:61]
	v_mfma_f32_16x16x32_bf16 v[50:53], v[176:179], v[184:187], v[50:53]
	v_mfma_f32_16x16x32_bf16 v[50:53], v[172:175], v[180:183], v[50:53]
	v_mfma_f32_16x16x32_bf16 v[34:37], v[172:175], v[188:191], v[34:37]
	v_mfma_f32_16x16x32_bf16 v[34:37], v[176:179], v[192:195], v[34:37]
	v_mfma_f32_16x16x32_bf16 v[42:45], v[168:171], v[192:195], v[42:45]
	v_mfma_f32_16x16x32_bf16 v[42:45], v[164:167], v[188:191], v[42:45]
	v_mfma_f32_16x16x32_bf16 v[26:29], v[164:167], v[196:199], v[26:29]
	v_mfma_f32_16x16x32_bf16 v[26:29], v[168:171], v[200:203], v[26:29]
	v_mfma_f32_16x16x32_bf16 v[18:21], v[176:179], v[200:203], v[18:21]
	v_mfma_f32_16x16x32_bf16 v[18:21], v[172:175], v[196:199], v[18:21]
	v_mfma_f32_16x16x32_bf16 v[2:5], v[172:175], v[208:211], v[2:5]
	v_mfma_f32_16x16x32_bf16 v[2:5], v[176:179], v[212:215], v[2:5]
	v_mfma_f32_16x16x32_bf16 v[10:13], v[168:171], v[212:215], v[10:13]
	v_mfma_f32_16x16x32_bf16 v[10:13], v[164:167], v[208:211], v[10:13]
	s_setprio 0
	s_barrier
	s_add_u32 s4, s4, 0x100
	s_addc_u32 s5, s5, 0
	s_add_u32 s42, s42, 0x100
	s_addc_u32 s43, s43, 0
	s_cmp_ge_i32 s44, s1
	s_mov_b32 s2, s44
	s_cbranch_scc0 .LBB0_267

.LBB0_524:
	s_lshl_b32 s0, s26, 20
	s_and_b32 s0, s0, 0xff00000
	s_add_u32 s0, s70, s0
	s_addc_u32 s23, s71, 0
	s_lshr_b32 s22, s26, 13
	s_and_b32 s24, s22, 0x7ff80
	s_add_u32 s22, s0, s24
	s_addc_u32 s23, s23, 0
	s_lshl_b32 s0, s26, 12
	s_and_b32 s0, s0, 0xff00000
	s_add_u32 s0, s30, s0
	s_addc_u32 s25, s31, 0
	s_add_u32 s24, s0, s24
	s_addc_u32 s25, s25, 0
	s_cmp_lt_i32 s37, 1
	v_cmp_gt_i64_e64 s[26:27], s[26:27], -1
	s_cbranch_scc1 .LBB0_546
	s_and_b64 s[40:41], s[26:27], exec
	s_cselect_b32 s0, s23, s39
	s_cselect_b32 s36, s22, s38
	s_cselect_b32 s65, s25, s3
	s_cselect_b32 s66, s24, s2
	s_add_i32 s67, s37, -2
	s_add_u32 s38, s38, 0x80080
	s_addc_u32 s39, s39, 0
	s_add_u32 s68, s2, 0x100
	s_addc_u32 s69, s3, 0
	s_mov_b32 s2, 0
	ds_read_b128 v[148:151], v144
	ds_read_b128 v[152:155], v144 offset:1024
	ds_read_b128 v[156:159], v144 offset:2048
	ds_read_b128 v[160:163], v144 offset:3072
	ds_read_b128 v[164:167], v145
	ds_read_b128 v[168:171], v145 offset:1024
	ds_read_b128 v[172:175], v145 offset:2048
	ds_read_b128 v[176:179], v145 offset:3072
	s_waitcnt lgkmcnt(0)
	s_add_i32 s72, s2, 2
	s_add_u32 s3, s38, 0xfff80080
	s_addc_u32 s40, s39, -1
	s_cmp_eq_u32 s67, s2
	s_cselect_b32 s2, s66, s68
	s_cselect_b32 s41, s0, s40
	s_cselect_b32 s40, s36, s3
	s_cselect_b32 s3, s65, s69
	v_lshl_add_u64 v[204:205], s[38:39], 0, v[138:139]
	s_add_i32 m0, s29, 0xc000
	ds_read_b128 v[180:183], v146
	ds_read_b128 v[184:187], v146 offset:1024
	ds_read_b128 v[188:191], v146 offset:2048
	ds_read_b128 v[192:195], v146 offset:3072
	ds_read_b128 v[196:199], v146 offset:4096
	ds_read_b128 v[200:203], v146 offset:5120
	ds_read_b128 v[208:211], v146 offset:6144
	ds_read_b128 v[212:215], v146 offset:7168
	global_load_lds_dwordx4 v[204:205], off
	v_lshl_add_u64 v[204:205], s[38:39], 0, v[140:141]
	s_add_i32 m0, s29, 0xe000
	s_nop 0
	global_load_lds_dwordx4 v[204:205], off
	s_waitcnt vmcnt(8)
	s_waitcnt lgkmcnt(0)
	s_barrier
	s_setprio 1
	s_waitcnt lgkmcnt(0)
	v_mfma_f32_16x16x32_bf16 v[126:129], v[148:151], v[180:183], 0
	v_mfma_f32_16x16x32_bf16 v[126:129], v[152:155], v[184:187], v[126:129]
	v_mfma_f32_16x16x32_bf16 v[122:125], v[160:163], v[184:187], 0
	v_mfma_f32_16x16x32_bf16 v[122:125], v[156:159], v[180:183], v[122:125]
	v_mfma_f32_16x16x32_bf16 v[102:105], v[156:159], v[188:191], 0
	v_mfma_f32_16x16x32_bf16 v[102:105], v[160:163], v[192:195], v[102:105]
	v_mfma_f32_16x16x32_bf16 v[110:113], v[152:155], v[192:195], 0
	v_mfma_f32_16x16x32_bf16 v[110:113], v[148:151], v[188:191], v[110:113]
	v_mfma_f32_16x16x32_bf16 v[94:97], v[148:151], v[196:199], 0
	v_mfma_f32_16x16x32_bf16 v[94:97], v[152:155], v[200:203], v[94:97]
	v_mfma_f32_16x16x32_bf16 v[86:89], v[160:163], v[200:203], 0
	v_mfma_f32_16x16x32_bf16 v[86:89], v[156:159], v[196:199], v[86:89]
	v_mfma_f32_16x16x32_bf16 v[70:73], v[156:159], v[208:211], 0
	v_mfma_f32_16x16x32_bf16 v[70:73], v[160:163], v[212:215], v[70:73]
	v_mfma_f32_16x16x32_bf16 v[78:81], v[152:155], v[212:215], 0
	v_mfma_f32_16x16x32_bf16 v[78:81], v[148:151], v[208:211], v[78:81]
	s_setprio 0
	s_setprio 1
	v_mfma_f32_16x16x32_bf16 v[118:121], v[164:167], v[180:183], 0
	v_mfma_f32_16x16x32_bf16 v[118:121], v[168:171], v[184:187], v[118:121]
	v_mfma_f32_16x16x32_bf16 v[114:117], v[176:179], v[184:187], 0
	v_mfma_f32_16x16x32_bf16 v[114:117], v[172:175], v[180:183], v[114:117]
	v_mfma_f32_16x16x32_bf16 v[98:101], v[172:175], v[188:191], 0
	v_mfma_f32_16x16x32_bf16 v[98:101], v[176:179], v[192:195], v[98:101]
	v_mfma_f32_16x16x32_bf16 v[106:109], v[168:171], v[192:195], 0
	v_mfma_f32_16x16x32_bf16 v[106:109], v[164:167], v[188:191], v[106:109]
	v_mfma_f32_16x16x32_bf16 v[90:93], v[164:167], v[196:199], 0
	v_mfma_f32_16x16x32_bf16 v[90:93], v[168:171], v[200:203], v[90:93]
	v_mfma_f32_16x16x32_bf16 v[82:85], v[176:179], v[200:203], 0
	v_mfma_f32_16x16x32_bf16 v[82:85], v[172:175], v[196:199], v[82:85]
	v_mfma_f32_16x16x32_bf16 v[66:69], v[172:175], v[208:211], 0
	v_mfma_f32_16x16x32_bf16 v[66:69], v[176:179], v[212:215], v[66:69]
	v_mfma_f32_16x16x32_bf16 v[74:77], v[168:171], v[212:215], 0
	v_mfma_f32_16x16x32_bf16 v[74:77], v[164:167], v[208:211], v[74:77]
	s_setprio 0
	s_barrier
	s_add_i32 s73, s52, s33
	v_lshl_add_u64 v[204:205], s[2:3], 0, v[132:133]
	s_mov_b32 m0, s73
	ds_read_b128 v[180:183], v146 offset:16384
	ds_read_b128 v[184:187], v146 offset:17408
	ds_read_b128 v[188:191], v146 offset:18432
	ds_read_b128 v[192:195], v146 offset:19456
	ds_read_b128 v[196:199], v146 offset:20480
	ds_read_b128 v[200:203], v146 offset:21504
	ds_read_b128 v[208:211], v146 offset:22528
	ds_read_b128 v[212:215], v146 offset:23552
	global_load_lds_dwordx4 v[204:205], off
	s_add_i32 m0, s73, 0x2000
	s_add_u32 s74, s2, 0x80000
	v_lshl_add_u64 v[216:217], s[2:3], 0, v[136:137]
	s_addc_u32 s75, s3, 0
	s_add_i32 s73, s53, s33
	global_load_lds_dwordx4 v[216:217], off
	v_lshl_add_u64 v[218:219], s[74:75], 0, v[132:133]
	s_mov_b32 m0, s73
	v_lshl_add_u64 v[220:221], s[40:41], 0, v[134:135]
	global_load_lds_dwordx4 v[218:219], off
	v_lshl_add_u64 v[218:219], s[74:75], 0, v[136:137]
	s_add_i32 m0, s73, 0x2000
	s_nop 0
	global_load_lds_dwordx4 v[218:219], off
	v_lshl_add_u64 v[218:219], s[40:41], 0, v[130:131]
	s_mov_b32 m0, s29
	s_nop 0
	global_load_lds_dwordx4 v[218:219], off
	s_mov_b32 m0, s35
	s_nop 0
	global_load_lds_dwordx4 v[220:221], off
	s_waitcnt vmcnt(8)
	s_waitcnt lgkmcnt(0)
	s_barrier
	s_setprio 1
	s_waitcnt lgkmcnt(0)
	v_mfma_f32_16x16x32_bf16 v[62:65], v[148:151], v[180:183], 0
	v_mfma_f32_16x16x32_bf16 v[62:65], v[152:155], v[184:187], v[62:65]
	v_mfma_f32_16x16x32_bf16 v[54:57], v[160:163], v[184:187], 0
	v_mfma_f32_16x16x32_bf16 v[54:57], v[156:159], v[180:183], v[54:57]
	v_mfma_f32_16x16x32_bf16 v[38:41], v[156:159], v[188:191], 0
	v_mfma_f32_16x16x32_bf16 v[38:41], v[160:163], v[192:195], v[38:41]
	v_mfma_f32_16x16x32_bf16 v[46:49], v[152:155], v[192:195], 0
	v_mfma_f32_16x16x32_bf16 v[46:49], v[148:151], v[188:191], v[46:49]
	v_mfma_f32_16x16x32_bf16 v[30:33], v[148:151], v[196:199], 0
	v_mfma_f32_16x16x32_bf16 v[30:33], v[152:155], v[200:203], v[30:33]
	v_mfma_f32_16x16x32_bf16 v[22:25], v[160:163], v[200:203], 0
	v_mfma_f32_16x16x32_bf16 v[22:25], v[156:159], v[196:199], v[22:25]
	v_mfma_f32_16x16x32_bf16 v[6:9], v[156:159], v[208:211], 0
	v_mfma_f32_16x16x32_bf16 v[6:9], v[160:163], v[212:215], v[6:9]
	v_mfma_f32_16x16x32_bf16 v[14:17], v[152:155], v[212:215], 0
	v_mfma_f32_16x16x32_bf16 v[14:17], v[148:151], v[208:211], v[14:17]
	s_setprio 0
	s_setprio 1
	v_mfma_f32_16x16x32_bf16 v[58:61], v[164:167], v[180:183], 0
	v_mfma_f32_16x16x32_bf16 v[58:61], v[168:171], v[184:187], v[58:61]
	v_mfma_f32_16x16x32_bf16 v[50:53], v[176:179], v[184:187], 0
	v_mfma_f32_16x16x32_bf16 v[50:53], v[172:175], v[180:183], v[50:53]
	v_mfma_f32_16x16x32_bf16 v[34:37], v[172:175], v[188:191], 0
	v_mfma_f32_16x16x32_bf16 v[34:37], v[176:179], v[192:195], v[34:37]
	v_mfma_f32_16x16x32_bf16 v[42:45], v[168:171], v[192:195], 0
	v_mfma_f32_16x16x32_bf16 v[42:45], v[164:167], v[188:191], v[42:45]
	v_mfma_f32_16x16x32_bf16 v[26:29], v[164:167], v[196:199], 0
	v_mfma_f32_16x16x32_bf16 v[26:29], v[168:171], v[200:203], v[26:29]
	v_mfma_f32_16x16x32_bf16 v[18:21], v[176:179], v[200:203], 0
	v_mfma_f32_16x16x32_bf16 v[18:21], v[172:175], v[196:199], v[18:21]
	v_mfma_f32_16x16x32_bf16 v[2:5], v[172:175], v[208:211], 0
	v_mfma_f32_16x16x32_bf16 v[2:5], v[176:179], v[212:215], v[2:5]
	v_mfma_f32_16x16x32_bf16 v[10:13], v[168:171], v[212:215], 0
	v_mfma_f32_16x16x32_bf16 v[10:13], v[164:167], v[208:211], v[10:13]
	s_setprio 0
	s_barrier
	s_add_i32 s73, 0, 0x18000
	v_add_u32_e32 v147, s73, v142
	s_add_i32 s74, 0, 0x1c000
	ds_read_b128 v[148:151], v147
	ds_read_b128 v[152:155], v147 offset:1024
	ds_read_b128 v[156:159], v147 offset:2048
	ds_read_b128 v[160:163], v147 offset:3072
	v_add_u32_e32 v147, s74, v142
	ds_read_b128 v[164:167], v147
	ds_read_b128 v[168:171], v147 offset:1024
	ds_read_b128 v[172:175], v147 offset:2048
	ds_read_b128 v[176:179], v147 offset:3072
	s_add_u32 s40, s40, 0x80000
	s_addc_u32 s41, s41, 0
	s_mov_b32 m0, s43
	v_lshl_add_u64 v[222:223], s[40:41], 0, v[130:131]
	ds_read_b128 v[180:183], v146 offset:32768
	ds_read_b128 v[184:187], v146 offset:33792
	ds_read_b128 v[188:191], v146 offset:34816
	ds_read_b128 v[192:195], v146 offset:35840
	ds_read_b128 v[196:199], v146 offset:36864
	ds_read_b128 v[200:203], v146 offset:37888
	ds_read_b128 v[208:211], v146 offset:38912
	ds_read_b128 v[212:215], v146 offset:39936
	global_load_lds_dwordx4 v[222:223], off
	v_lshl_add_u64 v[222:223], s[40:41], 0, v[134:135]
	s_mov_b32 m0, s44
	s_nop 0
	global_load_lds_dwordx4 v[222:223], off
	s_waitcnt vmcnt(8)
	s_waitcnt lgkmcnt(0)
	s_barrier
	s_setprio 1
	s_waitcnt lgkmcnt(0)
	v_mfma_f32_16x16x32_bf16 v[126:129], v[148:151], v[180:183], v[126:129]
	v_mfma_f32_16x16x32_bf16 v[126:129], v[152:155], v[184:187], v[126:129]
	v_mfma_f32_16x16x32_bf16 v[122:125], v[160:163], v[184:187], v[122:125]
	v_mfma_f32_16x16x32_bf16 v[122:125], v[156:159], v[180:183], v[122:125]
	v_mfma_f32_16x16x32_bf16 v[102:105], v[156:159], v[188:191], v[102:105]
	v_mfma_f32_16x16x32_bf16 v[102:105], v[160:163], v[192:195], v[102:105]
	v_mfma_f32_16x16x32_bf16 v[110:113], v[152:155], v[192:195], v[110:113]
	v_mfma_f32_16x16x32_bf16 v[110:113], v[148:151], v[188:191], v[110:113]
	v_mfma_f32_16x16x32_bf16 v[94:97], v[148:151], v[196:199], v[94:97]
	v_mfma_f32_16x16x32_bf16 v[94:97], v[152:155], v[200:203], v[94:97]
	v_mfma_f32_16x16x32_bf16 v[86:89], v[160:163], v[200:203], v[86:89]
	v_mfma_f32_16x16x32_bf16 v[86:89], v[156:159], v[196:199], v[86:89]
	v_mfma_f32_16x16x32_bf16 v[70:73], v[156:159], v[208:211], v[70:73]
	v_mfma_f32_16x16x32_bf16 v[70:73], v[160:163], v[212:215], v[70:73]
	v_mfma_f32_16x16x32_bf16 v[78:81], v[152:155], v[212:215], v[78:81]
	v_mfma_f32_16x16x32_bf16 v[78:81], v[148:151], v[208:211], v[78:81]
	s_setprio 0
	s_setprio 1
	v_mfma_f32_16x16x32_bf16 v[118:121], v[164:167], v[180:183], v[118:121]
	v_mfma_f32_16x16x32_bf16 v[118:121], v[168:171], v[184:187], v[118:121]
	v_mfma_f32_16x16x32_bf16 v[114:117], v[176:179], v[184:187], v[114:117]
	v_mfma_f32_16x16x32_bf16 v[114:117], v[172:175], v[180:183], v[114:117]
	v_mfma_f32_16x16x32_bf16 v[98:101], v[172:175], v[188:191], v[98:101]
	v_mfma_f32_16x16x32_bf16 v[98:101], v[176:179], v[192:195], v[98:101]
	v_mfma_f32_16x16x32_bf16 v[106:109], v[168:171], v[192:195], v[106:109]
	v_mfma_f32_16x16x32_bf16 v[106:109], v[164:167], v[188:191], v[106:109]
	v_mfma_f32_16x16x32_bf16 v[90:93], v[164:167], v[196:199], v[90:93]
	v_mfma_f32_16x16x32_bf16 v[90:93], v[168:171], v[200:203], v[90:93]
	v_mfma_f32_16x16x32_bf16 v[82:85], v[176:179], v[200:203], v[82:85]
	v_mfma_f32_16x16x32_bf16 v[82:85], v[172:175], v[196:199], v[82:85]
	v_mfma_f32_16x16x32_bf16 v[66:69], v[172:175], v[208:211], v[66:69]
	v_mfma_f32_16x16x32_bf16 v[66:69], v[176:179], v[212:215], v[66:69]
	v_mfma_f32_16x16x32_bf16 v[74:77], v[168:171], v[212:215], v[74:77]
	v_mfma_f32_16x16x32_bf16 v[74:77], v[164:167], v[208:211], v[74:77]
	s_setprio 0
	s_barrier
	s_add_i32 s40, s73, s33
	v_lshl_add_u64 v[204:205], v[204:205], 0, s[16:17]
	s_mov_b32 m0, s40
	ds_read_b128 v[180:183], v146 offset:49152
	ds_read_b128 v[184:187], v146 offset:50176
	ds_read_b128 v[188:191], v146 offset:51200
	ds_read_b128 v[192:195], v146 offset:52224
	ds_read_b128 v[196:199], v146 offset:53248
	ds_read_b128 v[200:203], v146 offset:54272
	ds_read_b128 v[208:211], v146 offset:55296
	ds_read_b128 v[212:215], v146 offset:56320
	global_load_lds_dwordx4 v[204:205], off
	s_add_i32 m0, s40, 0x2000
	s_add_u32 s2, s2, 0x80080
	v_lshl_add_u64 v[204:205], v[216:217], 0, s[16:17]
	s_addc_u32 s3, s3, 0
	s_add_i32 s40, s74, s33
	global_load_lds_dwordx4 v[204:205], off
	v_lshl_add_u64 v[204:205], s[2:3], 0, v[132:133]
	s_mov_b32 m0, s40
	s_nop 0
	global_load_lds_dwordx4 v[204:205], off
	v_lshl_add_u64 v[204:205], s[2:3], 0, v[136:137]
	s_add_i32 m0, s40, 0x2000
	s_nop 0
	global_load_lds_dwordx4 v[204:205], off
	v_lshl_add_u64 v[204:205], v[218:219], 0, s[16:17]
	s_mov_b32 m0, s46
	s_nop 0
	global_load_lds_dwordx4 v[204:205], off
	v_lshl_add_u64 v[204:205], v[220:221], 0, s[16:17]
	s_mov_b32 m0, s47
	s_nop 0
	global_load_lds_dwordx4 v[204:205], off
	s_waitcnt vmcnt(8)
	s_waitcnt lgkmcnt(0)
	s_barrier
	s_setprio 1
	s_waitcnt lgkmcnt(0)
	v_mfma_f32_16x16x32_bf16 v[62:65], v[148:151], v[180:183], v[62:65]
	v_mfma_f32_16x16x32_bf16 v[62:65], v[152:155], v[184:187], v[62:65]
	v_mfma_f32_16x16x32_bf16 v[54:57], v[160:163], v[184:187], v[54:57]
	v_mfma_f32_16x16x32_bf16 v[54:57], v[156:159], v[180:183], v[54:57]
	v_mfma_f32_16x16x32_bf16 v[38:41], v[156:159], v[188:191], v[38:41]
	v_mfma_f32_16x16x32_bf16 v[38:41], v[160:163], v[192:195], v[38:41]
	v_mfma_f32_16x16x32_bf16 v[46:49], v[152:155], v[192:195], v[46:49]
	v_mfma_f32_16x16x32_bf16 v[46:49], v[148:151], v[188:191], v[46:49]
	v_mfma_f32_16x16x32_bf16 v[30:33], v[148:151], v[196:199], v[30:33]
	v_mfma_f32_16x16x32_bf16 v[30:33], v[152:155], v[200:203], v[30:33]
	v_mfma_f32_16x16x32_bf16 v[22:25], v[160:163], v[200:203], v[22:25]
	v_mfma_f32_16x16x32_bf16 v[22:25], v[156:159], v[196:199], v[22:25]
	v_mfma_f32_16x16x32_bf16 v[6:9], v[156:159], v[208:211], v[6:9]
	v_mfma_f32_16x16x32_bf16 v[6:9], v[160:163], v[212:215], v[6:9]
	v_mfma_f32_16x16x32_bf16 v[14:17], v[152:155], v[212:215], v[14:17]
	v_mfma_f32_16x16x32_bf16 v[14:17], v[148:151], v[208:211], v[14:17]
	s_setprio 0
	s_setprio 1
	v_mfma_f32_16x16x32_bf16 v[58:61], v[164:167], v[180:183], v[58:61]
	v_mfma_f32_16x16x32_bf16 v[58:61], v[168:171], v[184:187], v[58:61]
	v_mfma_f32_16x16x32_bf16 v[50:53], v[176:179], v[184:187], v[50:53]
	v_mfma_f32_16x16x32_bf16 v[50:53], v[172:175], v[180:183], v[50:53]
	v_mfma_f32_16x16x32_bf16 v[34:37], v[172:175], v[188:191], v[34:37]
	v_mfma_f32_16x16x32_bf16 v[34:37], v[176:179], v[192:195], v[34:37]
	v_mfma_f32_16x16x32_bf16 v[42:45], v[168:171], v[192:195], v[42:45]
	v_mfma_f32_16x16x32_bf16 v[42:45], v[164:167], v[188:191], v[42:45]
	v_mfma_f32_16x16x32_bf16 v[26:29], v[164:167], v[196:199], v[26:29]
	v_mfma_f32_16x16x32_bf16 v[26:29], v[168:171], v[200:203], v[26:29]
	v_mfma_f32_16x16x32_bf16 v[18:21], v[176:179], v[200:203], v[18:21]
	v_mfma_f32_16x16x32_bf16 v[18:21], v[172:175], v[196:199], v[18:21]
	v_mfma_f32_16x16x32_bf16 v[2:5], v[172:175], v[208:211], v[2:5]
	v_mfma_f32_16x16x32_bf16 v[2:5], v[176:179], v[212:215], v[2:5]
	v_mfma_f32_16x16x32_bf16 v[10:13], v[168:171], v[212:215], v[10:13]
	v_mfma_f32_16x16x32_bf16 v[10:13], v[164:167], v[208:211], v[10:13]
	s_setprio 0
	s_barrier
	s_add_u32 s38, s38, 0x100
	s_addc_u32 s39, s39, 0
	s_add_u32 s68, s68, 0x100
	s_addc_u32 s69, s69, 0
	s_cmp_ge_i32 s72, s37
	s_mov_b32 s2, s72
	s_cbranch_scc1 .Lkpeel_exit_2
.LBB0_526:
	ds_read_b128 v[148:151], v144
	ds_read_b128 v[152:155], v144 offset:1024
	ds_read_b128 v[156:159], v144 offset:2048
	ds_read_b128 v[160:163], v144 offset:3072
	ds_read_b128 v[164:167], v145
	ds_read_b128 v[168:171], v145 offset:1024
	ds_read_b128 v[172:175], v145 offset:2048
	ds_read_b128 v[176:179], v145 offset:3072
	s_waitcnt lgkmcnt(0)
	s_add_i32 s72, s2, 2
	s_add_u32 s3, s38, 0xfff80080
	s_addc_u32 s40, s39, -1
	s_cmp_eq_u32 s67, s2
	s_cselect_b32 s2, s66, s68
	s_cselect_b32 s41, s0, s40
	s_cselect_b32 s40, s36, s3
	s_cselect_b32 s3, s65, s69
	v_lshl_add_u64 v[204:205], s[38:39], 0, v[138:139]
	s_add_i32 m0, s29, 0xc000
	ds_read_b128 v[180:183], v146
	ds_read_b128 v[184:187], v146 offset:1024
	ds_read_b128 v[188:191], v146 offset:2048
	ds_read_b128 v[192:195], v146 offset:3072
	ds_read_b128 v[196:199], v146 offset:4096
	ds_read_b128 v[200:203], v146 offset:5120
	ds_read_b128 v[208:211], v146 offset:6144
	ds_read_b128 v[212:215], v146 offset:7168
	global_load_lds_dwordx4 v[204:205], off
	v_lshl_add_u64 v[204:205], s[38:39], 0, v[140:141]
	s_add_i32 m0, s29, 0xe000
	s_nop 0
	global_load_lds_dwordx4 v[204:205], off
	s_waitcnt vmcnt(8)
	s_waitcnt lgkmcnt(0)
	s_barrier
	s_setprio 1
	s_waitcnt lgkmcnt(0)
	v_mfma_f32_16x16x32_bf16 v[126:129], v[148:151], v[180:183], v[126:129]
	v_mfma_f32_16x16x32_bf16 v[126:129], v[152:155], v[184:187], v[126:129]
	v_mfma_f32_16x16x32_bf16 v[122:125], v[160:163], v[184:187], v[122:125]
	v_mfma_f32_16x16x32_bf16 v[122:125], v[156:159], v[180:183], v[122:125]
	v_mfma_f32_16x16x32_bf16 v[102:105], v[156:159], v[188:191], v[102:105]
	v_mfma_f32_16x16x32_bf16 v[102:105], v[160:163], v[192:195], v[102:105]
	v_mfma_f32_16x16x32_bf16 v[110:113], v[152:155], v[192:195], v[110:113]
	v_mfma_f32_16x16x32_bf16 v[110:113], v[148:151], v[188:191], v[110:113]
	v_mfma_f32_16x16x32_bf16 v[94:97], v[148:151], v[196:199], v[94:97]
	v_mfma_f32_16x16x32_bf16 v[94:97], v[152:155], v[200:203], v[94:97]
	v_mfma_f32_16x16x32_bf16 v[86:89], v[160:163], v[200:203], v[86:89]
	v_mfma_f32_16x16x32_bf16 v[86:89], v[156:159], v[196:199], v[86:89]
	v_mfma_f32_16x16x32_bf16 v[70:73], v[156:159], v[208:211], v[70:73]
	v_mfma_f32_16x16x32_bf16 v[70:73], v[160:163], v[212:215], v[70:73]
	v_mfma_f32_16x16x32_bf16 v[78:81], v[152:155], v[212:215], v[78:81]
	v_mfma_f32_16x16x32_bf16 v[78:81], v[148:151], v[208:211], v[78:81]
	s_setprio 0
	s_setprio 1
	v_mfma_f32_16x16x32_bf16 v[118:121], v[164:167], v[180:183], v[118:121]
	v_mfma_f32_16x16x32_bf16 v[118:121], v[168:171], v[184:187], v[118:121]
	v_mfma_f32_16x16x32_bf16 v[114:117], v[176:179], v[184:187], v[114:117]
	v_mfma_f32_16x16x32_bf16 v[114:117], v[172:175], v[180:183], v[114:117]
	v_mfma_f32_16x16x32_bf16 v[98:101], v[172:175], v[188:191], v[98:101]
	v_mfma_f32_16x16x32_bf16 v[98:101], v[176:179], v[192:195], v[98:101]
	v_mfma_f32_16x16x32_bf16 v[106:109], v[168:171], v[192:195], v[106:109]
	v_mfma_f32_16x16x32_bf16 v[106:109], v[164:167], v[188:191], v[106:109]
	v_mfma_f32_16x16x32_bf16 v[90:93], v[164:167], v[196:199], v[90:93]
	v_mfma_f32_16x16x32_bf16 v[90:93], v[168:171], v[200:203], v[90:93]
	v_mfma_f32_16x16x32_bf16 v[82:85], v[176:179], v[200:203], v[82:85]
	v_mfma_f32_16x16x32_bf16 v[82:85], v[172:175], v[196:199], v[82:85]
	v_mfma_f32_16x16x32_bf16 v[66:69], v[172:175], v[208:211], v[66:69]
	v_mfma_f32_16x16x32_bf16 v[66:69], v[176:179], v[212:215], v[66:69]
	v_mfma_f32_16x16x32_bf16 v[74:77], v[168:171], v[212:215], v[74:77]
	v_mfma_f32_16x16x32_bf16 v[74:77], v[164:167], v[208:211], v[74:77]
	s_setprio 0
	s_barrier
	s_add_i32 s73, s52, s33
	v_lshl_add_u64 v[204:205], s[2:3], 0, v[132:133]
	s_mov_b32 m0, s73
	ds_read_b128 v[180:183], v146 offset:16384
	ds_read_b128 v[184:187], v146 offset:17408
	ds_read_b128 v[188:191], v146 offset:18432
	ds_read_b128 v[192:195], v146 offset:19456
	ds_read_b128 v[196:199], v146 offset:20480
	ds_read_b128 v[200:203], v146 offset:21504
	ds_read_b128 v[208:211], v146 offset:22528
	ds_read_b128 v[212:215], v146 offset:23552
	global_load_lds_dwordx4 v[204:205], off
	s_add_i32 m0, s73, 0x2000
	s_add_u32 s74, s2, 0x80000
	v_lshl_add_u64 v[216:217], s[2:3], 0, v[136:137]
	s_addc_u32 s75, s3, 0
	s_add_i32 s73, s53, s33
	global_load_lds_dwordx4 v[216:217], off
	v_lshl_add_u64 v[218:219], s[74:75], 0, v[132:133]
	s_mov_b32 m0, s73
	v_lshl_add_u64 v[220:221], s[40:41], 0, v[134:135]
	global_load_lds_dwordx4 v[218:219], off
	v_lshl_add_u64 v[218:219], s[74:75], 0, v[136:137]
	s_add_i32 m0, s73, 0x2000
	s_nop 0
	global_load_lds_dwordx4 v[218:219], off
	v_lshl_add_u64 v[218:219], s[40:41], 0, v[130:131]
	s_mov_b32 m0, s29
	s_nop 0
	global_load_lds_dwordx4 v[218:219], off
	s_mov_b32 m0, s35
	s_nop 0
	global_load_lds_dwordx4 v[220:221], off
	s_waitcnt vmcnt(8)
	s_waitcnt lgkmcnt(0)
	s_barrier
	s_setprio 1
	s_waitcnt lgkmcnt(0)
	v_mfma_f32_16x16x32_bf16 v[62:65], v[148:151], v[180:183], v[62:65]
	v_mfma_f32_16x16x32_bf16 v[62:65], v[152:155], v[184:187], v[62:65]
	v_mfma_f32_16x16x32_bf16 v[54:57], v[160:163], v[184:187], v[54:57]
	v_mfma_f32_16x16x32_bf16 v[54:57], v[156:159], v[180:183], v[54:57]
	v_mfma_f32_16x16x32_bf16 v[38:41], v[156:159], v[188:191], v[38:41]
	v_mfma_f32_16x16x32_bf16 v[38:41], v[160:163], v[192:195], v[38:41]
	v_mfma_f32_16x16x32_bf16 v[46:49], v[152:155], v[192:195], v[46:49]
	v_mfma_f32_16x16x32_bf16 v[46:49], v[148:151], v[188:191], v[46:49]
	v_mfma_f32_16x16x32_bf16 v[30:33], v[148:151], v[196:199], v[30:33]
	v_mfma_f32_16x16x32_bf16 v[30:33], v[152:155], v[200:203], v[30:33]
	v_mfma_f32_16x16x32_bf16 v[22:25], v[160:163], v[200:203], v[22:25]
	v_mfma_f32_16x16x32_bf16 v[22:25], v[156:159], v[196:199], v[22:25]
	v_mfma_f32_16x16x32_bf16 v[6:9], v[156:159], v[208:211], v[6:9]
	v_mfma_f32_16x16x32_bf16 v[6:9], v[160:163], v[212:215], v[6:9]
	v_mfma_f32_16x16x32_bf16 v[14:17], v[152:155], v[212:215], v[14:17]
	v_mfma_f32_16x16x32_bf16 v[14:17], v[148:151], v[208:211], v[14:17]
	s_setprio 0
	s_setprio 1
	v_mfma_f32_16x16x32_bf16 v[58:61], v[164:167], v[180:183], v[58:61]
	v_mfma_f32_16x16x32_bf16 v[58:61], v[168:171], v[184:187], v[58:61]
	v_mfma_f32_16x16x32_bf16 v[50:53], v[176:179], v[184:187], v[50:53]
	v_mfma_f32_16x16x32_bf16 v[50:53], v[172:175], v[180:183], v[50:53]
	v_mfma_f32_16x16x32_bf16 v[34:37], v[172:175], v[188:191], v[34:37]
	v_mfma_f32_16x16x32_bf16 v[34:37], v[176:179], v[192:195], v[34:37]
	v_mfma_f32_16x16x32_bf16 v[42:45], v[168:171], v[192:195], v[42:45]
	v_mfma_f32_16x16x32_bf16 v[42:45], v[164:167], v[188:191], v[42:45]
	v_mfma_f32_16x16x32_bf16 v[26:29], v[164:167], v[196:199], v[26:29]
	v_mfma_f32_16x16x32_bf16 v[26:29], v[168:171], v[200:203], v[26:29]
	v_mfma_f32_16x16x32_bf16 v[18:21], v[176:179], v[200:203], v[18:21]
	v_mfma_f32_16x16x32_bf16 v[18:21], v[172:175], v[196:199], v[18:21]
	v_mfma_f32_16x16x32_bf16 v[2:5], v[172:175], v[208:211], v[2:5]
	v_mfma_f32_16x16x32_bf16 v[2:5], v[176:179], v[212:215], v[2:5]
	v_mfma_f32_16x16x32_bf16 v[10:13], v[168:171], v[212:215], v[10:13]
	v_mfma_f32_16x16x32_bf16 v[10:13], v[164:167], v[208:211], v[10:13]
	s_setprio 0
	s_barrier
	s_add_i32 s73, 0, 0x18000
	v_add_u32_e32 v147, s73, v142
	s_add_i32 s74, 0, 0x1c000
	ds_read_b128 v[148:151], v147
	ds_read_b128 v[152:155], v147 offset:1024
	ds_read_b128 v[156:159], v147 offset:2048
	ds_read_b128 v[160:163], v147 offset:3072
	v_add_u32_e32 v147, s74, v142
	ds_read_b128 v[164:167], v147
	ds_read_b128 v[168:171], v147 offset:1024
	ds_read_b128 v[172:175], v147 offset:2048
	ds_read_b128 v[176:179], v147 offset:3072
	s_add_u32 s40, s40, 0x80000
	s_addc_u32 s41, s41, 0
	s_mov_b32 m0, s43
	v_lshl_add_u64 v[222:223], s[40:41], 0, v[130:131]
	ds_read_b128 v[180:183], v146 offset:32768
	ds_read_b128 v[184:187], v146 offset:33792
	ds_read_b128 v[188:191], v146 offset:34816
	ds_read_b128 v[192:195], v146 offset:35840
	ds_read_b128 v[196:199], v146 offset:36864
	ds_read_b128 v[200:203], v146 offset:37888
	ds_read_b128 v[208:211], v146 offset:38912
	ds_read_b128 v[212:215], v146 offset:39936
	global_load_lds_dwordx4 v[222:223], off
	v_lshl_add_u64 v[222:223], s[40:41], 0, v[134:135]
	s_mov_b32 m0, s44
	s_nop 0
	global_load_lds_dwordx4 v[222:223], off
	s_waitcnt vmcnt(8)
	s_waitcnt lgkmcnt(0)
	s_barrier
	s_setprio 1
	s_waitcnt lgkmcnt(0)
	v_mfma_f32_16x16x32_bf16 v[126:129], v[148:151], v[180:183], v[126:129]
	v_mfma_f32_16x16x32_bf16 v[126:129], v[152:155], v[184:187], v[126:129]
	v_mfma_f32_16x16x32_bf16 v[122:125], v[160:163], v[184:187], v[122:125]
	v_mfma_f32_16x16x32_bf16 v[122:125], v[156:159], v[180:183], v[122:125]
	v_mfma_f32_16x16x32_bf16 v[102:105], v[156:159], v[188:191], v[102:105]
	v_mfma_f32_16x16x32_bf16 v[102:105], v[160:163], v[192:195], v[102:105]
	v_mfma_f32_16x16x32_bf16 v[110:113], v[152:155], v[192:195], v[110:113]
	v_mfma_f32_16x16x32_bf16 v[110:113], v[148:151], v[188:191], v[110:113]
	v_mfma_f32_16x16x32_bf16 v[94:97], v[148:151], v[196:199], v[94:97]
	v_mfma_f32_16x16x32_bf16 v[94:97], v[152:155], v[200:203], v[94:97]
	v_mfma_f32_16x16x32_bf16 v[86:89], v[160:163], v[200:203], v[86:89]
	v_mfma_f32_16x16x32_bf16 v[86:89], v[156:159], v[196:199], v[86:89]
	v_mfma_f32_16x16x32_bf16 v[70:73], v[156:159], v[208:211], v[70:73]
	v_mfma_f32_16x16x32_bf16 v[70:73], v[160:163], v[212:215], v[70:73]
	v_mfma_f32_16x16x32_bf16 v[78:81], v[152:155], v[212:215], v[78:81]
	v_mfma_f32_16x16x32_bf16 v[78:81], v[148:151], v[208:211], v[78:81]
	s_setprio 0
	s_setprio 1
	v_mfma_f32_16x16x32_bf16 v[118:121], v[164:167], v[180:183], v[118:121]
	v_mfma_f32_16x16x32_bf16 v[118:121], v[168:171], v[184:187], v[118:121]
	v_mfma_f32_16x16x32_bf16 v[114:117], v[176:179], v[184:187], v[114:117]
	v_mfma_f32_16x16x32_bf16 v[114:117], v[172:175], v[180:183], v[114:117]
	v_mfma_f32_16x16x32_bf16 v[98:101], v[172:175], v[188:191], v[98:101]
	v_mfma_f32_16x16x32_bf16 v[98:101], v[176:179], v[192:195], v[98:101]
	v_mfma_f32_16x16x32_bf16 v[106:109], v[168:171], v[192:195], v[106:109]
	v_mfma_f32_16x16x32_bf16 v[106:109], v[164:167], v[188:191], v[106:109]
	v_mfma_f32_16x16x32_bf16 v[90:93], v[164:167], v[196:199], v[90:93]
	v_mfma_f32_16x16x32_bf16 v[90:93], v[168:171], v[200:203], v[90:93]
	v_mfma_f32_16x16x32_bf16 v[82:85], v[176:179], v[200:203], v[82:85]
	v_mfma_f32_16x16x32_bf16 v[82:85], v[172:175], v[196:199], v[82:85]
	v_mfma_f32_16x16x32_bf16 v[66:69], v[172:175], v[208:211], v[66:69]
	v_mfma_f32_16x16x32_bf16 v[66:69], v[176:179], v[212:215], v[66:69]
	v_mfma_f32_16x16x32_bf16 v[74:77], v[168:171], v[212:215], v[74:77]
	v_mfma_f32_16x16x32_bf16 v[74:77], v[164:167], v[208:211], v[74:77]
	s_setprio 0
	s_barrier
	s_add_i32 s40, s73, s33
	v_lshl_add_u64 v[204:205], v[204:205], 0, s[16:17]
	s_mov_b32 m0, s40
	ds_read_b128 v[180:183], v146 offset:49152
	ds_read_b128 v[184:187], v146 offset:50176
	ds_read_b128 v[188:191], v146 offset:51200
	ds_read_b128 v[192:195], v146 offset:52224
	ds_read_b128 v[196:199], v146 offset:53248
	ds_read_b128 v[200:203], v146 offset:54272
	ds_read_b128 v[208:211], v146 offset:55296
	ds_read_b128 v[212:215], v146 offset:56320
	global_load_lds_dwordx4 v[204:205], off
	s_add_i32 m0, s40, 0x2000
	s_add_u32 s2, s2, 0x80080
	v_lshl_add_u64 v[204:205], v[216:217], 0, s[16:17]
	s_addc_u32 s3, s3, 0
	s_add_i32 s40, s74, s33
	global_load_lds_dwordx4 v[204:205], off
	v_lshl_add_u64 v[204:205], s[2:3], 0, v[132:133]
	s_mov_b32 m0, s40
	s_nop 0
	global_load_lds_dwordx4 v[204:205], off
	v_lshl_add_u64 v[204:205], s[2:3], 0, v[136:137]
	s_add_i32 m0, s40, 0x2000
	s_nop 0
	global_load_lds_dwordx4 v[204:205], off
	v_lshl_add_u64 v[204:205], v[218:219], 0, s[16:17]
	s_mov_b32 m0, s46
	s_nop 0
	global_load_lds_dwordx4 v[204:205], off
	v_lshl_add_u64 v[204:205], v[220:221], 0, s[16:17]
	s_mov_b32 m0, s47
	s_nop 0
	global_load_lds_dwordx4 v[204:205], off
	s_waitcnt vmcnt(8)
	s_waitcnt lgkmcnt(0)
	s_barrier
	s_setprio 1
	s_waitcnt lgkmcnt(0)
	v_mfma_f32_16x16x32_bf16 v[62:65], v[148:151], v[180:183], v[62:65]
	v_mfma_f32_16x16x32_bf16 v[62:65], v[152:155], v[184:187], v[62:65]
	v_mfma_f32_16x16x32_bf16 v[54:57], v[160:163], v[184:187], v[54:57]
	v_mfma_f32_16x16x32_bf16 v[54:57], v[156:159], v[180:183], v[54:57]
	v_mfma_f32_16x16x32_bf16 v[38:41], v[156:159], v[188:191], v[38:41]
	v_mfma_f32_16x16x32_bf16 v[38:41], v[160:163], v[192:195], v[38:41]
	v_mfma_f32_16x16x32_bf16 v[46:49], v[152:155], v[192:195], v[46:49]
	v_mfma_f32_16x16x32_bf16 v[46:49], v[148:151], v[188:191], v[46:49]
	v_mfma_f32_16x16x32_bf16 v[30:33], v[148:151], v[196:199], v[30:33]
	v_mfma_f32_16x16x32_bf16 v[30:33], v[152:155], v[200:203], v[30:33]
	v_mfma_f32_16x16x32_bf16 v[22:25], v[160:163], v[200:203], v[22:25]
	v_mfma_f32_16x16x32_bf16 v[22:25], v[156:159], v[196:199], v[22:25]
	v_mfma_f32_16x16x32_bf16 v[6:9], v[156:159], v[208:211], v[6:9]
	v_mfma_f32_16x16x32_bf16 v[6:9], v[160:163], v[212:215], v[6:9]
	v_mfma_f32_16x16x32_bf16 v[14:17], v[152:155], v[212:215], v[14:17]
	v_mfma_f32_16x16x32_bf16 v[14:17], v[148:151], v[208:211], v[14:17]
	s_setprio 0
	s_setprio 1
	v_mfma_f32_16x16x32_bf16 v[58:61], v[164:167], v[180:183], v[58:61]
	v_mfma_f32_16x16x32_bf16 v[58:61], v[168:171], v[184:187], v[58:61]
	v_mfma_f32_16x16x32_bf16 v[50:53], v[176:179], v[184:187], v[50:53]
	v_mfma_f32_16x16x32_bf16 v[50:53], v[172:175], v[180:183], v[50:53]
	v_mfma_f32_16x16x32_bf16 v[34:37], v[172:175], v[188:191], v[34:37]
	v_mfma_f32_16x16x32_bf16 v[34:37], v[176:179], v[192:195], v[34:37]
	v_mfma_f32_16x16x32_bf16 v[42:45], v[168:171], v[192:195], v[42:45]
	v_mfma_f32_16x16x32_bf16 v[42:45], v[164:167], v[188:191], v[42:45]
	v_mfma_f32_16x16x32_bf16 v[26:29], v[164:167], v[196:199], v[26:29]
	v_mfma_f32_16x16x32_bf16 v[26:29], v[168:171], v[200:203], v[26:29]
	v_mfma_f32_16x16x32_bf16 v[18:21], v[176:179], v[200:203], v[18:21]
	v_mfma_f32_16x16x32_bf16 v[18:21], v[172:175], v[196:199], v[18:21]
	v_mfma_f32_16x16x32_bf16 v[2:5], v[172:175], v[208:211], v[2:5]
	v_mfma_f32_16x16x32_bf16 v[2:5], v[176:179], v[212:215], v[2:5]
	v_mfma_f32_16x16x32_bf16 v[10:13], v[168:171], v[212:215], v[10:13]
	v_mfma_f32_16x16x32_bf16 v[10:13], v[164:167], v[208:211], v[10:13]
	s_setprio 0
	s_barrier
	s_add_u32 s38, s38, 0x100
	s_addc_u32 s39, s39, 0
	s_add_u32 s68, s68, 0x100
	s_addc_u32 s69, s69, 0
	s_cmp_ge_i32 s72, s37
	s_mov_b32 s2, s72
	s_cbranch_scc0 .LBB0_526

.LBB0_632:
	s_lshl_b32 s11, s26, 20
	s_and_b32 s11, s11, 0xff00000
	v_readlane_b32 s46, v248, 20
	v_readlane_b32 s47, v248, 21
	s_add_u32 s11, s46, s11
	v_cmp_gt_i64_e64 s[0:1], s[26:27], -1
	s_addc_u32 s16, s47, 0
	s_lshr_b32 s27, s26, 13
	s_and_b32 s27, s27, 0x7ff80
	s_add_u32 s76, s11, s27
	s_addc_u32 s77, s16, 0
	s_lshl_b32 s11, s26, 12
	s_and_b32 s11, s11, 0xff00000
	s_add_u32 s11, s60, s11
	s_addc_u32 s16, s61, 0
	s_add_u32 s78, s11, s27
	s_addc_u32 s79, s16, 0
	s_cmp_lt_i32 s17, 1
	s_cbranch_scc1 .LBB0_640
	s_and_b64 s[26:27], s[0:1], exec
	s_cselect_b32 s11, s77, s19
	s_cselect_b32 s16, s76, s18
	s_cselect_b32 s46, s79, s3
	s_cselect_b32 s47, s78, s2
	s_add_i32 s50, s17, -2
	s_add_u32 s18, s18, 0x80080
	s_addc_u32 s19, s19, 0
	s_add_u32 s51, s2, 0x100
	s_addc_u32 s52, s3, 0
	s_mov_b32 s2, 0
	ds_read_b128 v[130:133], v197
	ds_read_b128 v[134:137], v197 offset:1024
	ds_read_b128 v[138:141], v197 offset:2048
	ds_read_b128 v[142:145], v197 offset:3072
	ds_read_b128 v[146:149], v198
	ds_read_b128 v[150:153], v198 offset:1024
	ds_read_b128 v[154:157], v198 offset:2048
	ds_read_b128 v[170:173], v198 offset:3072
	s_add_i32 s53, s2, 2
	s_add_u32 s3, s18, 0xfff80080
	s_addc_u32 s26, s19, -1
	s_cmp_eq_u32 s50, s2
	s_cselect_b32 s2, s47, s51
	s_cselect_b32 s27, s11, s26
	s_cselect_b32 s26, s16, s3
	s_cselect_b32 s3, s46, s52
	v_lshl_add_u64 v[204:205], s[18:19], 0, v[166:167]
	s_add_i32 m0, s13, 0xc000
	ds_read_b128 v[174:177], v199
	ds_read_b128 v[178:181], v199 offset:1024
	ds_read_b128 v[182:185], v199 offset:2048
	ds_read_b128 v[186:189], v199 offset:3072
	ds_read_b128 v[190:193], v199 offset:4096
	ds_read_b128 v[200:203], v199 offset:5120
	ds_read_b128 v[208:211], v199 offset:6144
	ds_read_b128 v[212:215], v199 offset:7168
	global_load_lds_dwordx4 v[204:205], off
	v_lshl_add_u64 v[204:205], s[18:19], 0, v[168:169]
	s_add_i32 m0, s13, 0xe000
	s_nop 0
	global_load_lds_dwordx4 v[204:205], off
	s_waitcnt vmcnt(8)
	s_waitcnt lgkmcnt(0)
	s_barrier
	s_setprio 1
	s_waitcnt lgkmcnt(0)
	v_mfma_f32_16x16x32_bf16 v[122:125], v[130:133], v[174:177], 0
	v_mfma_f32_16x16x32_bf16 v[122:125], v[134:137], v[178:181], v[122:125]
	v_mfma_f32_16x16x32_bf16 v[114:117], v[142:145], v[178:181], 0
	v_mfma_f32_16x16x32_bf16 v[114:117], v[138:141], v[174:177], v[114:117]
	v_mfma_f32_16x16x32_bf16 v[98:101], v[138:141], v[182:185], 0
	v_mfma_f32_16x16x32_bf16 v[98:101], v[142:145], v[186:189], v[98:101]
	v_mfma_f32_16x16x32_bf16 v[106:109], v[134:137], v[186:189], 0
	v_mfma_f32_16x16x32_bf16 v[106:109], v[130:133], v[182:185], v[106:109]
	v_mfma_f32_16x16x32_bf16 v[90:93], v[130:133], v[190:193], 0
	v_mfma_f32_16x16x32_bf16 v[90:93], v[134:137], v[200:203], v[90:93]
	v_mfma_f32_16x16x32_bf16 v[82:85], v[142:145], v[200:203], 0
	v_mfma_f32_16x16x32_bf16 v[82:85], v[138:141], v[190:193], v[82:85]
	v_mfma_f32_16x16x32_bf16 v[66:69], v[138:141], v[208:211], 0
	v_mfma_f32_16x16x32_bf16 v[66:69], v[142:145], v[212:215], v[66:69]
	v_mfma_f32_16x16x32_bf16 v[74:77], v[134:137], v[212:215], 0
	v_mfma_f32_16x16x32_bf16 v[74:77], v[130:133], v[208:211], v[74:77]
	s_setprio 0
	s_setprio 1
	v_mfma_f32_16x16x32_bf16 v[126:129], v[146:149], v[174:177], 0
	v_mfma_f32_16x16x32_bf16 v[126:129], v[150:153], v[178:181], v[126:129]
	v_mfma_f32_16x16x32_bf16 v[118:121], v[170:173], v[178:181], 0
	v_mfma_f32_16x16x32_bf16 v[118:121], v[154:157], v[174:177], v[118:121]
	v_mfma_f32_16x16x32_bf16 v[102:105], v[154:157], v[182:185], 0
	v_mfma_f32_16x16x32_bf16 v[102:105], v[170:173], v[186:189], v[102:105]
	v_mfma_f32_16x16x32_bf16 v[110:113], v[150:153], v[186:189], 0
	v_mfma_f32_16x16x32_bf16 v[110:113], v[146:149], v[182:185], v[110:113]
	v_mfma_f32_16x16x32_bf16 v[94:97], v[146:149], v[190:193], 0
	v_mfma_f32_16x16x32_bf16 v[94:97], v[150:153], v[200:203], v[94:97]
	v_mfma_f32_16x16x32_bf16 v[86:89], v[170:173], v[200:203], 0
	v_mfma_f32_16x16x32_bf16 v[86:89], v[154:157], v[190:193], v[86:89]
	v_mfma_f32_16x16x32_bf16 v[70:73], v[154:157], v[208:211], 0
	v_mfma_f32_16x16x32_bf16 v[70:73], v[170:173], v[212:215], v[70:73]
	v_mfma_f32_16x16x32_bf16 v[78:81], v[150:153], v[212:215], 0
	v_mfma_f32_16x16x32_bf16 v[78:81], v[146:149], v[208:211], v[78:81]
	s_setprio 0
	s_barrier
	s_add_i32 s64, s44, s35
	v_lshl_add_u64 v[204:205], s[2:3], 0, v[160:161]
	s_mov_b32 m0, s64
	ds_read_b128 v[174:177], v199 offset:16384
	ds_read_b128 v[178:181], v199 offset:17408
	ds_read_b128 v[182:185], v199 offset:18432
	ds_read_b128 v[186:189], v199 offset:19456
	ds_read_b128 v[190:193], v199 offset:20480
	ds_read_b128 v[200:203], v199 offset:21504
	ds_read_b128 v[208:211], v199 offset:22528
	ds_read_b128 v[212:215], v199 offset:23552
	global_load_lds_dwordx4 v[204:205], off
	s_add_i32 m0, s64, 0x2000
	s_add_u32 s80, s2, 0x80000
	v_lshl_add_u64 v[216:217], s[2:3], 0, v[164:165]
	s_addc_u32 s81, s3, 0
	s_add_i32 s64, s45, s35
	global_load_lds_dwordx4 v[216:217], off
	v_lshl_add_u64 v[218:219], s[80:81], 0, v[160:161]
	s_mov_b32 m0, s64
	v_lshl_add_u64 v[220:221], s[26:27], 0, v[162:163]
	global_load_lds_dwordx4 v[218:219], off
	v_lshl_add_u64 v[218:219], s[80:81], 0, v[164:165]
	s_add_i32 m0, s64, 0x2000
	s_nop 0
	global_load_lds_dwordx4 v[218:219], off
	v_lshl_add_u64 v[218:219], s[26:27], 0, v[158:159]
	s_mov_b32 m0, s13
	s_nop 0
	global_load_lds_dwordx4 v[218:219], off
	s_mov_b32 m0, s36
	s_nop 0
	global_load_lds_dwordx4 v[220:221], off
	s_waitcnt vmcnt(8)
	s_waitcnt lgkmcnt(0)
	s_barrier
	s_setprio 1
	s_waitcnt lgkmcnt(0)
	v_mfma_f32_16x16x32_bf16 v[58:61], v[130:133], v[174:177], 0
	v_mfma_f32_16x16x32_bf16 v[58:61], v[134:137], v[178:181], v[58:61]
	v_mfma_f32_16x16x32_bf16 v[50:53], v[142:145], v[178:181], 0
	v_mfma_f32_16x16x32_bf16 v[50:53], v[138:141], v[174:177], v[50:53]
	v_mfma_f32_16x16x32_bf16 v[34:37], v[138:141], v[182:185], 0
	v_mfma_f32_16x16x32_bf16 v[34:37], v[142:145], v[186:189], v[34:37]
	v_mfma_f32_16x16x32_bf16 v[42:45], v[134:137], v[186:189], 0
	v_mfma_f32_16x16x32_bf16 v[42:45], v[130:133], v[182:185], v[42:45]
	v_mfma_f32_16x16x32_bf16 v[26:29], v[130:133], v[190:193], 0
	v_mfma_f32_16x16x32_bf16 v[26:29], v[134:137], v[200:203], v[26:29]
	v_mfma_f32_16x16x32_bf16 v[18:21], v[142:145], v[200:203], 0
	v_mfma_f32_16x16x32_bf16 v[18:21], v[138:141], v[190:193], v[18:21]
	v_mfma_f32_16x16x32_bf16 v[2:5], v[138:141], v[208:211], 0
	v_mfma_f32_16x16x32_bf16 v[2:5], v[142:145], v[212:215], v[2:5]
	v_mfma_f32_16x16x32_bf16 v[10:13], v[134:137], v[212:215], 0
	v_mfma_f32_16x16x32_bf16 v[10:13], v[130:133], v[208:211], v[10:13]
	s_setprio 0
	s_setprio 1
	v_mfma_f32_16x16x32_bf16 v[62:65], v[146:149], v[174:177], 0
	v_mfma_f32_16x16x32_bf16 v[62:65], v[150:153], v[178:181], v[62:65]
	v_mfma_f32_16x16x32_bf16 v[54:57], v[170:173], v[178:181], 0
	v_mfma_f32_16x16x32_bf16 v[54:57], v[154:157], v[174:177], v[54:57]
	v_mfma_f32_16x16x32_bf16 v[38:41], v[154:157], v[182:185], 0
	v_mfma_f32_16x16x32_bf16 v[38:41], v[170:173], v[186:189], v[38:41]
	v_mfma_f32_16x16x32_bf16 v[46:49], v[150:153], v[186:189], 0
	v_mfma_f32_16x16x32_bf16 v[46:49], v[146:149], v[182:185], v[46:49]
	v_mfma_f32_16x16x32_bf16 v[30:33], v[146:149], v[190:193], 0
	v_mfma_f32_16x16x32_bf16 v[30:33], v[150:153], v[200:203], v[30:33]
	v_mfma_f32_16x16x32_bf16 v[22:25], v[170:173], v[200:203], 0
	v_mfma_f32_16x16x32_bf16 v[22:25], v[154:157], v[190:193], v[22:25]
	v_mfma_f32_16x16x32_bf16 v[6:9], v[154:157], v[208:211], 0
	v_mfma_f32_16x16x32_bf16 v[6:9], v[170:173], v[212:215], v[6:9]
	v_mfma_f32_16x16x32_bf16 v[14:17], v[150:153], v[212:215], 0
	v_mfma_f32_16x16x32_bf16 v[14:17], v[146:149], v[208:211], v[14:17]
	s_setprio 0
	s_barrier
	s_add_i32 s64, 0, 0x18000
	s_add_i32 s75, 0, 0x1c000
	v_add_u32_e32 v142, s64, v194
	v_add_u32_e32 v170, s75, v194
	ds_read_b128 v[130:133], v142
	ds_read_b128 v[134:137], v142 offset:1024
	ds_read_b128 v[138:141], v142 offset:2048
	ds_read_b128 v[142:145], v142 offset:3072
	ds_read_b128 v[146:149], v170
	ds_read_b128 v[150:153], v170 offset:1024
	ds_read_b128 v[154:157], v170 offset:2048
	ds_read_b128 v[170:173], v170 offset:3072
	s_add_u32 s26, s26, 0x80000
	s_addc_u32 s27, s27, 0
	s_mov_b32 m0, s37
	v_lshl_add_u64 v[222:223], s[26:27], 0, v[158:159]
	ds_read_b128 v[174:177], v199 offset:32768
	ds_read_b128 v[178:181], v199 offset:33792
	ds_read_b128 v[182:185], v199 offset:34816
	ds_read_b128 v[186:189], v199 offset:35840
	ds_read_b128 v[190:193], v199 offset:36864
	ds_read_b128 v[200:203], v199 offset:37888
	ds_read_b128 v[208:211], v199 offset:38912
	ds_read_b128 v[212:215], v199 offset:39936
	global_load_lds_dwordx4 v[222:223], off
	v_lshl_add_u64 v[222:223], s[26:27], 0, v[162:163]
	s_mov_b32 m0, s38
	s_nop 0
	global_load_lds_dwordx4 v[222:223], off
	s_waitcnt vmcnt(8)
	s_waitcnt lgkmcnt(0)
	s_barrier
	s_setprio 1
	s_waitcnt lgkmcnt(0)
	v_mfma_f32_16x16x32_bf16 v[122:125], v[130:133], v[174:177], v[122:125]
	v_mfma_f32_16x16x32_bf16 v[122:125], v[134:137], v[178:181], v[122:125]
	v_mfma_f32_16x16x32_bf16 v[114:117], v[142:145], v[178:181], v[114:117]
	v_mfma_f32_16x16x32_bf16 v[114:117], v[138:141], v[174:177], v[114:117]
	v_mfma_f32_16x16x32_bf16 v[98:101], v[138:141], v[182:185], v[98:101]
	v_mfma_f32_16x16x32_bf16 v[98:101], v[142:145], v[186:189], v[98:101]
	v_mfma_f32_16x16x32_bf16 v[106:109], v[134:137], v[186:189], v[106:109]
	v_mfma_f32_16x16x32_bf16 v[106:109], v[130:133], v[182:185], v[106:109]
	v_mfma_f32_16x16x32_bf16 v[90:93], v[130:133], v[190:193], v[90:93]
	v_mfma_f32_16x16x32_bf16 v[90:93], v[134:137], v[200:203], v[90:93]
	v_mfma_f32_16x16x32_bf16 v[82:85], v[142:145], v[200:203], v[82:85]
	v_mfma_f32_16x16x32_bf16 v[82:85], v[138:141], v[190:193], v[82:85]
	v_mfma_f32_16x16x32_bf16 v[66:69], v[138:141], v[208:211], v[66:69]
	v_mfma_f32_16x16x32_bf16 v[66:69], v[142:145], v[212:215], v[66:69]
	v_mfma_f32_16x16x32_bf16 v[74:77], v[134:137], v[212:215], v[74:77]
	v_mfma_f32_16x16x32_bf16 v[74:77], v[130:133], v[208:211], v[74:77]
	s_setprio 0
	s_setprio 1
	v_mfma_f32_16x16x32_bf16 v[126:129], v[146:149], v[174:177], v[126:129]
	v_mfma_f32_16x16x32_bf16 v[126:129], v[150:153], v[178:181], v[126:129]
	v_mfma_f32_16x16x32_bf16 v[118:121], v[170:173], v[178:181], v[118:121]
	v_mfma_f32_16x16x32_bf16 v[118:121], v[154:157], v[174:177], v[118:121]
	v_mfma_f32_16x16x32_bf16 v[102:105], v[154:157], v[182:185], v[102:105]
	v_mfma_f32_16x16x32_bf16 v[102:105], v[170:173], v[186:189], v[102:105]
	v_mfma_f32_16x16x32_bf16 v[110:113], v[150:153], v[186:189], v[110:113]
	v_mfma_f32_16x16x32_bf16 v[110:113], v[146:149], v[182:185], v[110:113]
	v_mfma_f32_16x16x32_bf16 v[94:97], v[146:149], v[190:193], v[94:97]
	v_mfma_f32_16x16x32_bf16 v[94:97], v[150:153], v[200:203], v[94:97]
	v_mfma_f32_16x16x32_bf16 v[86:89], v[170:173], v[200:203], v[86:89]
	v_mfma_f32_16x16x32_bf16 v[86:89], v[154:157], v[190:193], v[86:89]
	v_mfma_f32_16x16x32_bf16 v[70:73], v[154:157], v[208:211], v[70:73]
	v_mfma_f32_16x16x32_bf16 v[70:73], v[170:173], v[212:215], v[70:73]
	v_mfma_f32_16x16x32_bf16 v[78:81], v[150:153], v[212:215], v[78:81]
	v_mfma_f32_16x16x32_bf16 v[78:81], v[146:149], v[208:211], v[78:81]
	s_setprio 0
	s_barrier
	s_add_i32 s26, s64, s35
	v_lshl_add_u64 v[204:205], v[204:205], 0, s[68:69]
	s_mov_b32 m0, s26
	ds_read_b128 v[174:177], v199 offset:49152
	ds_read_b128 v[178:181], v199 offset:50176
	ds_read_b128 v[182:185], v199 offset:51200
	ds_read_b128 v[186:189], v199 offset:52224
	ds_read_b128 v[190:193], v199 offset:53248
	ds_read_b128 v[200:203], v199 offset:54272
	ds_read_b128 v[208:211], v199 offset:55296
	ds_read_b128 v[212:215], v199 offset:56320
	global_load_lds_dwordx4 v[204:205], off
	s_add_i32 m0, s26, 0x2000
	s_add_u32 s2, s2, 0x80080
	v_lshl_add_u64 v[204:205], v[216:217], 0, s[68:69]
	s_addc_u32 s3, s3, 0
	s_add_i32 s26, s75, s35
	global_load_lds_dwordx4 v[204:205], off
	v_lshl_add_u64 v[204:205], s[2:3], 0, v[160:161]
	s_mov_b32 m0, s26
	s_nop 0
	global_load_lds_dwordx4 v[204:205], off
	v_lshl_add_u64 v[204:205], s[2:3], 0, v[164:165]
	s_add_i32 m0, s26, 0x2000
	s_nop 0
	global_load_lds_dwordx4 v[204:205], off
	v_lshl_add_u64 v[204:205], v[218:219], 0, s[68:69]
	s_mov_b32 m0, s40
	s_nop 0
	global_load_lds_dwordx4 v[204:205], off
	v_lshl_add_u64 v[204:205], v[220:221], 0, s[68:69]
	s_mov_b32 m0, s41
	s_nop 0
	global_load_lds_dwordx4 v[204:205], off
	s_waitcnt vmcnt(8)
	s_waitcnt lgkmcnt(0)
	s_barrier
	s_setprio 1
	s_waitcnt lgkmcnt(0)
	v_mfma_f32_16x16x32_bf16 v[58:61], v[130:133], v[174:177], v[58:61]
	v_mfma_f32_16x16x32_bf16 v[58:61], v[134:137], v[178:181], v[58:61]
	v_mfma_f32_16x16x32_bf16 v[50:53], v[142:145], v[178:181], v[50:53]
	v_mfma_f32_16x16x32_bf16 v[50:53], v[138:141], v[174:177], v[50:53]
	v_mfma_f32_16x16x32_bf16 v[34:37], v[138:141], v[182:185], v[34:37]
	v_mfma_f32_16x16x32_bf16 v[34:37], v[142:145], v[186:189], v[34:37]
	v_mfma_f32_16x16x32_bf16 v[42:45], v[134:137], v[186:189], v[42:45]
	v_mfma_f32_16x16x32_bf16 v[42:45], v[130:133], v[182:185], v[42:45]
	v_mfma_f32_16x16x32_bf16 v[26:29], v[130:133], v[190:193], v[26:29]
	v_mfma_f32_16x16x32_bf16 v[26:29], v[134:137], v[200:203], v[26:29]
	v_mfma_f32_16x16x32_bf16 v[18:21], v[142:145], v[200:203], v[18:21]
	v_mfma_f32_16x16x32_bf16 v[18:21], v[138:141], v[190:193], v[18:21]
	v_mfma_f32_16x16x32_bf16 v[2:5], v[138:141], v[208:211], v[2:5]
	v_mfma_f32_16x16x32_bf16 v[2:5], v[142:145], v[212:215], v[2:5]
	v_mfma_f32_16x16x32_bf16 v[10:13], v[134:137], v[212:215], v[10:13]
	v_mfma_f32_16x16x32_bf16 v[10:13], v[130:133], v[208:211], v[10:13]
	s_setprio 0
	s_setprio 1
	v_mfma_f32_16x16x32_bf16 v[62:65], v[146:149], v[174:177], v[62:65]
	v_mfma_f32_16x16x32_bf16 v[62:65], v[150:153], v[178:181], v[62:65]
	v_mfma_f32_16x16x32_bf16 v[54:57], v[170:173], v[178:181], v[54:57]
	v_mfma_f32_16x16x32_bf16 v[54:57], v[154:157], v[174:177], v[54:57]
	v_mfma_f32_16x16x32_bf16 v[38:41], v[154:157], v[182:185], v[38:41]
	v_mfma_f32_16x16x32_bf16 v[38:41], v[170:173], v[186:189], v[38:41]
	v_mfma_f32_16x16x32_bf16 v[46:49], v[150:153], v[186:189], v[46:49]
	v_mfma_f32_16x16x32_bf16 v[46:49], v[146:149], v[182:185], v[46:49]
	v_mfma_f32_16x16x32_bf16 v[30:33], v[146:149], v[190:193], v[30:33]
	v_mfma_f32_16x16x32_bf16 v[30:33], v[150:153], v[200:203], v[30:33]
	v_mfma_f32_16x16x32_bf16 v[22:25], v[170:173], v[200:203], v[22:25]
	v_mfma_f32_16x16x32_bf16 v[22:25], v[154:157], v[190:193], v[22:25]
	v_mfma_f32_16x16x32_bf16 v[6:9], v[154:157], v[208:211], v[6:9]
	v_mfma_f32_16x16x32_bf16 v[6:9], v[170:173], v[212:215], v[6:9]
	v_mfma_f32_16x16x32_bf16 v[14:17], v[150:153], v[212:215], v[14:17]
	v_mfma_f32_16x16x32_bf16 v[14:17], v[146:149], v[208:211], v[14:17]
	s_setprio 0
	s_barrier
	s_add_u32 s18, s18, 0x100
	s_addc_u32 s19, s19, 0
	s_add_u32 s51, s51, 0x100
	s_addc_u32 s52, s52, 0
	s_cmp_ge_i32 s53, s17
	s_mov_b32 s2, s53
	s_cbranch_scc1 .Lkpeel_exit_3
.LBB0_634:
	ds_read_b128 v[130:133], v197
	ds_read_b128 v[134:137], v197 offset:1024
	ds_read_b128 v[138:141], v197 offset:2048
	ds_read_b128 v[142:145], v197 offset:3072
	ds_read_b128 v[146:149], v198
	ds_read_b128 v[150:153], v198 offset:1024
	ds_read_b128 v[154:157], v198 offset:2048
	ds_read_b128 v[170:173], v198 offset:3072
	s_add_i32 s53, s2, 2
	s_add_u32 s3, s18, 0xfff80080
	s_addc_u32 s26, s19, -1
	s_cmp_eq_u32 s50, s2
	s_cselect_b32 s2, s47, s51
	s_cselect_b32 s27, s11, s26
	s_cselect_b32 s26, s16, s3
	s_cselect_b32 s3, s46, s52
	v_lshl_add_u64 v[204:205], s[18:19], 0, v[166:167]
	s_add_i32 m0, s13, 0xc000
	ds_read_b128 v[174:177], v199
	ds_read_b128 v[178:181], v199 offset:1024
	ds_read_b128 v[182:185], v199 offset:2048
	ds_read_b128 v[186:189], v199 offset:3072
	ds_read_b128 v[190:193], v199 offset:4096
	ds_read_b128 v[200:203], v199 offset:5120
	ds_read_b128 v[208:211], v199 offset:6144
	ds_read_b128 v[212:215], v199 offset:7168
	global_load_lds_dwordx4 v[204:205], off
	v_lshl_add_u64 v[204:205], s[18:19], 0, v[168:169]
	s_add_i32 m0, s13, 0xe000
	s_nop 0
	global_load_lds_dwordx4 v[204:205], off
	s_waitcnt vmcnt(8)
	s_waitcnt lgkmcnt(0)
	s_barrier
	s_setprio 1
	s_waitcnt lgkmcnt(0)
	v_mfma_f32_16x16x32_bf16 v[122:125], v[130:133], v[174:177], v[122:125]
	v_mfma_f32_16x16x32_bf16 v[122:125], v[134:137], v[178:181], v[122:125]
	v_mfma_f32_16x16x32_bf16 v[114:117], v[142:145], v[178:181], v[114:117]
	v_mfma_f32_16x16x32_bf16 v[114:117], v[138:141], v[174:177], v[114:117]
	v_mfma_f32_16x16x32_bf16 v[98:101], v[138:141], v[182:185], v[98:101]
	v_mfma_f32_16x16x32_bf16 v[98:101], v[142:145], v[186:189], v[98:101]
	v_mfma_f32_16x16x32_bf16 v[106:109], v[134:137], v[186:189], v[106:109]
	v_mfma_f32_16x16x32_bf16 v[106:109], v[130:133], v[182:185], v[106:109]
	v_mfma_f32_16x16x32_bf16 v[90:93], v[130:133], v[190:193], v[90:93]
	v_mfma_f32_16x16x32_bf16 v[90:93], v[134:137], v[200:203], v[90:93]
	v_mfma_f32_16x16x32_bf16 v[82:85], v[142:145], v[200:203], v[82:85]
	v_mfma_f32_16x16x32_bf16 v[82:85], v[138:141], v[190:193], v[82:85]
	v_mfma_f32_16x16x32_bf16 v[66:69], v[138:141], v[208:211], v[66:69]
	v_mfma_f32_16x16x32_bf16 v[66:69], v[142:145], v[212:215], v[66:69]
	v_mfma_f32_16x16x32_bf16 v[74:77], v[134:137], v[212:215], v[74:77]
	v_mfma_f32_16x16x32_bf16 v[74:77], v[130:133], v[208:211], v[74:77]
	s_setprio 0
	s_setprio 1
	v_mfma_f32_16x16x32_bf16 v[126:129], v[146:149], v[174:177], v[126:129]
	v_mfma_f32_16x16x32_bf16 v[126:129], v[150:153], v[178:181], v[126:129]
	v_mfma_f32_16x16x32_bf16 v[118:121], v[170:173], v[178:181], v[118:121]
	v_mfma_f32_16x16x32_bf16 v[118:121], v[154:157], v[174:177], v[118:121]
	v_mfma_f32_16x16x32_bf16 v[102:105], v[154:157], v[182:185], v[102:105]
	v_mfma_f32_16x16x32_bf16 v[102:105], v[170:173], v[186:189], v[102:105]
	v_mfma_f32_16x16x32_bf16 v[110:113], v[150:153], v[186:189], v[110:113]
	v_mfma_f32_16x16x32_bf16 v[110:113], v[146:149], v[182:185], v[110:113]
	v_mfma_f32_16x16x32_bf16 v[94:97], v[146:149], v[190:193], v[94:97]
	v_mfma_f32_16x16x32_bf16 v[94:97], v[150:153], v[200:203], v[94:97]
	v_mfma_f32_16x16x32_bf16 v[86:89], v[170:173], v[200:203], v[86:89]
	v_mfma_f32_16x16x32_bf16 v[86:89], v[154:157], v[190:193], v[86:89]
	v_mfma_f32_16x16x32_bf16 v[70:73], v[154:157], v[208:211], v[70:73]
	v_mfma_f32_16x16x32_bf16 v[70:73], v[170:173], v[212:215], v[70:73]
	v_mfma_f32_16x16x32_bf16 v[78:81], v[150:153], v[212:215], v[78:81]
	v_mfma_f32_16x16x32_bf16 v[78:81], v[146:149], v[208:211], v[78:81]
	s_setprio 0
	s_barrier
	s_add_i32 s64, s44, s35
	v_lshl_add_u64 v[204:205], s[2:3], 0, v[160:161]
	s_mov_b32 m0, s64
	ds_read_b128 v[174:177], v199 offset:16384
	ds_read_b128 v[178:181], v199 offset:17408
	ds_read_b128 v[182:185], v199 offset:18432
	ds_read_b128 v[186:189], v199 offset:19456
	ds_read_b128 v[190:193], v199 offset:20480
	ds_read_b128 v[200:203], v199 offset:21504
	ds_read_b128 v[208:211], v199 offset:22528
	ds_read_b128 v[212:215], v199 offset:23552
	global_load_lds_dwordx4 v[204:205], off
	s_add_i32 m0, s64, 0x2000
	s_add_u32 s80, s2, 0x80000
	v_lshl_add_u64 v[216:217], s[2:3], 0, v[164:165]
	s_addc_u32 s81, s3, 0
	s_add_i32 s64, s45, s35
	global_load_lds_dwordx4 v[216:217], off
	v_lshl_add_u64 v[218:219], s[80:81], 0, v[160:161]
	s_mov_b32 m0, s64
	v_lshl_add_u64 v[220:221], s[26:27], 0, v[162:163]
	global_load_lds_dwordx4 v[218:219], off
	v_lshl_add_u64 v[218:219], s[80:81], 0, v[164:165]
	s_add_i32 m0, s64, 0x2000
	s_nop 0
	global_load_lds_dwordx4 v[218:219], off
	v_lshl_add_u64 v[218:219], s[26:27], 0, v[158:159]
	s_mov_b32 m0, s13
	s_nop 0
	global_load_lds_dwordx4 v[218:219], off
	s_mov_b32 m0, s36
	s_nop 0
	global_load_lds_dwordx4 v[220:221], off
	s_waitcnt vmcnt(8)
	s_waitcnt lgkmcnt(0)
	s_barrier
	s_setprio 1
	s_waitcnt lgkmcnt(0)
	v_mfma_f32_16x16x32_bf16 v[58:61], v[130:133], v[174:177], v[58:61]
	v_mfma_f32_16x16x32_bf16 v[58:61], v[134:137], v[178:181], v[58:61]
	v_mfma_f32_16x16x32_bf16 v[50:53], v[142:145], v[178:181], v[50:53]
	v_mfma_f32_16x16x32_bf16 v[50:53], v[138:141], v[174:177], v[50:53]
	v_mfma_f32_16x16x32_bf16 v[34:37], v[138:141], v[182:185], v[34:37]
	v_mfma_f32_16x16x32_bf16 v[34:37], v[142:145], v[186:189], v[34:37]
	v_mfma_f32_16x16x32_bf16 v[42:45], v[134:137], v[186:189], v[42:45]
	v_mfma_f32_16x16x32_bf16 v[42:45], v[130:133], v[182:185], v[42:45]
	v_mfma_f32_16x16x32_bf16 v[26:29], v[130:133], v[190:193], v[26:29]
	v_mfma_f32_16x16x32_bf16 v[26:29], v[134:137], v[200:203], v[26:29]
	v_mfma_f32_16x16x32_bf16 v[18:21], v[142:145], v[200:203], v[18:21]
	v_mfma_f32_16x16x32_bf16 v[18:21], v[138:141], v[190:193], v[18:21]
	v_mfma_f32_16x16x32_bf16 v[2:5], v[138:141], v[208:211], v[2:5]
	v_mfma_f32_16x16x32_bf16 v[2:5], v[142:145], v[212:215], v[2:5]
	v_mfma_f32_16x16x32_bf16 v[10:13], v[134:137], v[212:215], v[10:13]
	v_mfma_f32_16x16x32_bf16 v[10:13], v[130:133], v[208:211], v[10:13]
	s_setprio 0
	s_setprio 1
	v_mfma_f32_16x16x32_bf16 v[62:65], v[146:149], v[174:177], v[62:65]
	v_mfma_f32_16x16x32_bf16 v[62:65], v[150:153], v[178:181], v[62:65]
	v_mfma_f32_16x16x32_bf16 v[54:57], v[170:173], v[178:181], v[54:57]
	v_mfma_f32_16x16x32_bf16 v[54:57], v[154:157], v[174:177], v[54:57]
	v_mfma_f32_16x16x32_bf16 v[38:41], v[154:157], v[182:185], v[38:41]
	v_mfma_f32_16x16x32_bf16 v[38:41], v[170:173], v[186:189], v[38:41]
	v_mfma_f32_16x16x32_bf16 v[46:49], v[150:153], v[186:189], v[46:49]
	v_mfma_f32_16x16x32_bf16 v[46:49], v[146:149], v[182:185], v[46:49]
	v_mfma_f32_16x16x32_bf16 v[30:33], v[146:149], v[190:193], v[30:33]
	v_mfma_f32_16x16x32_bf16 v[30:33], v[150:153], v[200:203], v[30:33]
	v_mfma_f32_16x16x32_bf16 v[22:25], v[170:173], v[200:203], v[22:25]
	v_mfma_f32_16x16x32_bf16 v[22:25], v[154:157], v[190:193], v[22:25]
	v_mfma_f32_16x16x32_bf16 v[6:9], v[154:157], v[208:211], v[6:9]
	v_mfma_f32_16x16x32_bf16 v[6:9], v[170:173], v[212:215], v[6:9]
	v_mfma_f32_16x16x32_bf16 v[14:17], v[150:153], v[212:215], v[14:17]
	v_mfma_f32_16x16x32_bf16 v[14:17], v[146:149], v[208:211], v[14:17]
	s_setprio 0
	s_barrier
	s_add_i32 s64, 0, 0x18000
	s_add_i32 s75, 0, 0x1c000
	v_add_u32_e32 v142, s64, v194
	v_add_u32_e32 v170, s75, v194
	ds_read_b128 v[130:133], v142
	ds_read_b128 v[134:137], v142 offset:1024
	ds_read_b128 v[138:141], v142 offset:2048
	ds_read_b128 v[142:145], v142 offset:3072
	ds_read_b128 v[146:149], v170
	ds_read_b128 v[150:153], v170 offset:1024
	ds_read_b128 v[154:157], v170 offset:2048
	ds_read_b128 v[170:173], v170 offset:3072
	s_add_u32 s26, s26, 0x80000
	s_addc_u32 s27, s27, 0
	s_mov_b32 m0, s37
	v_lshl_add_u64 v[222:223], s[26:27], 0, v[158:159]
	ds_read_b128 v[174:177], v199 offset:32768
	ds_read_b128 v[178:181], v199 offset:33792
	ds_read_b128 v[182:185], v199 offset:34816
	ds_read_b128 v[186:189], v199 offset:35840
	ds_read_b128 v[190:193], v199 offset:36864
	ds_read_b128 v[200:203], v199 offset:37888
	ds_read_b128 v[208:211], v199 offset:38912
	ds_read_b128 v[212:215], v199 offset:39936
	global_load_lds_dwordx4 v[222:223], off
	v_lshl_add_u64 v[222:223], s[26:27], 0, v[162:163]
	s_mov_b32 m0, s38
	s_nop 0
	global_load_lds_dwordx4 v[222:223], off
	s_waitcnt vmcnt(8)
	s_waitcnt lgkmcnt(0)
	s_barrier
	s_setprio 1
	s_waitcnt lgkmcnt(0)
	v_mfma_f32_16x16x32_bf16 v[122:125], v[130:133], v[174:177], v[122:125]
	v_mfma_f32_16x16x32_bf16 v[122:125], v[134:137], v[178:181], v[122:125]
	v_mfma_f32_16x16x32_bf16 v[114:117], v[142:145], v[178:181], v[114:117]
	v_mfma_f32_16x16x32_bf16 v[114:117], v[138:141], v[174:177], v[114:117]
	v_mfma_f32_16x16x32_bf16 v[98:101], v[138:141], v[182:185], v[98:101]
	v_mfma_f32_16x16x32_bf16 v[98:101], v[142:145], v[186:189], v[98:101]
	v_mfma_f32_16x16x32_bf16 v[106:109], v[134:137], v[186:189], v[106:109]
	v_mfma_f32_16x16x32_bf16 v[106:109], v[130:133], v[182:185], v[106:109]
	v_mfma_f32_16x16x32_bf16 v[90:93], v[130:133], v[190:193], v[90:93]
	v_mfma_f32_16x16x32_bf16 v[90:93], v[134:137], v[200:203], v[90:93]
	v_mfma_f32_16x16x32_bf16 v[82:85], v[142:145], v[200:203], v[82:85]
	v_mfma_f32_16x16x32_bf16 v[82:85], v[138:141], v[190:193], v[82:85]
	v_mfma_f32_16x16x32_bf16 v[66:69], v[138:141], v[208:211], v[66:69]
	v_mfma_f32_16x16x32_bf16 v[66:69], v[142:145], v[212:215], v[66:69]
	v_mfma_f32_16x16x32_bf16 v[74:77], v[134:137], v[212:215], v[74:77]
	v_mfma_f32_16x16x32_bf16 v[74:77], v[130:133], v[208:211], v[74:77]
	s_setprio 0
	s_setprio 1
	v_mfma_f32_16x16x32_bf16 v[126:129], v[146:149], v[174:177], v[126:129]
	v_mfma_f32_16x16x32_bf16 v[126:129], v[150:153], v[178:181], v[126:129]
	v_mfma_f32_16x16x32_bf16 v[118:121], v[170:173], v[178:181], v[118:121]
	v_mfma_f32_16x16x32_bf16 v[118:121], v[154:157], v[174:177], v[118:121]
	v_mfma_f32_16x16x32_bf16 v[102:105], v[154:157], v[182:185], v[102:105]
	v_mfma_f32_16x16x32_bf16 v[102:105], v[170:173], v[186:189], v[102:105]
	v_mfma_f32_16x16x32_bf16 v[110:113], v[150:153], v[186:189], v[110:113]
	v_mfma_f32_16x16x32_bf16 v[110:113], v[146:149], v[182:185], v[110:113]
	v_mfma_f32_16x16x32_bf16 v[94:97], v[146:149], v[190:193], v[94:97]
	v_mfma_f32_16x16x32_bf16 v[94:97], v[150:153], v[200:203], v[94:97]
	v_mfma_f32_16x16x32_bf16 v[86:89], v[170:173], v[200:203], v[86:89]
	v_mfma_f32_16x16x32_bf16 v[86:89], v[154:157], v[190:193], v[86:89]
	v_mfma_f32_16x16x32_bf16 v[70:73], v[154:157], v[208:211], v[70:73]
	v_mfma_f32_16x16x32_bf16 v[70:73], v[170:173], v[212:215], v[70:73]
	v_mfma_f32_16x16x32_bf16 v[78:81], v[150:153], v[212:215], v[78:81]
	v_mfma_f32_16x16x32_bf16 v[78:81], v[146:149], v[208:211], v[78:81]
	s_setprio 0
	s_barrier
	s_add_i32 s26, s64, s35
	v_lshl_add_u64 v[204:205], v[204:205], 0, s[68:69]
	s_mov_b32 m0, s26
	ds_read_b128 v[174:177], v199 offset:49152
	ds_read_b128 v[178:181], v199 offset:50176
	ds_read_b128 v[182:185], v199 offset:51200
	ds_read_b128 v[186:189], v199 offset:52224
	ds_read_b128 v[190:193], v199 offset:53248
	ds_read_b128 v[200:203], v199 offset:54272
	ds_read_b128 v[208:211], v199 offset:55296
	ds_read_b128 v[212:215], v199 offset:56320
	global_load_lds_dwordx4 v[204:205], off
	s_add_i32 m0, s26, 0x2000
	s_add_u32 s2, s2, 0x80080
	v_lshl_add_u64 v[204:205], v[216:217], 0, s[68:69]
	s_addc_u32 s3, s3, 0
	s_add_i32 s26, s75, s35
	global_load_lds_dwordx4 v[204:205], off
	v_lshl_add_u64 v[204:205], s[2:3], 0, v[160:161]
	s_mov_b32 m0, s26
	s_nop 0
	global_load_lds_dwordx4 v[204:205], off
	v_lshl_add_u64 v[204:205], s[2:3], 0, v[164:165]
	s_add_i32 m0, s26, 0x2000
	s_nop 0
	global_load_lds_dwordx4 v[204:205], off
	v_lshl_add_u64 v[204:205], v[218:219], 0, s[68:69]
	s_mov_b32 m0, s40
	s_nop 0
	global_load_lds_dwordx4 v[204:205], off
	v_lshl_add_u64 v[204:205], v[220:221], 0, s[68:69]
	s_mov_b32 m0, s41
	s_nop 0
	global_load_lds_dwordx4 v[204:205], off
	s_waitcnt vmcnt(8)
	s_waitcnt lgkmcnt(0)
	s_barrier
	s_setprio 1
	s_waitcnt lgkmcnt(0)
	v_mfma_f32_16x16x32_bf16 v[58:61], v[130:133], v[174:177], v[58:61]
	v_mfma_f32_16x16x32_bf16 v[58:61], v[134:137], v[178:181], v[58:61]
	v_mfma_f32_16x16x32_bf16 v[50:53], v[142:145], v[178:181], v[50:53]
	v_mfma_f32_16x16x32_bf16 v[50:53], v[138:141], v[174:177], v[50:53]
	v_mfma_f32_16x16x32_bf16 v[34:37], v[138:141], v[182:185], v[34:37]
	v_mfma_f32_16x16x32_bf16 v[34:37], v[142:145], v[186:189], v[34:37]
	v_mfma_f32_16x16x32_bf16 v[42:45], v[134:137], v[186:189], v[42:45]
	v_mfma_f32_16x16x32_bf16 v[42:45], v[130:133], v[182:185], v[42:45]
	v_mfma_f32_16x16x32_bf16 v[26:29], v[130:133], v[190:193], v[26:29]
	v_mfma_f32_16x16x32_bf16 v[26:29], v[134:137], v[200:203], v[26:29]
	v_mfma_f32_16x16x32_bf16 v[18:21], v[142:145], v[200:203], v[18:21]
	v_mfma_f32_16x16x32_bf16 v[18:21], v[138:141], v[190:193], v[18:21]
	v_mfma_f32_16x16x32_bf16 v[2:5], v[138:141], v[208:211], v[2:5]
	v_mfma_f32_16x16x32_bf16 v[2:5], v[142:145], v[212:215], v[2:5]
	v_mfma_f32_16x16x32_bf16 v[10:13], v[134:137], v[212:215], v[10:13]
	v_mfma_f32_16x16x32_bf16 v[10:13], v[130:133], v[208:211], v[10:13]
	s_setprio 0
	s_setprio 1
	v_mfma_f32_16x16x32_bf16 v[62:65], v[146:149], v[174:177], v[62:65]
	v_mfma_f32_16x16x32_bf16 v[62:65], v[150:153], v[178:181], v[62:65]
	v_mfma_f32_16x16x32_bf16 v[54:57], v[170:173], v[178:181], v[54:57]
	v_mfma_f32_16x16x32_bf16 v[54:57], v[154:157], v[174:177], v[54:57]
	v_mfma_f32_16x16x32_bf16 v[38:41], v[154:157], v[182:185], v[38:41]
	v_mfma_f32_16x16x32_bf16 v[38:41], v[170:173], v[186:189], v[38:41]
	v_mfma_f32_16x16x32_bf16 v[46:49], v[150:153], v[186:189], v[46:49]
	v_mfma_f32_16x16x32_bf16 v[46:49], v[146:149], v[182:185], v[46:49]
	v_mfma_f32_16x16x32_bf16 v[30:33], v[146:149], v[190:193], v[30:33]
	v_mfma_f32_16x16x32_bf16 v[30:33], v[150:153], v[200:203], v[30:33]
	v_mfma_f32_16x16x32_bf16 v[22:25], v[170:173], v[200:203], v[22:25]
	v_mfma_f32_16x16x32_bf16 v[22:25], v[154:157], v[190:193], v[22:25]
	v_mfma_f32_16x16x32_bf16 v[6:9], v[154:157], v[208:211], v[6:9]
	v_mfma_f32_16x16x32_bf16 v[6:9], v[170:173], v[212:215], v[6:9]
	v_mfma_f32_16x16x32_bf16 v[14:17], v[150:153], v[212:215], v[14:17]
	v_mfma_f32_16x16x32_bf16 v[14:17], v[146:149], v[208:211], v[14:17]
	s_setprio 0
	s_barrier
	s_add_u32 s18, s18, 0x100
	s_addc_u32 s19, s19, 0
	s_add_u32 s51, s51, 0x100
	s_addc_u32 s52, s52, 0
	s_cmp_ge_i32 s53, s17
	s_mov_b32 s2, s53
	s_cbranch_scc0 .LBB0_634

.LBB0_798:
	s_lshl_b32 s0, s26, 21
	s_and_b32 s0, s0, 0x1fe00000
	v_readlane_b32 s22, v248, 22
	v_readlane_b32 s23, v248, 23
	s_add_u32 s0, s22, s0
	s_addc_u32 s23, s23, 0
	s_lshr_b32 s22, s26, 13
	s_and_b32 s24, s22, 0x7ff80
	s_add_u32 s22, s0, s24
	s_addc_u32 s23, s23, 0
	s_lshl_b32 s0, s26, 13
	s_and_b32 s0, s0, 0x1fe00000
	s_add_u32 s0, s82, s0
	s_addc_u32 s25, s83, 0
	s_add_u32 s24, s0, s24
	s_addc_u32 s25, s25, 0
	s_cmp_lt_i32 s35, 1
	v_cmp_gt_i64_e64 s[26:27], s[26:27], -1
	s_cbranch_scc1 .LBB0_820
	s_and_b64 s[38:39], s[26:27], exec
	s_cselect_b32 s0, s23, s37
	s_cselect_b32 s34, s22, s36
	s_cselect_b32 s56, s25, s3
	s_cselect_b32 s57, s24, s2
	s_add_i32 s58, s35, -2
	s_add_u32 s36, s36, 0x100080
	s_addc_u32 s37, s37, 0
	s_add_u32 s59, s2, 0x100
	s_addc_u32 s60, s3, 0
	s_mov_b32 s2, 0
	ds_read_b128 v[148:151], v144
	ds_read_b128 v[152:155], v144 offset:1024
	ds_read_b128 v[156:159], v144 offset:2048
	ds_read_b128 v[160:163], v144 offset:3072
	ds_read_b128 v[164:167], v145
	ds_read_b128 v[168:171], v145 offset:1024
	ds_read_b128 v[172:175], v145 offset:2048
	ds_read_b128 v[176:179], v145 offset:3072
	s_add_i32 s61, s2, 2
	s_add_u32 s3, s36, 0xfff00080
	s_addc_u32 s38, s37, -1
	s_cmp_eq_u32 s58, s2
	s_cselect_b32 s2, s57, s59
	s_cselect_b32 s39, s0, s38
	s_cselect_b32 s38, s34, s3
	s_cselect_b32 s3, s56, s60
	v_lshl_add_u64 v[204:205], s[36:37], 0, v[138:139]
	s_add_i32 m0, s29, 0xc000
	ds_read_b128 v[180:183], v146
	ds_read_b128 v[184:187], v146 offset:1024
	ds_read_b128 v[188:191], v146 offset:2048
	ds_read_b128 v[192:195], v146 offset:3072
	ds_read_b128 v[196:199], v146 offset:4096
	ds_read_b128 v[200:203], v146 offset:5120
	ds_read_b128 v[208:211], v146 offset:6144
	ds_read_b128 v[212:215], v146 offset:7168
	global_load_lds_dwordx4 v[204:205], off
	v_lshl_add_u64 v[204:205], s[36:37], 0, v[140:141]
	s_add_i32 m0, s29, 0xe000
	s_nop 0
	global_load_lds_dwordx4 v[204:205], off
	s_waitcnt vmcnt(8)
	s_waitcnt lgkmcnt(0)
	s_barrier
	s_setprio 1
	s_waitcnt lgkmcnt(0)
	v_mfma_f32_16x16x32_bf16 v[126:129], v[148:151], v[180:183], 0
	v_mfma_f32_16x16x32_bf16 v[126:129], v[152:155], v[184:187], v[126:129]
	v_mfma_f32_16x16x32_bf16 v[122:125], v[160:163], v[184:187], 0
	v_mfma_f32_16x16x32_bf16 v[122:125], v[156:159], v[180:183], v[122:125]
	v_mfma_f32_16x16x32_bf16 v[102:105], v[156:159], v[188:191], 0
	v_mfma_f32_16x16x32_bf16 v[102:105], v[160:163], v[192:195], v[102:105]
	v_mfma_f32_16x16x32_bf16 v[110:113], v[152:155], v[192:195], 0
	v_mfma_f32_16x16x32_bf16 v[110:113], v[148:151], v[188:191], v[110:113]
	v_mfma_f32_16x16x32_bf16 v[94:97], v[148:151], v[196:199], 0
	v_mfma_f32_16x16x32_bf16 v[94:97], v[152:155], v[200:203], v[94:97]
	v_mfma_f32_16x16x32_bf16 v[86:89], v[160:163], v[200:203], 0
	v_mfma_f32_16x16x32_bf16 v[86:89], v[156:159], v[196:199], v[86:89]
	v_mfma_f32_16x16x32_bf16 v[70:73], v[156:159], v[208:211], 0
	v_mfma_f32_16x16x32_bf16 v[70:73], v[160:163], v[212:215], v[70:73]
	v_mfma_f32_16x16x32_bf16 v[78:81], v[152:155], v[212:215], 0
	v_mfma_f32_16x16x32_bf16 v[78:81], v[148:151], v[208:211], v[78:81]
	s_setprio 0
	s_setprio 1
	v_mfma_f32_16x16x32_bf16 v[118:121], v[164:167], v[180:183], 0
	v_mfma_f32_16x16x32_bf16 v[118:121], v[168:171], v[184:187], v[118:121]
	v_mfma_f32_16x16x32_bf16 v[114:117], v[176:179], v[184:187], 0
	v_mfma_f32_16x16x32_bf16 v[114:117], v[172:175], v[180:183], v[114:117]
	v_mfma_f32_16x16x32_bf16 v[98:101], v[172:175], v[188:191], 0
	v_mfma_f32_16x16x32_bf16 v[98:101], v[176:179], v[192:195], v[98:101]
	v_mfma_f32_16x16x32_bf16 v[106:109], v[168:171], v[192:195], 0
	v_mfma_f32_16x16x32_bf16 v[106:109], v[164:167], v[188:191], v[106:109]
	v_mfma_f32_16x16x32_bf16 v[90:93], v[164:167], v[196:199], 0
	v_mfma_f32_16x16x32_bf16 v[90:93], v[168:171], v[200:203], v[90:93]
	v_mfma_f32_16x16x32_bf16 v[82:85], v[176:179], v[200:203], 0
	v_mfma_f32_16x16x32_bf16 v[82:85], v[172:175], v[196:199], v[82:85]
	v_mfma_f32_16x16x32_bf16 v[66:69], v[172:175], v[208:211], 0
	v_mfma_f32_16x16x32_bf16 v[66:69], v[176:179], v[212:215], v[66:69]
	v_mfma_f32_16x16x32_bf16 v[74:77], v[168:171], v[212:215], 0
	v_mfma_f32_16x16x32_bf16 v[74:77], v[164:167], v[208:211], v[74:77]
	s_setprio 0
	s_barrier
	s_add_i32 s64, s50, s33
	v_lshl_add_u64 v[204:205], s[2:3], 0, v[132:133]
	s_mov_b32 m0, s64
	ds_read_b128 v[180:183], v146 offset:16384
	ds_read_b128 v[184:187], v146 offset:17408
	ds_read_b128 v[188:191], v146 offset:18432
	ds_read_b128 v[192:195], v146 offset:19456
	ds_read_b128 v[196:199], v146 offset:20480
	ds_read_b128 v[200:203], v146 offset:21504
	ds_read_b128 v[208:211], v146 offset:22528
	ds_read_b128 v[212:215], v146 offset:23552
	global_load_lds_dwordx4 v[204:205], off
	s_add_i32 m0, s64, 0x2000
	s_add_u32 s64, s2, 0x100000
	v_lshl_add_u64 v[216:217], s[2:3], 0, v[136:137]
	s_addc_u32 s65, s3, 0
	s_add_i32 s66, s51, s33
	global_load_lds_dwordx4 v[216:217], off
	v_lshl_add_u64 v[218:219], s[64:65], 0, v[132:133]
	s_mov_b32 m0, s66
	v_lshl_add_u64 v[220:221], s[38:39], 0, v[134:135]
	global_load_lds_dwordx4 v[218:219], off
	v_lshl_add_u64 v[218:219], s[64:65], 0, v[136:137]
	s_add_i32 m0, s66, 0x2000
	s_nop 0
	global_load_lds_dwordx4 v[218:219], off
	v_lshl_add_u64 v[218:219], s[38:39], 0, v[130:131]
	s_mov_b32 m0, s29
	s_nop 0
	global_load_lds_dwordx4 v[218:219], off
	s_mov_b32 m0, s31
	s_nop 0
	global_load_lds_dwordx4 v[220:221], off
	s_waitcnt vmcnt(8)
	s_waitcnt lgkmcnt(0)
	s_barrier
	s_setprio 1
	s_waitcnt lgkmcnt(0)
	v_mfma_f32_16x16x32_bf16 v[62:65], v[148:151], v[180:183], 0
	v_mfma_f32_16x16x32_bf16 v[62:65], v[152:155], v[184:187], v[62:65]
	v_mfma_f32_16x16x32_bf16 v[54:57], v[160:163], v[184:187], 0
	v_mfma_f32_16x16x32_bf16 v[54:57], v[156:159], v[180:183], v[54:57]
	v_mfma_f32_16x16x32_bf16 v[38:41], v[156:159], v[188:191], 0
	v_mfma_f32_16x16x32_bf16 v[38:41], v[160:163], v[192:195], v[38:41]
	v_mfma_f32_16x16x32_bf16 v[46:49], v[152:155], v[192:195], 0
	v_mfma_f32_16x16x32_bf16 v[46:49], v[148:151], v[188:191], v[46:49]
	v_mfma_f32_16x16x32_bf16 v[30:33], v[148:151], v[196:199], 0
	v_mfma_f32_16x16x32_bf16 v[30:33], v[152:155], v[200:203], v[30:33]
	v_mfma_f32_16x16x32_bf16 v[22:25], v[160:163], v[200:203], 0
	v_mfma_f32_16x16x32_bf16 v[22:25], v[156:159], v[196:199], v[22:25]
	v_mfma_f32_16x16x32_bf16 v[6:9], v[156:159], v[208:211], 0
	v_mfma_f32_16x16x32_bf16 v[6:9], v[160:163], v[212:215], v[6:9]
	v_mfma_f32_16x16x32_bf16 v[14:17], v[152:155], v[212:215], 0
	v_mfma_f32_16x16x32_bf16 v[14:17], v[148:151], v[208:211], v[14:17]
	s_setprio 0
	s_setprio 1
	v_mfma_f32_16x16x32_bf16 v[58:61], v[164:167], v[180:183], 0
	v_mfma_f32_16x16x32_bf16 v[58:61], v[168:171], v[184:187], v[58:61]
	v_mfma_f32_16x16x32_bf16 v[50:53], v[176:179], v[184:187], 0
	v_mfma_f32_16x16x32_bf16 v[50:53], v[172:175], v[180:183], v[50:53]
	v_mfma_f32_16x16x32_bf16 v[34:37], v[172:175], v[188:191], 0
	v_mfma_f32_16x16x32_bf16 v[34:37], v[176:179], v[192:195], v[34:37]
	v_mfma_f32_16x16x32_bf16 v[42:45], v[168:171], v[192:195], 0
	v_mfma_f32_16x16x32_bf16 v[42:45], v[164:167], v[188:191], v[42:45]
	v_mfma_f32_16x16x32_bf16 v[26:29], v[164:167], v[196:199], 0
	v_mfma_f32_16x16x32_bf16 v[26:29], v[168:171], v[200:203], v[26:29]
	v_mfma_f32_16x16x32_bf16 v[18:21], v[176:179], v[200:203], 0
	v_mfma_f32_16x16x32_bf16 v[18:21], v[172:175], v[196:199], v[18:21]
	v_mfma_f32_16x16x32_bf16 v[2:5], v[172:175], v[208:211], 0
	v_mfma_f32_16x16x32_bf16 v[2:5], v[176:179], v[212:215], v[2:5]
	v_mfma_f32_16x16x32_bf16 v[10:13], v[168:171], v[212:215], 0
	v_mfma_f32_16x16x32_bf16 v[10:13], v[164:167], v[208:211], v[10:13]
	s_setprio 0
	s_barrier
	s_add_i32 s64, 0, 0x18000
	v_add_u32_e32 v147, s64, v142
	s_add_i32 s65, 0, 0x1c000
	ds_read_b128 v[148:151], v147
	ds_read_b128 v[152:155], v147 offset:1024
	ds_read_b128 v[156:159], v147 offset:2048
	ds_read_b128 v[160:163], v147 offset:3072
	v_add_u32_e32 v147, s65, v142
	ds_read_b128 v[164:167], v147
	ds_read_b128 v[168:171], v147 offset:1024
	ds_read_b128 v[172:175], v147 offset:2048
	ds_read_b128 v[176:179], v147 offset:3072
	s_add_u32 s38, s38, 0x100000
	s_addc_u32 s39, s39, 0
	s_mov_b32 m0, s41
	v_lshl_add_u64 v[222:223], s[38:39], 0, v[130:131]
	ds_read_b128 v[180:183], v146 offset:32768
	ds_read_b128 v[184:187], v146 offset:33792
	ds_read_b128 v[188:191], v146 offset:34816
	ds_read_b128 v[192:195], v146 offset:35840
	ds_read_b128 v[196:199], v146 offset:36864
	ds_read_b128 v[200:203], v146 offset:37888
	ds_read_b128 v[208:211], v146 offset:38912
	ds_read_b128 v[212:215], v146 offset:39936
	global_load_lds_dwordx4 v[222:223], off
	v_lshl_add_u64 v[222:223], s[38:39], 0, v[134:135]
	s_mov_b32 m0, s42
	s_nop 0
	global_load_lds_dwordx4 v[222:223], off
	s_waitcnt vmcnt(8)
	s_waitcnt lgkmcnt(0)
	s_barrier
	s_setprio 1
	s_waitcnt lgkmcnt(0)
	v_mfma_f32_16x16x32_bf16 v[126:129], v[148:151], v[180:183], v[126:129]
	v_mfma_f32_16x16x32_bf16 v[126:129], v[152:155], v[184:187], v[126:129]
	v_mfma_f32_16x16x32_bf16 v[122:125], v[160:163], v[184:187], v[122:125]
	v_mfma_f32_16x16x32_bf16 v[122:125], v[156:159], v[180:183], v[122:125]
	v_mfma_f32_16x16x32_bf16 v[102:105], v[156:159], v[188:191], v[102:105]
	v_mfma_f32_16x16x32_bf16 v[102:105], v[160:163], v[192:195], v[102:105]
	v_mfma_f32_16x16x32_bf16 v[110:113], v[152:155], v[192:195], v[110:113]
	v_mfma_f32_16x16x32_bf16 v[110:113], v[148:151], v[188:191], v[110:113]
	v_mfma_f32_16x16x32_bf16 v[94:97], v[148:151], v[196:199], v[94:97]
	v_mfma_f32_16x16x32_bf16 v[94:97], v[152:155], v[200:203], v[94:97]
	v_mfma_f32_16x16x32_bf16 v[86:89], v[160:163], v[200:203], v[86:89]
	v_mfma_f32_16x16x32_bf16 v[86:89], v[156:159], v[196:199], v[86:89]
	v_mfma_f32_16x16x32_bf16 v[70:73], v[156:159], v[208:211], v[70:73]
	v_mfma_f32_16x16x32_bf16 v[70:73], v[160:163], v[212:215], v[70:73]
	v_mfma_f32_16x16x32_bf16 v[78:81], v[152:155], v[212:215], v[78:81]
	v_mfma_f32_16x16x32_bf16 v[78:81], v[148:151], v[208:211], v[78:81]
	s_setprio 0
	s_setprio 1
	v_mfma_f32_16x16x32_bf16 v[118:121], v[164:167], v[180:183], v[118:121]
	v_mfma_f32_16x16x32_bf16 v[118:121], v[168:171], v[184:187], v[118:121]
	v_mfma_f32_16x16x32_bf16 v[114:117], v[176:179], v[184:187], v[114:117]
	v_mfma_f32_16x16x32_bf16 v[114:117], v[172:175], v[180:183], v[114:117]
	v_mfma_f32_16x16x32_bf16 v[98:101], v[172:175], v[188:191], v[98:101]
	v_mfma_f32_16x16x32_bf16 v[98:101], v[176:179], v[192:195], v[98:101]
	v_mfma_f32_16x16x32_bf16 v[106:109], v[168:171], v[192:195], v[106:109]
	v_mfma_f32_16x16x32_bf16 v[106:109], v[164:167], v[188:191], v[106:109]
	v_mfma_f32_16x16x32_bf16 v[90:93], v[164:167], v[196:199], v[90:93]
	v_mfma_f32_16x16x32_bf16 v[90:93], v[168:171], v[200:203], v[90:93]
	v_mfma_f32_16x16x32_bf16 v[82:85], v[176:179], v[200:203], v[82:85]
	v_mfma_f32_16x16x32_bf16 v[82:85], v[172:175], v[196:199], v[82:85]
	v_mfma_f32_16x16x32_bf16 v[66:69], v[172:175], v[208:211], v[66:69]
	v_mfma_f32_16x16x32_bf16 v[66:69], v[176:179], v[212:215], v[66:69]
	v_mfma_f32_16x16x32_bf16 v[74:77], v[168:171], v[212:215], v[74:77]
	v_mfma_f32_16x16x32_bf16 v[74:77], v[164:167], v[208:211], v[74:77]
	s_setprio 0
	s_barrier
	s_add_i32 s38, s64, s33
	v_lshl_add_u64 v[204:205], v[204:205], 0, s[16:17]
	s_mov_b32 m0, s38
	ds_read_b128 v[180:183], v146 offset:49152
	ds_read_b128 v[184:187], v146 offset:50176
	ds_read_b128 v[188:191], v146 offset:51200
	ds_read_b128 v[192:195], v146 offset:52224
	ds_read_b128 v[196:199], v146 offset:53248
	ds_read_b128 v[200:203], v146 offset:54272
	ds_read_b128 v[208:211], v146 offset:55296
	ds_read_b128 v[212:215], v146 offset:56320
	global_load_lds_dwordx4 v[204:205], off
	s_add_i32 m0, s38, 0x2000
	s_add_u32 s2, s2, 0x100080
	v_lshl_add_u64 v[204:205], v[216:217], 0, s[16:17]
	s_addc_u32 s3, s3, 0
	s_add_i32 s38, s65, s33
	global_load_lds_dwordx4 v[204:205], off
	v_lshl_add_u64 v[204:205], s[2:3], 0, v[132:133]
	s_mov_b32 m0, s38
	s_nop 0
	global_load_lds_dwordx4 v[204:205], off
	v_lshl_add_u64 v[204:205], s[2:3], 0, v[136:137]
	s_add_i32 m0, s38, 0x2000
	s_nop 0
	global_load_lds_dwordx4 v[204:205], off
	v_lshl_add_u64 v[204:205], v[218:219], 0, s[16:17]
	s_mov_b32 m0, s44
	s_nop 0
	global_load_lds_dwordx4 v[204:205], off
	v_lshl_add_u64 v[204:205], v[220:221], 0, s[16:17]
	s_mov_b32 m0, s45
	s_nop 0
	global_load_lds_dwordx4 v[204:205], off
	s_waitcnt vmcnt(8)
	s_waitcnt lgkmcnt(0)
	s_barrier
	s_setprio 1
	s_waitcnt lgkmcnt(0)
	v_mfma_f32_16x16x32_bf16 v[62:65], v[148:151], v[180:183], v[62:65]
	v_mfma_f32_16x16x32_bf16 v[62:65], v[152:155], v[184:187], v[62:65]
	v_mfma_f32_16x16x32_bf16 v[54:57], v[160:163], v[184:187], v[54:57]
	v_mfma_f32_16x16x32_bf16 v[54:57], v[156:159], v[180:183], v[54:57]
	v_mfma_f32_16x16x32_bf16 v[38:41], v[156:159], v[188:191], v[38:41]
	v_mfma_f32_16x16x32_bf16 v[38:41], v[160:163], v[192:195], v[38:41]
	v_mfma_f32_16x16x32_bf16 v[46:49], v[152:155], v[192:195], v[46:49]
	v_mfma_f32_16x16x32_bf16 v[46:49], v[148:151], v[188:191], v[46:49]
	v_mfma_f32_16x16x32_bf16 v[30:33], v[148:151], v[196:199], v[30:33]
	v_mfma_f32_16x16x32_bf16 v[30:33], v[152:155], v[200:203], v[30:33]
	v_mfma_f32_16x16x32_bf16 v[22:25], v[160:163], v[200:203], v[22:25]
	v_mfma_f32_16x16x32_bf16 v[22:25], v[156:159], v[196:199], v[22:25]
	v_mfma_f32_16x16x32_bf16 v[6:9], v[156:159], v[208:211], v[6:9]
	v_mfma_f32_16x16x32_bf16 v[6:9], v[160:163], v[212:215], v[6:9]
	v_mfma_f32_16x16x32_bf16 v[14:17], v[152:155], v[212:215], v[14:17]
	v_mfma_f32_16x16x32_bf16 v[14:17], v[148:151], v[208:211], v[14:17]
	s_setprio 0
	s_setprio 1
	v_mfma_f32_16x16x32_bf16 v[58:61], v[164:167], v[180:183], v[58:61]
	v_mfma_f32_16x16x32_bf16 v[58:61], v[168:171], v[184:187], v[58:61]
	v_mfma_f32_16x16x32_bf16 v[50:53], v[176:179], v[184:187], v[50:53]
	v_mfma_f32_16x16x32_bf16 v[50:53], v[172:175], v[180:183], v[50:53]
	v_mfma_f32_16x16x32_bf16 v[34:37], v[172:175], v[188:191], v[34:37]
	v_mfma_f32_16x16x32_bf16 v[34:37], v[176:179], v[192:195], v[34:37]
	v_mfma_f32_16x16x32_bf16 v[42:45], v[168:171], v[192:195], v[42:45]
	v_mfma_f32_16x16x32_bf16 v[42:45], v[164:167], v[188:191], v[42:45]
	v_mfma_f32_16x16x32_bf16 v[26:29], v[164:167], v[196:199], v[26:29]
	v_mfma_f32_16x16x32_bf16 v[26:29], v[168:171], v[200:203], v[26:29]
	v_mfma_f32_16x16x32_bf16 v[18:21], v[176:179], v[200:203], v[18:21]
	v_mfma_f32_16x16x32_bf16 v[18:21], v[172:175], v[196:199], v[18:21]
	v_mfma_f32_16x16x32_bf16 v[2:5], v[172:175], v[208:211], v[2:5]
	v_mfma_f32_16x16x32_bf16 v[2:5], v[176:179], v[212:215], v[2:5]
	v_mfma_f32_16x16x32_bf16 v[10:13], v[168:171], v[212:215], v[10:13]
	v_mfma_f32_16x16x32_bf16 v[10:13], v[164:167], v[208:211], v[10:13]
	s_setprio 0
	s_barrier
	s_add_u32 s36, s36, 0x100
	s_addc_u32 s37, s37, 0
	s_add_u32 s59, s59, 0x100
	s_addc_u32 s60, s60, 0
	s_cmp_ge_i32 s61, s35
	s_mov_b32 s2, s61
	s_cbranch_scc1 .Lkpeel_exit_4
.LBB0_800:
	ds_read_b128 v[148:151], v144
	ds_read_b128 v[152:155], v144 offset:1024
	ds_read_b128 v[156:159], v144 offset:2048
	ds_read_b128 v[160:163], v144 offset:3072
	ds_read_b128 v[164:167], v145
	ds_read_b128 v[168:171], v145 offset:1024
	ds_read_b128 v[172:175], v145 offset:2048
	ds_read_b128 v[176:179], v145 offset:3072
	s_add_i32 s61, s2, 2
	s_add_u32 s3, s36, 0xfff00080
	s_addc_u32 s38, s37, -1
	s_cmp_eq_u32 s58, s2
	s_cselect_b32 s2, s57, s59
	s_cselect_b32 s39, s0, s38
	s_cselect_b32 s38, s34, s3
	s_cselect_b32 s3, s56, s60
	v_lshl_add_u64 v[204:205], s[36:37], 0, v[138:139]
	s_add_i32 m0, s29, 0xc000
	ds_read_b128 v[180:183], v146
	ds_read_b128 v[184:187], v146 offset:1024
	ds_read_b128 v[188:191], v146 offset:2048
	ds_read_b128 v[192:195], v146 offset:3072
	ds_read_b128 v[196:199], v146 offset:4096
	ds_read_b128 v[200:203], v146 offset:5120
	ds_read_b128 v[208:211], v146 offset:6144
	ds_read_b128 v[212:215], v146 offset:7168
	global_load_lds_dwordx4 v[204:205], off
	v_lshl_add_u64 v[204:205], s[36:37], 0, v[140:141]
	s_add_i32 m0, s29, 0xe000
	s_nop 0
	global_load_lds_dwordx4 v[204:205], off
	s_waitcnt vmcnt(8)
	s_waitcnt lgkmcnt(0)
	s_barrier
	s_setprio 1
	s_waitcnt lgkmcnt(0)
	v_mfma_f32_16x16x32_bf16 v[126:129], v[148:151], v[180:183], v[126:129]
	v_mfma_f32_16x16x32_bf16 v[126:129], v[152:155], v[184:187], v[126:129]
	v_mfma_f32_16x16x32_bf16 v[122:125], v[160:163], v[184:187], v[122:125]
	v_mfma_f32_16x16x32_bf16 v[122:125], v[156:159], v[180:183], v[122:125]
	v_mfma_f32_16x16x32_bf16 v[102:105], v[156:159], v[188:191], v[102:105]
	v_mfma_f32_16x16x32_bf16 v[102:105], v[160:163], v[192:195], v[102:105]
	v_mfma_f32_16x16x32_bf16 v[110:113], v[152:155], v[192:195], v[110:113]
	v_mfma_f32_16x16x32_bf16 v[110:113], v[148:151], v[188:191], v[110:113]
	v_mfma_f32_16x16x32_bf16 v[94:97], v[148:151], v[196:199], v[94:97]
	v_mfma_f32_16x16x32_bf16 v[94:97], v[152:155], v[200:203], v[94:97]
	v_mfma_f32_16x16x32_bf16 v[86:89], v[160:163], v[200:203], v[86:89]
	v_mfma_f32_16x16x32_bf16 v[86:89], v[156:159], v[196:199], v[86:89]
	v_mfma_f32_16x16x32_bf16 v[70:73], v[156:159], v[208:211], v[70:73]
	v_mfma_f32_16x16x32_bf16 v[70:73], v[160:163], v[212:215], v[70:73]
	v_mfma_f32_16x16x32_bf16 v[78:81], v[152:155], v[212:215], v[78:81]
	v_mfma_f32_16x16x32_bf16 v[78:81], v[148:151], v[208:211], v[78:81]
	s_setprio 0
	s_setprio 1
	v_mfma_f32_16x16x32_bf16 v[118:121], v[164:167], v[180:183], v[118:121]
	v_mfma_f32_16x16x32_bf16 v[118:121], v[168:171], v[184:187], v[118:121]
	v_mfma_f32_16x16x32_bf16 v[114:117], v[176:179], v[184:187], v[114:117]
	v_mfma_f32_16x16x32_bf16 v[114:117], v[172:175], v[180:183], v[114:117]
	v_mfma_f32_16x16x32_bf16 v[98:101], v[172:175], v[188:191], v[98:101]
	v_mfma_f32_16x16x32_bf16 v[98:101], v[176:179], v[192:195], v[98:101]
	v_mfma_f32_16x16x32_bf16 v[106:109], v[168:171], v[192:195], v[106:109]
	v_mfma_f32_16x16x32_bf16 v[106:109], v[164:167], v[188:191], v[106:109]
	v_mfma_f32_16x16x32_bf16 v[90:93], v[164:167], v[196:199], v[90:93]
	v_mfma_f32_16x16x32_bf16 v[90:93], v[168:171], v[200:203], v[90:93]
	v_mfma_f32_16x16x32_bf16 v[82:85], v[176:179], v[200:203], v[82:85]
	v_mfma_f32_16x16x32_bf16 v[82:85], v[172:175], v[196:199], v[82:85]
	v_mfma_f32_16x16x32_bf16 v[66:69], v[172:175], v[208:211], v[66:69]
	v_mfma_f32_16x16x32_bf16 v[66:69], v[176:179], v[212:215], v[66:69]
	v_mfma_f32_16x16x32_bf16 v[74:77], v[168:171], v[212:215], v[74:77]
	v_mfma_f32_16x16x32_bf16 v[74:77], v[164:167], v[208:211], v[74:77]
	s_setprio 0
	s_barrier
	s_add_i32 s64, s50, s33
	v_lshl_add_u64 v[204:205], s[2:3], 0, v[132:133]
	s_mov_b32 m0, s64
	ds_read_b128 v[180:183], v146 offset:16384
	ds_read_b128 v[184:187], v146 offset:17408
	ds_read_b128 v[188:191], v146 offset:18432
	ds_read_b128 v[192:195], v146 offset:19456
	ds_read_b128 v[196:199], v146 offset:20480
	ds_read_b128 v[200:203], v146 offset:21504
	ds_read_b128 v[208:211], v146 offset:22528
	ds_read_b128 v[212:215], v146 offset:23552
	global_load_lds_dwordx4 v[204:205], off
	s_add_i32 m0, s64, 0x2000
	s_add_u32 s64, s2, 0x100000
	v_lshl_add_u64 v[216:217], s[2:3], 0, v[136:137]
	s_addc_u32 s65, s3, 0
	s_add_i32 s66, s51, s33
	global_load_lds_dwordx4 v[216:217], off
	v_lshl_add_u64 v[218:219], s[64:65], 0, v[132:133]
	s_mov_b32 m0, s66
	v_lshl_add_u64 v[220:221], s[38:39], 0, v[134:135]
	global_load_lds_dwordx4 v[218:219], off
	v_lshl_add_u64 v[218:219], s[64:65], 0, v[136:137]
	s_add_i32 m0, s66, 0x2000
	s_nop 0
	global_load_lds_dwordx4 v[218:219], off
	v_lshl_add_u64 v[218:219], s[38:39], 0, v[130:131]
	s_mov_b32 m0, s29
	s_nop 0
	global_load_lds_dwordx4 v[218:219], off
	s_mov_b32 m0, s31
	s_nop 0
	global_load_lds_dwordx4 v[220:221], off
	s_waitcnt vmcnt(8)
	s_waitcnt lgkmcnt(0)
	s_barrier
	s_setprio 1
	s_waitcnt lgkmcnt(0)
	v_mfma_f32_16x16x32_bf16 v[62:65], v[148:151], v[180:183], v[62:65]
	v_mfma_f32_16x16x32_bf16 v[62:65], v[152:155], v[184:187], v[62:65]
	v_mfma_f32_16x16x32_bf16 v[54:57], v[160:163], v[184:187], v[54:57]
	v_mfma_f32_16x16x32_bf16 v[54:57], v[156:159], v[180:183], v[54:57]
	v_mfma_f32_16x16x32_bf16 v[38:41], v[156:159], v[188:191], v[38:41]
	v_mfma_f32_16x16x32_bf16 v[38:41], v[160:163], v[192:195], v[38:41]
	v_mfma_f32_16x16x32_bf16 v[46:49], v[152:155], v[192:195], v[46:49]
	v_mfma_f32_16x16x32_bf16 v[46:49], v[148:151], v[188:191], v[46:49]
	v_mfma_f32_16x16x32_bf16 v[30:33], v[148:151], v[196:199], v[30:33]
	v_mfma_f32_16x16x32_bf16 v[30:33], v[152:155], v[200:203], v[30:33]
	v_mfma_f32_16x16x32_bf16 v[22:25], v[160:163], v[200:203], v[22:25]
	v_mfma_f32_16x16x32_bf16 v[22:25], v[156:159], v[196:199], v[22:25]
	v_mfma_f32_16x16x32_bf16 v[6:9], v[156:159], v[208:211], v[6:9]
	v_mfma_f32_16x16x32_bf16 v[6:9], v[160:163], v[212:215], v[6:9]
	v_mfma_f32_16x16x32_bf16 v[14:17], v[152:155], v[212:215], v[14:17]
	v_mfma_f32_16x16x32_bf16 v[14:17], v[148:151], v[208:211], v[14:17]
	s_setprio 0
	s_setprio 1
	v_mfma_f32_16x16x32_bf16 v[58:61], v[164:167], v[180:183], v[58:61]
	v_mfma_f32_16x16x32_bf16 v[58:61], v[168:171], v[184:187], v[58:61]
	v_mfma_f32_16x16x32_bf16 v[50:53], v[176:179], v[184:187], v[50:53]
	v_mfma_f32_16x16x32_bf16 v[50:53], v[172:175], v[180:183], v[50:53]
	v_mfma_f32_16x16x32_bf16 v[34:37], v[172:175], v[188:191], v[34:37]
	v_mfma_f32_16x16x32_bf16 v[34:37], v[176:179], v[192:195], v[34:37]
	v_mfma_f32_16x16x32_bf16 v[42:45], v[168:171], v[192:195], v[42:45]
	v_mfma_f32_16x16x32_bf16 v[42:45], v[164:167], v[188:191], v[42:45]
	v_mfma_f32_16x16x32_bf16 v[26:29], v[164:167], v[196:199], v[26:29]
	v_mfma_f32_16x16x32_bf16 v[26:29], v[168:171], v[200:203], v[26:29]
	v_mfma_f32_16x16x32_bf16 v[18:21], v[176:179], v[200:203], v[18:21]
	v_mfma_f32_16x16x32_bf16 v[18:21], v[172:175], v[196:199], v[18:21]
	v_mfma_f32_16x16x32_bf16 v[2:5], v[172:175], v[208:211], v[2:5]
	v_mfma_f32_16x16x32_bf16 v[2:5], v[176:179], v[212:215], v[2:5]
	v_mfma_f32_16x16x32_bf16 v[10:13], v[168:171], v[212:215], v[10:13]
	v_mfma_f32_16x16x32_bf16 v[10:13], v[164:167], v[208:211], v[10:13]
	s_setprio 0
	s_barrier
	s_add_i32 s64, 0, 0x18000
	v_add_u32_e32 v147, s64, v142
	s_add_i32 s65, 0, 0x1c000
	ds_read_b128 v[148:151], v147
	ds_read_b128 v[152:155], v147 offset:1024
	ds_read_b128 v[156:159], v147 offset:2048
	ds_read_b128 v[160:163], v147 offset:3072
	v_add_u32_e32 v147, s65, v142
	ds_read_b128 v[164:167], v147
	ds_read_b128 v[168:171], v147 offset:1024
	ds_read_b128 v[172:175], v147 offset:2048
	ds_read_b128 v[176:179], v147 offset:3072
	s_add_u32 s38, s38, 0x100000
	s_addc_u32 s39, s39, 0
	s_mov_b32 m0, s41
	v_lshl_add_u64 v[222:223], s[38:39], 0, v[130:131]
	ds_read_b128 v[180:183], v146 offset:32768
	ds_read_b128 v[184:187], v146 offset:33792
	ds_read_b128 v[188:191], v146 offset:34816
	ds_read_b128 v[192:195], v146 offset:35840
	ds_read_b128 v[196:199], v146 offset:36864
	ds_read_b128 v[200:203], v146 offset:37888
	ds_read_b128 v[208:211], v146 offset:38912
	ds_read_b128 v[212:215], v146 offset:39936
	global_load_lds_dwordx4 v[222:223], off
	v_lshl_add_u64 v[222:223], s[38:39], 0, v[134:135]
	s_mov_b32 m0, s42
	s_nop 0
	global_load_lds_dwordx4 v[222:223], off
	s_waitcnt vmcnt(8)
	s_waitcnt lgkmcnt(0)
	s_barrier
	s_setprio 1
	s_waitcnt lgkmcnt(0)
	v_mfma_f32_16x16x32_bf16 v[126:129], v[148:151], v[180:183], v[126:129]
	v_mfma_f32_16x16x32_bf16 v[126:129], v[152:155], v[184:187], v[126:129]
	v_mfma_f32_16x16x32_bf16 v[122:125], v[160:163], v[184:187], v[122:125]
	v_mfma_f32_16x16x32_bf16 v[122:125], v[156:159], v[180:183], v[122:125]
	v_mfma_f32_16x16x32_bf16 v[102:105], v[156:159], v[188:191], v[102:105]
	v_mfma_f32_16x16x32_bf16 v[102:105], v[160:163], v[192:195], v[102:105]
	v_mfma_f32_16x16x32_bf16 v[110:113], v[152:155], v[192:195], v[110:113]
	v_mfma_f32_16x16x32_bf16 v[110:113], v[148:151], v[188:191], v[110:113]
	v_mfma_f32_16x16x32_bf16 v[94:97], v[148:151], v[196:199], v[94:97]
	v_mfma_f32_16x16x32_bf16 v[94:97], v[152:155], v[200:203], v[94:97]
	v_mfma_f32_16x16x32_bf16 v[86:89], v[160:163], v[200:203], v[86:89]
	v_mfma_f32_16x16x32_bf16 v[86:89], v[156:159], v[196:199], v[86:89]
	v_mfma_f32_16x16x32_bf16 v[70:73], v[156:159], v[208:211], v[70:73]
	v_mfma_f32_16x16x32_bf16 v[70:73], v[160:163], v[212:215], v[70:73]
	v_mfma_f32_16x16x32_bf16 v[78:81], v[152:155], v[212:215], v[78:81]
	v_mfma_f32_16x16x32_bf16 v[78:81], v[148:151], v[208:211], v[78:81]
	s_setprio 0
	s_setprio 1
	v_mfma_f32_16x16x32_bf16 v[118:121], v[164:167], v[180:183], v[118:121]
	v_mfma_f32_16x16x32_bf16 v[118:121], v[168:171], v[184:187], v[118:121]
	v_mfma_f32_16x16x32_bf16 v[114:117], v[176:179], v[184:187], v[114:117]
	v_mfma_f32_16x16x32_bf16 v[114:117], v[172:175], v[180:183], v[114:117]
	v_mfma_f32_16x16x32_bf16 v[98:101], v[172:175], v[188:191], v[98:101]
	v_mfma_f32_16x16x32_bf16 v[98:101], v[176:179], v[192:195], v[98:101]
	v_mfma_f32_16x16x32_bf16 v[106:109], v[168:171], v[192:195], v[106:109]
	v_mfma_f32_16x16x32_bf16 v[106:109], v[164:167], v[188:191], v[106:109]
	v_mfma_f32_16x16x32_bf16 v[90:93], v[164:167], v[196:199], v[90:93]
	v_mfma_f32_16x16x32_bf16 v[90:93], v[168:171], v[200:203], v[90:93]
	v_mfma_f32_16x16x32_bf16 v[82:85], v[176:179], v[200:203], v[82:85]
	v_mfma_f32_16x16x32_bf16 v[82:85], v[172:175], v[196:199], v[82:85]
	v_mfma_f32_16x16x32_bf16 v[66:69], v[172:175], v[208:211], v[66:69]
	v_mfma_f32_16x16x32_bf16 v[66:69], v[176:179], v[212:215], v[66:69]
	v_mfma_f32_16x16x32_bf16 v[74:77], v[168:171], v[212:215], v[74:77]
	v_mfma_f32_16x16x32_bf16 v[74:77], v[164:167], v[208:211], v[74:77]
	s_setprio 0
	s_barrier
	s_add_i32 s38, s64, s33
	v_lshl_add_u64 v[204:205], v[204:205], 0, s[16:17]
	s_mov_b32 m0, s38
	ds_read_b128 v[180:183], v146 offset:49152
	ds_read_b128 v[184:187], v146 offset:50176
	ds_read_b128 v[188:191], v146 offset:51200
	ds_read_b128 v[192:195], v146 offset:52224
	ds_read_b128 v[196:199], v146 offset:53248
	ds_read_b128 v[200:203], v146 offset:54272
	ds_read_b128 v[208:211], v146 offset:55296
	ds_read_b128 v[212:215], v146 offset:56320
	global_load_lds_dwordx4 v[204:205], off
	s_add_i32 m0, s38, 0x2000
	s_add_u32 s2, s2, 0x100080
	v_lshl_add_u64 v[204:205], v[216:217], 0, s[16:17]
	s_addc_u32 s3, s3, 0
	s_add_i32 s38, s65, s33
	global_load_lds_dwordx4 v[204:205], off
	v_lshl_add_u64 v[204:205], s[2:3], 0, v[132:133]
	s_mov_b32 m0, s38
	s_nop 0
	global_load_lds_dwordx4 v[204:205], off
	v_lshl_add_u64 v[204:205], s[2:3], 0, v[136:137]
	s_add_i32 m0, s38, 0x2000
	s_nop 0
	global_load_lds_dwordx4 v[204:205], off
	v_lshl_add_u64 v[204:205], v[218:219], 0, s[16:17]
	s_mov_b32 m0, s44
	s_nop 0
	global_load_lds_dwordx4 v[204:205], off
	v_lshl_add_u64 v[204:205], v[220:221], 0, s[16:17]
	s_mov_b32 m0, s45
	s_nop 0
	global_load_lds_dwordx4 v[204:205], off
	s_waitcnt vmcnt(8)
	s_waitcnt lgkmcnt(0)
	s_barrier
	s_setprio 1
	s_waitcnt lgkmcnt(0)
	v_mfma_f32_16x16x32_bf16 v[62:65], v[148:151], v[180:183], v[62:65]
	v_mfma_f32_16x16x32_bf16 v[62:65], v[152:155], v[184:187], v[62:65]
	v_mfma_f32_16x16x32_bf16 v[54:57], v[160:163], v[184:187], v[54:57]
	v_mfma_f32_16x16x32_bf16 v[54:57], v[156:159], v[180:183], v[54:57]
	v_mfma_f32_16x16x32_bf16 v[38:41], v[156:159], v[188:191], v[38:41]
	v_mfma_f32_16x16x32_bf16 v[38:41], v[160:163], v[192:195], v[38:41]
	v_mfma_f32_16x16x32_bf16 v[46:49], v[152:155], v[192:195], v[46:49]
	v_mfma_f32_16x16x32_bf16 v[46:49], v[148:151], v[188:191], v[46:49]
	v_mfma_f32_16x16x32_bf16 v[30:33], v[148:151], v[196:199], v[30:33]
	v_mfma_f32_16x16x32_bf16 v[30:33], v[152:155], v[200:203], v[30:33]
	v_mfma_f32_16x16x32_bf16 v[22:25], v[160:163], v[200:203], v[22:25]
	v_mfma_f32_16x16x32_bf16 v[22:25], v[156:159], v[196:199], v[22:25]
	v_mfma_f32_16x16x32_bf16 v[6:9], v[156:159], v[208:211], v[6:9]
	v_mfma_f32_16x16x32_bf16 v[6:9], v[160:163], v[212:215], v[6:9]
	v_mfma_f32_16x16x32_bf16 v[14:17], v[152:155], v[212:215], v[14:17]
	v_mfma_f32_16x16x32_bf16 v[14:17], v[148:151], v[208:211], v[14:17]
	s_setprio 0
	s_setprio 1
	v_mfma_f32_16x16x32_bf16 v[58:61], v[164:167], v[180:183], v[58:61]
	v_mfma_f32_16x16x32_bf16 v[58:61], v[168:171], v[184:187], v[58:61]
	v_mfma_f32_16x16x32_bf16 v[50:53], v[176:179], v[184:187], v[50:53]
	v_mfma_f32_16x16x32_bf16 v[50:53], v[172:175], v[180:183], v[50:53]
	v_mfma_f32_16x16x32_bf16 v[34:37], v[172:175], v[188:191], v[34:37]
	v_mfma_f32_16x16x32_bf16 v[34:37], v[176:179], v[192:195], v[34:37]
	v_mfma_f32_16x16x32_bf16 v[42:45], v[168:171], v[192:195], v[42:45]
	v_mfma_f32_16x16x32_bf16 v[42:45], v[164:167], v[188:191], v[42:45]
	v_mfma_f32_16x16x32_bf16 v[26:29], v[164:167], v[196:199], v[26:29]
	v_mfma_f32_16x16x32_bf16 v[26:29], v[168:171], v[200:203], v[26:29]
	v_mfma_f32_16x16x32_bf16 v[18:21], v[176:179], v[200:203], v[18:21]
	v_mfma_f32_16x16x32_bf16 v[18:21], v[172:175], v[196:199], v[18:21]
	v_mfma_f32_16x16x32_bf16 v[2:5], v[172:175], v[208:211], v[2:5]
	v_mfma_f32_16x16x32_bf16 v[2:5], v[176:179], v[212:215], v[2:5]
	v_mfma_f32_16x16x32_bf16 v[10:13], v[168:171], v[212:215], v[10:13]
	v_mfma_f32_16x16x32_bf16 v[10:13], v[164:167], v[208:211], v[10:13]
	s_setprio 0
	s_barrier
	s_add_u32 s36, s36, 0x100
	s_addc_u32 s37, s37, 0
	s_add_u32 s59, s59, 0x100
	s_addc_u32 s60, s60, 0
	s_cmp_ge_i32 s61, s35
	s_mov_b32 s2, s61
	s_cbranch_scc0 .LBB0_800

.LBB0_959:
	s_lshl_b32 s0, s16, 20
	s_and_b32 s0, s0, 0xff00000
	v_readlane_b32 s12, v248, 20
	v_readlane_b32 s13, v248, 21
	s_add_u32 s0, s12, s0
	s_addc_u32 s1, s13, 0
	s_lshr_b32 s12, s16, 13
	s_and_b32 s12, s12, 0x7ff80
	s_add_u32 s0, s0, s12
	s_addc_u32 s1, s1, 0
	s_lshl_b32 s13, s16, 12
	s_and_b32 s13, s13, 0xff00000
	v_readlane_b32 s24, v248, 51
	s_add_u32 s13, s24, s13
	v_readlane_b32 s24, v248, 53
	s_addc_u32 s24, s24, 0
	s_add_u32 s12, s13, s12
	s_addc_u32 s13, s24, 0
	s_cmp_lt_i32 s19, 1
	v_cmp_gt_i64_e64 s[16:17], s[16:17], -1
	s_cbranch_scc1 .LBB0_976
	s_and_b64 s[36:37], s[16:17], exec
	s_cselect_b32 s24, s1, s35
	s_cselect_b32 s53, s0, s34
	s_cselect_b32 s56, s13, s3
	s_cselect_b32 s57, s12, s2
	s_add_i32 s58, s19, -2
	s_add_u32 s34, s34, 0x80080
	s_addc_u32 s35, s35, 0
	s_add_u32 s59, s2, 0x100
	s_addc_u32 s60, s3, 0
	s_mov_b32 s2, 0
	s_add_i32 s61, s2, 2
	s_add_u32 s3, s34, 0xfff80080
	s_addc_u32 s36, s35, -1
	s_add_i32 s64, 0, 0x10000
	s_cmp_eq_u32 s58, s2
	s_cselect_b32 s37, s24, s36
	s_cselect_b32 s36, s53, s3
	v_add_u32_e32 v142, s64, v131
	s_cselect_b32 s3, s56, s60
	s_cselect_b32 s2, s57, s59
	s_add_i32 s66, 0, 0x14000
	ds_read_b128 v[148:151], v142
	ds_read_b128 v[152:155], v142 offset:1024
	ds_read_b128 v[156:159], v142 offset:2048
	ds_read_b128 v[160:163], v142 offset:3072
	v_add_u32_e32 v142, s66, v131
	ds_read_b128 v[188:191], v142
	ds_read_b128 v[192:195], v142 offset:1024
	ds_read_b128 v[196:199], v142 offset:2048
	ds_read_b128 v[200:203], v142 offset:3072
	v_lshl_add_u64 v[236:237], s[34:35], 0, v[144:145]
	s_add_i32 m0, s40, 0xc000
	ds_read_b128 v[204:207], v186
	ds_read_b128 v[208:211], v186 offset:1024
	ds_read_b128 v[212:215], v186 offset:2048
	ds_read_b128 v[216:219], v186 offset:3072
	ds_read_b128 v[220:223], v186 offset:4096
	ds_read_b128 v[224:227], v186 offset:5120
	ds_read_b128 v[228:231], v186 offset:6144
	ds_read_b128 v[232:235], v186 offset:7168
	global_load_lds_dwordx4 v[236:237], off
	v_lshl_add_u64 v[236:237], s[34:35], 0, v[146:147]
	s_add_i32 m0, s40, 0xe000
	s_nop 0
	global_load_lds_dwordx4 v[236:237], off
	s_waitcnt vmcnt(8)
	s_waitcnt lgkmcnt(0)
	s_barrier
	s_setprio 1
	s_waitcnt lgkmcnt(0)
	v_mfma_i32_16x16x64_i8 v[126:129], v[148:151], v[204:207], 0
	v_mfma_i32_16x16x64_i8 v[126:129], v[152:155], v[208:211], v[126:129]
	v_mfma_i32_16x16x64_i8 v[122:125], v[160:163], v[208:211], 0
	v_mfma_i32_16x16x64_i8 v[122:125], v[156:159], v[204:207], v[122:125]
	v_mfma_i32_16x16x64_i8 v[114:117], v[156:159], v[212:215], 0
	v_mfma_i32_16x16x64_i8 v[114:117], v[160:163], v[216:219], v[114:117]
	v_mfma_i32_16x16x64_i8 v[118:121], v[152:155], v[216:219], 0
	v_mfma_i32_16x16x64_i8 v[118:121], v[148:151], v[212:215], v[118:121]
	v_mfma_i32_16x16x64_i8 v[110:113], v[148:151], v[220:223], 0
	v_mfma_i32_16x16x64_i8 v[110:113], v[152:155], v[224:227], v[110:113]
	v_mfma_i32_16x16x64_i8 v[106:109], v[160:163], v[224:227], 0
	v_mfma_i32_16x16x64_i8 v[106:109], v[156:159], v[220:223], v[106:109]
	v_mfma_i32_16x16x64_i8 v[98:101], v[156:159], v[228:231], 0
	v_mfma_i32_16x16x64_i8 v[98:101], v[160:163], v[232:235], v[98:101]
	v_mfma_i32_16x16x64_i8 v[102:105], v[152:155], v[232:235], 0
	v_mfma_i32_16x16x64_i8 v[102:105], v[148:151], v[228:231], v[102:105]
	s_setprio 0
	s_setprio 1
	v_mfma_i32_16x16x64_i8 v[94:97], v[188:191], v[204:207], 0
	v_mfma_i32_16x16x64_i8 v[94:97], v[192:195], v[208:211], v[94:97]
	v_mfma_i32_16x16x64_i8 v[90:93], v[200:203], v[208:211], 0
	v_mfma_i32_16x16x64_i8 v[90:93], v[196:199], v[204:207], v[90:93]
	v_mfma_i32_16x16x64_i8 v[82:85], v[196:199], v[212:215], 0
	v_mfma_i32_16x16x64_i8 v[82:85], v[200:203], v[216:219], v[82:85]
	v_mfma_i32_16x16x64_i8 v[86:89], v[192:195], v[216:219], 0
	v_mfma_i32_16x16x64_i8 v[86:89], v[188:191], v[212:215], v[86:89]
	v_mfma_i32_16x16x64_i8 v[78:81], v[188:191], v[220:223], 0
	v_mfma_i32_16x16x64_i8 v[78:81], v[192:195], v[224:227], v[78:81]
	v_mfma_i32_16x16x64_i8 v[74:77], v[200:203], v[224:227], 0
	v_mfma_i32_16x16x64_i8 v[74:77], v[196:199], v[220:223], v[74:77]
	v_mfma_i32_16x16x64_i8 v[66:69], v[196:199], v[228:231], 0
	v_mfma_i32_16x16x64_i8 v[66:69], v[200:203], v[232:235], v[66:69]
	v_mfma_i32_16x16x64_i8 v[70:73], v[192:195], v[232:235], 0
	v_mfma_i32_16x16x64_i8 v[70:73], v[188:191], v[228:231], v[70:73]
	s_setprio 0
	s_barrier
	s_add_i32 s64, s64, s39
	v_lshl_add_u64 v[236:237], s[2:3], 0, v[136:137]
	s_mov_b32 m0, s64
	ds_read_b128 v[204:207], v186 offset:16384
	ds_read_b128 v[208:211], v186 offset:17408
	ds_read_b128 v[212:215], v186 offset:18432
	ds_read_b128 v[216:219], v186 offset:19456
	ds_read_b128 v[220:223], v186 offset:20480
	ds_read_b128 v[224:227], v186 offset:21504
	ds_read_b128 v[228:231], v186 offset:22528
	ds_read_b128 v[232:235], v186 offset:23552
	global_load_lds_dwordx4 v[236:237], off
	s_add_i32 m0, s64, 0x2000
	s_add_u32 s64, s2, 0x80000
	v_lshl_add_u64 v[238:239], s[2:3], 0, v[140:141]
	s_addc_u32 s65, s3, 0
	s_add_i32 s66, s66, s39
	global_load_lds_dwordx4 v[238:239], off
	v_lshl_add_u64 v[240:241], s[64:65], 0, v[136:137]
	s_mov_b32 m0, s66
	v_lshl_add_u64 v[242:243], s[36:37], 0, v[138:139]
	global_load_lds_dwordx4 v[240:241], off
	v_lshl_add_u64 v[240:241], s[64:65], 0, v[140:141]
	s_add_i32 m0, s66, 0x2000
	s_nop 0
	global_load_lds_dwordx4 v[240:241], off
	v_lshl_add_u64 v[240:241], s[36:37], 0, v[134:135]
	s_mov_b32 m0, s40
	s_nop 0
	global_load_lds_dwordx4 v[240:241], off
	s_mov_b32 m0, s41
	s_nop 0
	global_load_lds_dwordx4 v[242:243], off
	s_waitcnt vmcnt(8)
	s_waitcnt lgkmcnt(0)
	s_barrier
	s_setprio 1
	s_waitcnt lgkmcnt(0)
	v_mfma_i32_16x16x64_i8 v[62:65], v[148:151], v[204:207], 0
	v_mfma_i32_16x16x64_i8 v[62:65], v[152:155], v[208:211], v[62:65]
	v_mfma_i32_16x16x64_i8 v[58:61], v[160:163], v[208:211], 0
	v_mfma_i32_16x16x64_i8 v[58:61], v[156:159], v[204:207], v[58:61]
	v_mfma_i32_16x16x64_i8 v[50:53], v[156:159], v[212:215], 0
	v_mfma_i32_16x16x64_i8 v[50:53], v[160:163], v[216:219], v[50:53]
	v_mfma_i32_16x16x64_i8 v[54:57], v[152:155], v[216:219], 0
	v_mfma_i32_16x16x64_i8 v[54:57], v[148:151], v[212:215], v[54:57]
	v_mfma_i32_16x16x64_i8 v[46:49], v[148:151], v[220:223], 0
	v_mfma_i32_16x16x64_i8 v[46:49], v[152:155], v[224:227], v[46:49]
	v_mfma_i32_16x16x64_i8 v[42:45], v[160:163], v[224:227], 0
	v_mfma_i32_16x16x64_i8 v[42:45], v[156:159], v[220:223], v[42:45]
	v_mfma_i32_16x16x64_i8 v[34:37], v[156:159], v[228:231], 0
	v_mfma_i32_16x16x64_i8 v[34:37], v[160:163], v[232:235], v[34:37]
	v_mfma_i32_16x16x64_i8 v[38:41], v[152:155], v[232:235], 0
	v_mfma_i32_16x16x64_i8 v[38:41], v[148:151], v[228:231], v[38:41]
	s_setprio 0
	s_setprio 1
	v_mfma_i32_16x16x64_i8 v[30:33], v[188:191], v[204:207], 0
	v_mfma_i32_16x16x64_i8 v[30:33], v[192:195], v[208:211], v[30:33]
	v_mfma_i32_16x16x64_i8 v[26:29], v[200:203], v[208:211], 0
	v_mfma_i32_16x16x64_i8 v[26:29], v[196:199], v[204:207], v[26:29]
	v_mfma_i32_16x16x64_i8 v[18:21], v[196:199], v[212:215], 0
	v_mfma_i32_16x16x64_i8 v[18:21], v[200:203], v[216:219], v[18:21]
	v_mfma_i32_16x16x64_i8 v[22:25], v[192:195], v[216:219], 0
	v_mfma_i32_16x16x64_i8 v[22:25], v[188:191], v[212:215], v[22:25]
	v_mfma_i32_16x16x64_i8 v[14:17], v[188:191], v[220:223], 0
	v_mfma_i32_16x16x64_i8 v[14:17], v[192:195], v[224:227], v[14:17]
	v_mfma_i32_16x16x64_i8 v[10:13], v[200:203], v[224:227], 0
	v_mfma_i32_16x16x64_i8 v[10:13], v[196:199], v[220:223], v[10:13]
	v_mfma_i32_16x16x64_i8 v[2:5], v[196:199], v[228:231], 0
	v_mfma_i32_16x16x64_i8 v[2:5], v[200:203], v[232:235], v[2:5]
	v_mfma_i32_16x16x64_i8 v[6:9], v[192:195], v[232:235], 0
	v_mfma_i32_16x16x64_i8 v[6:9], v[188:191], v[228:231], v[6:9]
	s_setprio 0
	s_barrier
	s_add_i32 s64, 0, 0x18000
	v_add_u32_e32 v142, s64, v131
	s_add_i32 s65, 0, 0x1c000
	ds_read_b128 v[148:151], v142
	ds_read_b128 v[152:155], v142 offset:1024
	ds_read_b128 v[156:159], v142 offset:2048
	ds_read_b128 v[160:163], v142 offset:3072
	v_add_u32_e32 v142, s65, v131
	ds_read_b128 v[188:191], v142
	ds_read_b128 v[192:195], v142 offset:1024
	ds_read_b128 v[196:199], v142 offset:2048
	ds_read_b128 v[200:203], v142 offset:3072
	s_add_u32 s36, s36, 0x80000
	s_addc_u32 s37, s37, 0
	s_mov_b32 m0, s42
	v_lshl_add_u64 v[244:245], s[36:37], 0, v[134:135]
	ds_read_b128 v[204:207], v186 offset:32768
	ds_read_b128 v[208:211], v186 offset:33792
	ds_read_b128 v[212:215], v186 offset:34816
	ds_read_b128 v[216:219], v186 offset:35840
	ds_read_b128 v[220:223], v186 offset:36864
	ds_read_b128 v[224:227], v186 offset:37888
	ds_read_b128 v[228:231], v186 offset:38912
	ds_read_b128 v[232:235], v186 offset:39936
	global_load_lds_dwordx4 v[244:245], off
	v_lshl_add_u64 v[244:245], s[36:37], 0, v[138:139]
	s_mov_b32 m0, s43
	s_nop 0
	global_load_lds_dwordx4 v[244:245], off
	s_waitcnt vmcnt(8)
	s_waitcnt lgkmcnt(0)
	s_barrier
	s_setprio 1
	s_waitcnt lgkmcnt(0)
	v_mfma_i32_16x16x64_i8 v[126:129], v[148:151], v[204:207], v[126:129]
	v_mfma_i32_16x16x64_i8 v[126:129], v[152:155], v[208:211], v[126:129]
	v_mfma_i32_16x16x64_i8 v[122:125], v[160:163], v[208:211], v[122:125]
	v_mfma_i32_16x16x64_i8 v[122:125], v[156:159], v[204:207], v[122:125]
	v_mfma_i32_16x16x64_i8 v[114:117], v[156:159], v[212:215], v[114:117]
	v_mfma_i32_16x16x64_i8 v[114:117], v[160:163], v[216:219], v[114:117]
	v_mfma_i32_16x16x64_i8 v[118:121], v[152:155], v[216:219], v[118:121]
	v_mfma_i32_16x16x64_i8 v[118:121], v[148:151], v[212:215], v[118:121]
	v_mfma_i32_16x16x64_i8 v[110:113], v[148:151], v[220:223], v[110:113]
	v_mfma_i32_16x16x64_i8 v[110:113], v[152:155], v[224:227], v[110:113]
	v_mfma_i32_16x16x64_i8 v[106:109], v[160:163], v[224:227], v[106:109]
	v_mfma_i32_16x16x64_i8 v[106:109], v[156:159], v[220:223], v[106:109]
	v_mfma_i32_16x16x64_i8 v[98:101], v[156:159], v[228:231], v[98:101]
	v_mfma_i32_16x16x64_i8 v[98:101], v[160:163], v[232:235], v[98:101]
	v_mfma_i32_16x16x64_i8 v[102:105], v[152:155], v[232:235], v[102:105]
	v_mfma_i32_16x16x64_i8 v[102:105], v[148:151], v[228:231], v[102:105]
	s_setprio 0
	s_setprio 1
	v_mfma_i32_16x16x64_i8 v[94:97], v[188:191], v[204:207], v[94:97]
	v_mfma_i32_16x16x64_i8 v[94:97], v[192:195], v[208:211], v[94:97]
	v_mfma_i32_16x16x64_i8 v[90:93], v[200:203], v[208:211], v[90:93]
	v_mfma_i32_16x16x64_i8 v[90:93], v[196:199], v[204:207], v[90:93]
	v_mfma_i32_16x16x64_i8 v[82:85], v[196:199], v[212:215], v[82:85]
	v_mfma_i32_16x16x64_i8 v[82:85], v[200:203], v[216:219], v[82:85]
	v_mfma_i32_16x16x64_i8 v[86:89], v[192:195], v[216:219], v[86:89]
	v_mfma_i32_16x16x64_i8 v[86:89], v[188:191], v[212:215], v[86:89]
	v_mfma_i32_16x16x64_i8 v[78:81], v[188:191], v[220:223], v[78:81]
	v_mfma_i32_16x16x64_i8 v[78:81], v[192:195], v[224:227], v[78:81]
	v_mfma_i32_16x16x64_i8 v[74:77], v[200:203], v[224:227], v[74:77]
	v_mfma_i32_16x16x64_i8 v[74:77], v[196:199], v[220:223], v[74:77]
	v_mfma_i32_16x16x64_i8 v[66:69], v[196:199], v[228:231], v[66:69]
	v_mfma_i32_16x16x64_i8 v[66:69], v[200:203], v[232:235], v[66:69]
	v_mfma_i32_16x16x64_i8 v[70:73], v[192:195], v[232:235], v[70:73]
	v_mfma_i32_16x16x64_i8 v[70:73], v[188:191], v[228:231], v[70:73]
	s_setprio 0
	s_barrier
	s_add_i32 s36, s64, s39
	v_lshl_add_u64 v[236:237], v[236:237], 0, s[28:29]
	s_mov_b32 m0, s36
	ds_read_b128 v[204:207], v186 offset:49152
	ds_read_b128 v[208:211], v186 offset:50176
	ds_read_b128 v[212:215], v186 offset:51200
	ds_read_b128 v[216:219], v186 offset:52224
	ds_read_b128 v[220:223], v186 offset:53248
	ds_read_b128 v[224:227], v186 offset:54272
	ds_read_b128 v[228:231], v186 offset:55296
	ds_read_b128 v[232:235], v186 offset:56320
	global_load_lds_dwordx4 v[236:237], off
	s_add_i32 m0, s36, 0x2000
	s_add_u32 s2, s2, 0x80080
	v_lshl_add_u64 v[236:237], v[238:239], 0, s[28:29]
	s_addc_u32 s3, s3, 0
	s_add_i32 s36, s65, s39
	global_load_lds_dwordx4 v[236:237], off
	v_lshl_add_u64 v[236:237], s[2:3], 0, v[136:137]
	s_mov_b32 m0, s36
	s_nop 0
	global_load_lds_dwordx4 v[236:237], off
	v_lshl_add_u64 v[236:237], s[2:3], 0, v[140:141]
	s_add_i32 m0, s36, 0x2000
	s_nop 0
	global_load_lds_dwordx4 v[236:237], off
	v_lshl_add_u64 v[236:237], v[240:241], 0, s[28:29]
	s_mov_b32 m0, s45
	s_nop 0
	global_load_lds_dwordx4 v[236:237], off
	v_lshl_add_u64 v[236:237], v[242:243], 0, s[28:29]
	s_mov_b32 m0, s52
	s_nop 0
	global_load_lds_dwordx4 v[236:237], off
	s_waitcnt vmcnt(8)
	s_waitcnt lgkmcnt(0)
	s_barrier
	s_setprio 1
	s_waitcnt lgkmcnt(0)
	v_mfma_i32_16x16x64_i8 v[62:65], v[148:151], v[204:207], v[62:65]
	v_mfma_i32_16x16x64_i8 v[62:65], v[152:155], v[208:211], v[62:65]
	v_mfma_i32_16x16x64_i8 v[58:61], v[160:163], v[208:211], v[58:61]
	v_mfma_i32_16x16x64_i8 v[58:61], v[156:159], v[204:207], v[58:61]
	v_mfma_i32_16x16x64_i8 v[50:53], v[156:159], v[212:215], v[50:53]
	v_mfma_i32_16x16x64_i8 v[50:53], v[160:163], v[216:219], v[50:53]
	v_mfma_i32_16x16x64_i8 v[54:57], v[152:155], v[216:219], v[54:57]
	v_mfma_i32_16x16x64_i8 v[54:57], v[148:151], v[212:215], v[54:57]
	v_mfma_i32_16x16x64_i8 v[46:49], v[148:151], v[220:223], v[46:49]
	v_mfma_i32_16x16x64_i8 v[46:49], v[152:155], v[224:227], v[46:49]
	v_mfma_i32_16x16x64_i8 v[42:45], v[160:163], v[224:227], v[42:45]
	v_mfma_i32_16x16x64_i8 v[42:45], v[156:159], v[220:223], v[42:45]
	v_mfma_i32_16x16x64_i8 v[34:37], v[156:159], v[228:231], v[34:37]
	v_mfma_i32_16x16x64_i8 v[34:37], v[160:163], v[232:235], v[34:37]
	v_mfma_i32_16x16x64_i8 v[38:41], v[152:155], v[232:235], v[38:41]
	v_mfma_i32_16x16x64_i8 v[38:41], v[148:151], v[228:231], v[38:41]
	s_setprio 0
	s_setprio 1
	v_mfma_i32_16x16x64_i8 v[30:33], v[188:191], v[204:207], v[30:33]
	v_mfma_i32_16x16x64_i8 v[30:33], v[192:195], v[208:211], v[30:33]
	v_mfma_i32_16x16x64_i8 v[26:29], v[200:203], v[208:211], v[26:29]
	v_mfma_i32_16x16x64_i8 v[26:29], v[196:199], v[204:207], v[26:29]
	v_mfma_i32_16x16x64_i8 v[18:21], v[196:199], v[212:215], v[18:21]
	v_mfma_i32_16x16x64_i8 v[18:21], v[200:203], v[216:219], v[18:21]
	v_mfma_i32_16x16x64_i8 v[22:25], v[192:195], v[216:219], v[22:25]
	v_mfma_i32_16x16x64_i8 v[22:25], v[188:191], v[212:215], v[22:25]
	v_mfma_i32_16x16x64_i8 v[14:17], v[188:191], v[220:223], v[14:17]
	v_mfma_i32_16x16x64_i8 v[14:17], v[192:195], v[224:227], v[14:17]
	v_mfma_i32_16x16x64_i8 v[10:13], v[200:203], v[224:227], v[10:13]
	v_mfma_i32_16x16x64_i8 v[10:13], v[196:199], v[220:223], v[10:13]
	v_mfma_i32_16x16x64_i8 v[2:5], v[196:199], v[228:231], v[2:5]
	v_mfma_i32_16x16x64_i8 v[2:5], v[200:203], v[232:235], v[2:5]
	v_mfma_i32_16x16x64_i8 v[6:9], v[192:195], v[232:235], v[6:9]
	v_mfma_i32_16x16x64_i8 v[6:9], v[188:191], v[228:231], v[6:9]
	s_setprio 0
	s_barrier
	s_add_u32 s34, s34, 0x100
	s_addc_u32 s35, s35, 0
	s_add_u32 s59, s59, 0x100
	s_addc_u32 s60, s60, 0
	s_cmp_ge_i32 s61, s19
	s_mov_b32 s2, s61
	s_cbranch_scc1 .Lkpeel_exit_5
.LBB0_961:
	s_add_i32 s61, s2, 2
	s_add_u32 s3, s34, 0xfff80080
	s_addc_u32 s36, s35, -1
	s_add_i32 s64, 0, 0x10000
	s_cmp_eq_u32 s58, s2
	s_cselect_b32 s37, s24, s36
	s_cselect_b32 s36, s53, s3
	v_add_u32_e32 v142, s64, v131
	s_cselect_b32 s3, s56, s60
	s_cselect_b32 s2, s57, s59
	s_add_i32 s66, 0, 0x14000
	ds_read_b128 v[148:151], v142
	ds_read_b128 v[152:155], v142 offset:1024
	ds_read_b128 v[156:159], v142 offset:2048
	ds_read_b128 v[160:163], v142 offset:3072
	v_add_u32_e32 v142, s66, v131
	ds_read_b128 v[188:191], v142
	ds_read_b128 v[192:195], v142 offset:1024
	ds_read_b128 v[196:199], v142 offset:2048
	ds_read_b128 v[200:203], v142 offset:3072
	v_lshl_add_u64 v[236:237], s[34:35], 0, v[144:145]
	s_add_i32 m0, s40, 0xc000
	ds_read_b128 v[204:207], v186
	ds_read_b128 v[208:211], v186 offset:1024
	ds_read_b128 v[212:215], v186 offset:2048
	ds_read_b128 v[216:219], v186 offset:3072
	ds_read_b128 v[220:223], v186 offset:4096
	ds_read_b128 v[224:227], v186 offset:5120
	ds_read_b128 v[228:231], v186 offset:6144
	ds_read_b128 v[232:235], v186 offset:7168
	global_load_lds_dwordx4 v[236:237], off
	v_lshl_add_u64 v[236:237], s[34:35], 0, v[146:147]
	s_add_i32 m0, s40, 0xe000
	s_nop 0
	global_load_lds_dwordx4 v[236:237], off
	s_waitcnt vmcnt(8)
	s_waitcnt lgkmcnt(0)
	s_barrier
	s_setprio 1
	s_waitcnt lgkmcnt(0)
	v_mfma_i32_16x16x64_i8 v[126:129], v[148:151], v[204:207], v[126:129]
	v_mfma_i32_16x16x64_i8 v[126:129], v[152:155], v[208:211], v[126:129]
	v_mfma_i32_16x16x64_i8 v[122:125], v[160:163], v[208:211], v[122:125]
	v_mfma_i32_16x16x64_i8 v[122:125], v[156:159], v[204:207], v[122:125]
	v_mfma_i32_16x16x64_i8 v[114:117], v[156:159], v[212:215], v[114:117]
	v_mfma_i32_16x16x64_i8 v[114:117], v[160:163], v[216:219], v[114:117]
	v_mfma_i32_16x16x64_i8 v[118:121], v[152:155], v[216:219], v[118:121]
	v_mfma_i32_16x16x64_i8 v[118:121], v[148:151], v[212:215], v[118:121]
	v_mfma_i32_16x16x64_i8 v[110:113], v[148:151], v[220:223], v[110:113]
	v_mfma_i32_16x16x64_i8 v[110:113], v[152:155], v[224:227], v[110:113]
	v_mfma_i32_16x16x64_i8 v[106:109], v[160:163], v[224:227], v[106:109]
	v_mfma_i32_16x16x64_i8 v[106:109], v[156:159], v[220:223], v[106:109]
	v_mfma_i32_16x16x64_i8 v[98:101], v[156:159], v[228:231], v[98:101]
	v_mfma_i32_16x16x64_i8 v[98:101], v[160:163], v[232:235], v[98:101]
	v_mfma_i32_16x16x64_i8 v[102:105], v[152:155], v[232:235], v[102:105]
	v_mfma_i32_16x16x64_i8 v[102:105], v[148:151], v[228:231], v[102:105]
	s_setprio 0
	s_setprio 1
	v_mfma_i32_16x16x64_i8 v[94:97], v[188:191], v[204:207], v[94:97]
	v_mfma_i32_16x16x64_i8 v[94:97], v[192:195], v[208:211], v[94:97]
	v_mfma_i32_16x16x64_i8 v[90:93], v[200:203], v[208:211], v[90:93]
	v_mfma_i32_16x16x64_i8 v[90:93], v[196:199], v[204:207], v[90:93]
	v_mfma_i32_16x16x64_i8 v[82:85], v[196:199], v[212:215], v[82:85]
	v_mfma_i32_16x16x64_i8 v[82:85], v[200:203], v[216:219], v[82:85]
	v_mfma_i32_16x16x64_i8 v[86:89], v[192:195], v[216:219], v[86:89]
	v_mfma_i32_16x16x64_i8 v[86:89], v[188:191], v[212:215], v[86:89]
	v_mfma_i32_16x16x64_i8 v[78:81], v[188:191], v[220:223], v[78:81]
	v_mfma_i32_16x16x64_i8 v[78:81], v[192:195], v[224:227], v[78:81]
	v_mfma_i32_16x16x64_i8 v[74:77], v[200:203], v[224:227], v[74:77]
	v_mfma_i32_16x16x64_i8 v[74:77], v[196:199], v[220:223], v[74:77]
	v_mfma_i32_16x16x64_i8 v[66:69], v[196:199], v[228:231], v[66:69]
	v_mfma_i32_16x16x64_i8 v[66:69], v[200:203], v[232:235], v[66:69]
	v_mfma_i32_16x16x64_i8 v[70:73], v[192:195], v[232:235], v[70:73]
	v_mfma_i32_16x16x64_i8 v[70:73], v[188:191], v[228:231], v[70:73]
	s_setprio 0
	s_barrier
	s_add_i32 s64, s64, s39
	v_lshl_add_u64 v[236:237], s[2:3], 0, v[136:137]
	s_mov_b32 m0, s64
	ds_read_b128 v[204:207], v186 offset:16384
	ds_read_b128 v[208:211], v186 offset:17408
	ds_read_b128 v[212:215], v186 offset:18432
	ds_read_b128 v[216:219], v186 offset:19456
	ds_read_b128 v[220:223], v186 offset:20480
	ds_read_b128 v[224:227], v186 offset:21504
	ds_read_b128 v[228:231], v186 offset:22528
	ds_read_b128 v[232:235], v186 offset:23552
	global_load_lds_dwordx4 v[236:237], off
	s_add_i32 m0, s64, 0x2000
	s_add_u32 s64, s2, 0x80000
	v_lshl_add_u64 v[238:239], s[2:3], 0, v[140:141]
	s_addc_u32 s65, s3, 0
	s_add_i32 s66, s66, s39
	global_load_lds_dwordx4 v[238:239], off
	v_lshl_add_u64 v[240:241], s[64:65], 0, v[136:137]
	s_mov_b32 m0, s66
	v_lshl_add_u64 v[242:243], s[36:37], 0, v[138:139]
	global_load_lds_dwordx4 v[240:241], off
	v_lshl_add_u64 v[240:241], s[64:65], 0, v[140:141]
	s_add_i32 m0, s66, 0x2000
	s_nop 0
	global_load_lds_dwordx4 v[240:241], off
	v_lshl_add_u64 v[240:241], s[36:37], 0, v[134:135]
	s_mov_b32 m0, s40
	s_nop 0
	global_load_lds_dwordx4 v[240:241], off
	s_mov_b32 m0, s41
	s_nop 0
	global_load_lds_dwordx4 v[242:243], off
	s_waitcnt vmcnt(8)
	s_waitcnt lgkmcnt(0)
	s_barrier
	s_setprio 1
	s_waitcnt lgkmcnt(0)
	v_mfma_i32_16x16x64_i8 v[62:65], v[148:151], v[204:207], v[62:65]
	v_mfma_i32_16x16x64_i8 v[62:65], v[152:155], v[208:211], v[62:65]
	v_mfma_i32_16x16x64_i8 v[58:61], v[160:163], v[208:211], v[58:61]
	v_mfma_i32_16x16x64_i8 v[58:61], v[156:159], v[204:207], v[58:61]
	v_mfma_i32_16x16x64_i8 v[50:53], v[156:159], v[212:215], v[50:53]
	v_mfma_i32_16x16x64_i8 v[50:53], v[160:163], v[216:219], v[50:53]
	v_mfma_i32_16x16x64_i8 v[54:57], v[152:155], v[216:219], v[54:57]
	v_mfma_i32_16x16x64_i8 v[54:57], v[148:151], v[212:215], v[54:57]
	v_mfma_i32_16x16x64_i8 v[46:49], v[148:151], v[220:223], v[46:49]
	v_mfma_i32_16x16x64_i8 v[46:49], v[152:155], v[224:227], v[46:49]
	v_mfma_i32_16x16x64_i8 v[42:45], v[160:163], v[224:227], v[42:45]
	v_mfma_i32_16x16x64_i8 v[42:45], v[156:159], v[220:223], v[42:45]
	v_mfma_i32_16x16x64_i8 v[34:37], v[156:159], v[228:231], v[34:37]
	v_mfma_i32_16x16x64_i8 v[34:37], v[160:163], v[232:235], v[34:37]
	v_mfma_i32_16x16x64_i8 v[38:41], v[152:155], v[232:235], v[38:41]
	v_mfma_i32_16x16x64_i8 v[38:41], v[148:151], v[228:231], v[38:41]
	s_setprio 0
	s_setprio 1
	v_mfma_i32_16x16x64_i8 v[30:33], v[188:191], v[204:207], v[30:33]
	v_mfma_i32_16x16x64_i8 v[30:33], v[192:195], v[208:211], v[30:33]
	v_mfma_i32_16x16x64_i8 v[26:29], v[200:203], v[208:211], v[26:29]
	v_mfma_i32_16x16x64_i8 v[26:29], v[196:199], v[204:207], v[26:29]
	v_mfma_i32_16x16x64_i8 v[18:21], v[196:199], v[212:215], v[18:21]
	v_mfma_i32_16x16x64_i8 v[18:21], v[200:203], v[216:219], v[18:21]
	v_mfma_i32_16x16x64_i8 v[22:25], v[192:195], v[216:219], v[22:25]
	v_mfma_i32_16x16x64_i8 v[22:25], v[188:191], v[212:215], v[22:25]
	v_mfma_i32_16x16x64_i8 v[14:17], v[188:191], v[220:223], v[14:17]
	v_mfma_i32_16x16x64_i8 v[14:17], v[192:195], v[224:227], v[14:17]
	v_mfma_i32_16x16x64_i8 v[10:13], v[200:203], v[224:227], v[10:13]
	v_mfma_i32_16x16x64_i8 v[10:13], v[196:199], v[220:223], v[10:13]
	v_mfma_i32_16x16x64_i8 v[2:5], v[196:199], v[228:231], v[2:5]
	v_mfma_i32_16x16x64_i8 v[2:5], v[200:203], v[232:235], v[2:5]
	v_mfma_i32_16x16x64_i8 v[6:9], v[192:195], v[232:235], v[6:9]
	v_mfma_i32_16x16x64_i8 v[6:9], v[188:191], v[228:231], v[6:9]
	s_setprio 0
	s_barrier
	s_add_i32 s64, 0, 0x18000
	v_add_u32_e32 v142, s64, v131
	s_add_i32 s65, 0, 0x1c000
	ds_read_b128 v[148:151], v142
	ds_read_b128 v[152:155], v142 offset:1024
	ds_read_b128 v[156:159], v142 offset:2048
	ds_read_b128 v[160:163], v142 offset:3072
	v_add_u32_e32 v142, s65, v131
	ds_read_b128 v[188:191], v142
	ds_read_b128 v[192:195], v142 offset:1024
	ds_read_b128 v[196:199], v142 offset:2048
	ds_read_b128 v[200:203], v142 offset:3072
	s_add_u32 s36, s36, 0x80000
	s_addc_u32 s37, s37, 0
	s_mov_b32 m0, s42
	v_lshl_add_u64 v[244:245], s[36:37], 0, v[134:135]
	ds_read_b128 v[204:207], v186 offset:32768
	ds_read_b128 v[208:211], v186 offset:33792
	ds_read_b128 v[212:215], v186 offset:34816
	ds_read_b128 v[216:219], v186 offset:35840
	ds_read_b128 v[220:223], v186 offset:36864
	ds_read_b128 v[224:227], v186 offset:37888
	ds_read_b128 v[228:231], v186 offset:38912
	ds_read_b128 v[232:235], v186 offset:39936
	global_load_lds_dwordx4 v[244:245], off
	v_lshl_add_u64 v[244:245], s[36:37], 0, v[138:139]
	s_mov_b32 m0, s43
	s_nop 0
	global_load_lds_dwordx4 v[244:245], off
	s_waitcnt vmcnt(8)
	s_waitcnt lgkmcnt(0)
	s_barrier
	s_setprio 1
	s_waitcnt lgkmcnt(0)
	v_mfma_i32_16x16x64_i8 v[126:129], v[148:151], v[204:207], v[126:129]
	v_mfma_i32_16x16x64_i8 v[126:129], v[152:155], v[208:211], v[126:129]
	v_mfma_i32_16x16x64_i8 v[122:125], v[160:163], v[208:211], v[122:125]
	v_mfma_i32_16x16x64_i8 v[122:125], v[156:159], v[204:207], v[122:125]
	v_mfma_i32_16x16x64_i8 v[114:117], v[156:159], v[212:215], v[114:117]
	v_mfma_i32_16x16x64_i8 v[114:117], v[160:163], v[216:219], v[114:117]
	v_mfma_i32_16x16x64_i8 v[118:121], v[152:155], v[216:219], v[118:121]
	v_mfma_i32_16x16x64_i8 v[118:121], v[148:151], v[212:215], v[118:121]
	v_mfma_i32_16x16x64_i8 v[110:113], v[148:151], v[220:223], v[110:113]
	v_mfma_i32_16x16x64_i8 v[110:113], v[152:155], v[224:227], v[110:113]
	v_mfma_i32_16x16x64_i8 v[106:109], v[160:163], v[224:227], v[106:109]
	v_mfma_i32_16x16x64_i8 v[106:109], v[156:159], v[220:223], v[106:109]
	v_mfma_i32_16x16x64_i8 v[98:101], v[156:159], v[228:231], v[98:101]
	v_mfma_i32_16x16x64_i8 v[98:101], v[160:163], v[232:235], v[98:101]
	v_mfma_i32_16x16x64_i8 v[102:105], v[152:155], v[232:235], v[102:105]
	v_mfma_i32_16x16x64_i8 v[102:105], v[148:151], v[228:231], v[102:105]
	s_setprio 0
	s_setprio 1
	v_mfma_i32_16x16x64_i8 v[94:97], v[188:191], v[204:207], v[94:97]
	v_mfma_i32_16x16x64_i8 v[94:97], v[192:195], v[208:211], v[94:97]
	v_mfma_i32_16x16x64_i8 v[90:93], v[200:203], v[208:211], v[90:93]
	v_mfma_i32_16x16x64_i8 v[90:93], v[196:199], v[204:207], v[90:93]
	v_mfma_i32_16x16x64_i8 v[82:85], v[196:199], v[212:215], v[82:85]
	v_mfma_i32_16x16x64_i8 v[82:85], v[200:203], v[216:219], v[82:85]
	v_mfma_i32_16x16x64_i8 v[86:89], v[192:195], v[216:219], v[86:89]
	v_mfma_i32_16x16x64_i8 v[86:89], v[188:191], v[212:215], v[86:89]
	v_mfma_i32_16x16x64_i8 v[78:81], v[188:191], v[220:223], v[78:81]
	v_mfma_i32_16x16x64_i8 v[78:81], v[192:195], v[224:227], v[78:81]
	v_mfma_i32_16x16x64_i8 v[74:77], v[200:203], v[224:227], v[74:77]
	v_mfma_i32_16x16x64_i8 v[74:77], v[196:199], v[220:223], v[74:77]
	v_mfma_i32_16x16x64_i8 v[66:69], v[196:199], v[228:231], v[66:69]
	v_mfma_i32_16x16x64_i8 v[66:69], v[200:203], v[232:235], v[66:69]
	v_mfma_i32_16x16x64_i8 v[70:73], v[192:195], v[232:235], v[70:73]
	v_mfma_i32_16x16x64_i8 v[70:73], v[188:191], v[228:231], v[70:73]
	s_setprio 0
	s_barrier
	s_add_i32 s36, s64, s39
	v_lshl_add_u64 v[236:237], v[236:237], 0, s[28:29]
	s_mov_b32 m0, s36
	ds_read_b128 v[204:207], v186 offset:49152
	ds_read_b128 v[208:211], v186 offset:50176
	ds_read_b128 v[212:215], v186 offset:51200
	ds_read_b128 v[216:219], v186 offset:52224
	ds_read_b128 v[220:223], v186 offset:53248
	ds_read_b128 v[224:227], v186 offset:54272
	ds_read_b128 v[228:231], v186 offset:55296
	ds_read_b128 v[232:235], v186 offset:56320
	global_load_lds_dwordx4 v[236:237], off
	s_add_i32 m0, s36, 0x2000
	s_add_u32 s2, s2, 0x80080
	v_lshl_add_u64 v[236:237], v[238:239], 0, s[28:29]
	s_addc_u32 s3, s3, 0
	s_add_i32 s36, s65, s39
	global_load_lds_dwordx4 v[236:237], off
	v_lshl_add_u64 v[236:237], s[2:3], 0, v[136:137]
	s_mov_b32 m0, s36
	s_nop 0
	global_load_lds_dwordx4 v[236:237], off
	v_lshl_add_u64 v[236:237], s[2:3], 0, v[140:141]
	s_add_i32 m0, s36, 0x2000
	s_nop 0
	global_load_lds_dwordx4 v[236:237], off
	v_lshl_add_u64 v[236:237], v[240:241], 0, s[28:29]
	s_mov_b32 m0, s45
	s_nop 0
	global_load_lds_dwordx4 v[236:237], off
	v_lshl_add_u64 v[236:237], v[242:243], 0, s[28:29]
	s_mov_b32 m0, s52
	s_nop 0
	global_load_lds_dwordx4 v[236:237], off
	s_waitcnt vmcnt(8)
	s_waitcnt lgkmcnt(0)
	s_barrier
	s_setprio 1
	s_waitcnt lgkmcnt(0)
	v_mfma_i32_16x16x64_i8 v[62:65], v[148:151], v[204:207], v[62:65]
	v_mfma_i32_16x16x64_i8 v[62:65], v[152:155], v[208:211], v[62:65]
	v_mfma_i32_16x16x64_i8 v[58:61], v[160:163], v[208:211], v[58:61]
	v_mfma_i32_16x16x64_i8 v[58:61], v[156:159], v[204:207], v[58:61]
	v_mfma_i32_16x16x64_i8 v[50:53], v[156:159], v[212:215], v[50:53]
	v_mfma_i32_16x16x64_i8 v[50:53], v[160:163], v[216:219], v[50:53]
	v_mfma_i32_16x16x64_i8 v[54:57], v[152:155], v[216:219], v[54:57]
	v_mfma_i32_16x16x64_i8 v[54:57], v[148:151], v[212:215], v[54:57]
	v_mfma_i32_16x16x64_i8 v[46:49], v[148:151], v[220:223], v[46:49]
	v_mfma_i32_16x16x64_i8 v[46:49], v[152:155], v[224:227], v[46:49]
	v_mfma_i32_16x16x64_i8 v[42:45], v[160:163], v[224:227], v[42:45]
	v_mfma_i32_16x16x64_i8 v[42:45], v[156:159], v[220:223], v[42:45]
	v_mfma_i32_16x16x64_i8 v[34:37], v[156:159], v[228:231], v[34:37]
	v_mfma_i32_16x16x64_i8 v[34:37], v[160:163], v[232:235], v[34:37]
	v_mfma_i32_16x16x64_i8 v[38:41], v[152:155], v[232:235], v[38:41]
	v_mfma_i32_16x16x64_i8 v[38:41], v[148:151], v[228:231], v[38:41]
	s_setprio 0
	s_setprio 1
	v_mfma_i32_16x16x64_i8 v[30:33], v[188:191], v[204:207], v[30:33]
	v_mfma_i32_16x16x64_i8 v[30:33], v[192:195], v[208:211], v[30:33]
	v_mfma_i32_16x16x64_i8 v[26:29], v[200:203], v[208:211], v[26:29]
	v_mfma_i32_16x16x64_i8 v[26:29], v[196:199], v[204:207], v[26:29]
	v_mfma_i32_16x16x64_i8 v[18:21], v[196:199], v[212:215], v[18:21]
	v_mfma_i32_16x16x64_i8 v[18:21], v[200:203], v[216:219], v[18:21]
	v_mfma_i32_16x16x64_i8 v[22:25], v[192:195], v[216:219], v[22:25]
	v_mfma_i32_16x16x64_i8 v[22:25], v[188:191], v[212:215], v[22:25]
	v_mfma_i32_16x16x64_i8 v[14:17], v[188:191], v[220:223], v[14:17]
	v_mfma_i32_16x16x64_i8 v[14:17], v[192:195], v[224:227], v[14:17]
	v_mfma_i32_16x16x64_i8 v[10:13], v[200:203], v[224:227], v[10:13]
	v_mfma_i32_16x16x64_i8 v[10:13], v[196:199], v[220:223], v[10:13]
	v_mfma_i32_16x16x64_i8 v[2:5], v[196:199], v[228:231], v[2:5]
	v_mfma_i32_16x16x64_i8 v[2:5], v[200:203], v[232:235], v[2:5]
	v_mfma_i32_16x16x64_i8 v[6:9], v[192:195], v[232:235], v[6:9]
	v_mfma_i32_16x16x64_i8 v[6:9], v[188:191], v[228:231], v[6:9]
	s_setprio 0
	s_barrier
	s_add_u32 s34, s34, 0x100
	s_addc_u32 s35, s35, 0
	s_add_u32 s59, s59, 0x100
	s_addc_u32 s60, s60, 0
	s_cmp_ge_i32 s61, s19
	s_mov_b32 s2, s61
	s_cbranch_scc0 .LBB0_961

.LBB0_1126:
	s_cmp_lt_i32 s29, 1
	s_cbranch_scc1 .LBB0_1148
	s_add_i32 s18, s29, -2
	s_add_u32 s30, s30, 0x2b0080
	s_addc_u32 s31, s31, 0
	s_add_u32 s28, s2, 0x100
	s_addc_u32 s52, s3, 0
	s_mov_b32 s2, 0
	ds_read_b128 v[148:151], v145
	ds_read_b128 v[152:155], v145 offset:1024
	ds_read_b128 v[156:159], v145 offset:2048
	ds_read_b128 v[160:163], v145 offset:3072
	ds_read_b128 v[164:167], v146
	ds_read_b128 v[170:173], v146 offset:1024
	ds_read_b128 v[174:177], v146 offset:2048
	ds_read_b128 v[178:181], v146 offset:3072
	s_add_i32 s53, s2, 2
	s_add_u32 s3, s30, 0xffd50080
	s_addc_u32 s34, s31, -1
	s_cmp_eq_u32 s18, s2
	s_cselect_b32 s2, s26, s28
	s_cselect_b32 s35, s25, s34
	s_cselect_b32 s34, s24, s3
	s_cselect_b32 s3, s27, s52
	v_lshl_add_u64 v[214:215], s[30:31], 0, v[140:141]
	s_add_i32 m0, s37, 0xc000
	ds_read_b128 v[182:185], v147
	ds_read_b128 v[186:189], v147 offset:1024
	ds_read_b128 v[190:193], v147 offset:2048
	ds_read_b128 v[194:197], v147 offset:3072
	ds_read_b128 v[198:201], v147 offset:4096
	ds_read_b128 v[202:205], v147 offset:5120
	ds_read_b128 v[206:209], v147 offset:6144
	ds_read_b128 v[210:213], v147 offset:7168
	global_load_lds_dwordx4 v[214:215], off
	v_lshl_add_u64 v[214:215], s[30:31], 0, v[142:143]
	s_add_i32 m0, s37, 0xe000
	s_nop 0
	global_load_lds_dwordx4 v[214:215], off
	s_waitcnt vmcnt(8)
	s_waitcnt lgkmcnt(0)
	s_barrier
	s_setprio 1
	s_waitcnt lgkmcnt(0)
	v_mfma_f32_16x16x32_bf16 v[124:127], v[148:151], v[182:185], 0
	v_mfma_f32_16x16x32_bf16 v[124:127], v[152:155], v[186:189], v[124:127]
	v_mfma_f32_16x16x32_bf16 v[120:123], v[160:163], v[186:189], 0
	v_mfma_f32_16x16x32_bf16 v[120:123], v[156:159], v[182:185], v[120:123]
	v_mfma_f32_16x16x32_bf16 v[100:103], v[156:159], v[190:193], 0
	v_mfma_f32_16x16x32_bf16 v[100:103], v[160:163], v[194:197], v[100:103]
	v_mfma_f32_16x16x32_bf16 v[108:111], v[152:155], v[194:197], 0
	v_mfma_f32_16x16x32_bf16 v[108:111], v[148:151], v[190:193], v[108:111]
	v_mfma_f32_16x16x32_bf16 v[92:95], v[148:151], v[198:201], 0
	v_mfma_f32_16x16x32_bf16 v[92:95], v[152:155], v[202:205], v[92:95]
	v_mfma_f32_16x16x32_bf16 v[84:87], v[160:163], v[202:205], 0
	v_mfma_f32_16x16x32_bf16 v[84:87], v[156:159], v[198:201], v[84:87]
	v_mfma_f32_16x16x32_bf16 v[68:71], v[156:159], v[206:209], 0
	v_mfma_f32_16x16x32_bf16 v[68:71], v[160:163], v[210:213], v[68:71]
	v_mfma_f32_16x16x32_bf16 v[76:79], v[152:155], v[210:213], 0
	v_mfma_f32_16x16x32_bf16 v[76:79], v[148:151], v[206:209], v[76:79]
	s_setprio 0
	s_setprio 1
	v_mfma_f32_16x16x32_bf16 v[116:119], v[164:167], v[182:185], 0
	v_mfma_f32_16x16x32_bf16 v[116:119], v[170:173], v[186:189], v[116:119]
	v_mfma_f32_16x16x32_bf16 v[112:115], v[178:181], v[186:189], 0
	v_mfma_f32_16x16x32_bf16 v[112:115], v[174:177], v[182:185], v[112:115]
	v_mfma_f32_16x16x32_bf16 v[96:99], v[174:177], v[190:193], 0
	v_mfma_f32_16x16x32_bf16 v[96:99], v[178:181], v[194:197], v[96:99]
	v_mfma_f32_16x16x32_bf16 v[104:107], v[170:173], v[194:197], 0
	v_mfma_f32_16x16x32_bf16 v[104:107], v[164:167], v[190:193], v[104:107]
	v_mfma_f32_16x16x32_bf16 v[88:91], v[164:167], v[198:201], 0
	v_mfma_f32_16x16x32_bf16 v[88:91], v[170:173], v[202:205], v[88:91]
	v_mfma_f32_16x16x32_bf16 v[80:83], v[178:181], v[202:205], 0
	v_mfma_f32_16x16x32_bf16 v[80:83], v[174:177], v[198:201], v[80:83]
	v_mfma_f32_16x16x32_bf16 v[64:67], v[174:177], v[206:209], 0
	v_mfma_f32_16x16x32_bf16 v[64:67], v[178:181], v[210:213], v[64:67]
	v_mfma_f32_16x16x32_bf16 v[72:75], v[170:173], v[210:213], 0
	v_mfma_f32_16x16x32_bf16 v[72:75], v[164:167], v[206:209], v[72:75]
	s_setprio 0
	s_barrier
	s_add_i32 s56, s46, s33
	v_lshl_add_u64 v[214:215], s[2:3], 0, v[134:135]
	s_mov_b32 m0, s56
	ds_read_b128 v[182:185], v147 offset:16384
	ds_read_b128 v[186:189], v147 offset:17408
	ds_read_b128 v[190:193], v147 offset:18432
	ds_read_b128 v[194:197], v147 offset:19456
	ds_read_b128 v[198:201], v147 offset:20480
	ds_read_b128 v[202:205], v147 offset:21504
	ds_read_b128 v[206:209], v147 offset:22528
	ds_read_b128 v[210:213], v147 offset:23552
	global_load_lds_dwordx4 v[214:215], off
	s_add_i32 m0, s56, 0x2000
	s_add_u32 s56, s2, 0x2b0000
	v_lshl_add_u64 v[216:217], s[2:3], 0, v[138:139]
	s_addc_u32 s57, s3, 0
	s_add_i32 s58, s47, s33
	global_load_lds_dwordx4 v[216:217], off
	v_lshl_add_u64 v[218:219], s[56:57], 0, v[134:135]
	s_mov_b32 m0, s58
	v_lshl_add_u64 v[220:221], s[34:35], 0, v[136:137]
	global_load_lds_dwordx4 v[218:219], off
	v_lshl_add_u64 v[218:219], s[56:57], 0, v[138:139]
	s_add_i32 m0, s58, 0x2000
	s_nop 0
	global_load_lds_dwordx4 v[218:219], off
	v_lshl_add_u64 v[218:219], s[34:35], 0, v[128:129]
	s_mov_b32 m0, s37
	s_nop 0
	global_load_lds_dwordx4 v[218:219], off
	s_mov_b32 m0, s38
	s_nop 0
	global_load_lds_dwordx4 v[220:221], off
	s_waitcnt vmcnt(8)
	s_waitcnt lgkmcnt(0)
	s_barrier
	s_setprio 1
	s_waitcnt lgkmcnt(0)
	v_mfma_f32_16x16x32_bf16 v[60:63], v[148:151], v[182:185], 0
	v_mfma_f32_16x16x32_bf16 v[60:63], v[152:155], v[186:189], v[60:63]
	v_mfma_f32_16x16x32_bf16 v[52:55], v[160:163], v[186:189], 0
	v_mfma_f32_16x16x32_bf16 v[52:55], v[156:159], v[182:185], v[52:55]
	v_mfma_f32_16x16x32_bf16 v[36:39], v[156:159], v[190:193], 0
	v_mfma_f32_16x16x32_bf16 v[36:39], v[160:163], v[194:197], v[36:39]
	v_mfma_f32_16x16x32_bf16 v[44:47], v[152:155], v[194:197], 0
	v_mfma_f32_16x16x32_bf16 v[44:47], v[148:151], v[190:193], v[44:47]
	v_mfma_f32_16x16x32_bf16 v[28:31], v[148:151], v[198:201], 0
	v_mfma_f32_16x16x32_bf16 v[28:31], v[152:155], v[202:205], v[28:31]
	v_mfma_f32_16x16x32_bf16 v[20:23], v[160:163], v[202:205], 0
	v_mfma_f32_16x16x32_bf16 v[20:23], v[156:159], v[198:201], v[20:23]
	v_mfma_f32_16x16x32_bf16 v[4:7], v[156:159], v[206:209], 0
	v_mfma_f32_16x16x32_bf16 v[4:7], v[160:163], v[210:213], v[4:7]
	v_mfma_f32_16x16x32_bf16 v[12:15], v[152:155], v[210:213], 0
	v_mfma_f32_16x16x32_bf16 v[12:15], v[148:151], v[206:209], v[12:15]
	s_setprio 0
	s_setprio 1
	v_mfma_f32_16x16x32_bf16 v[56:59], v[164:167], v[182:185], 0
	v_mfma_f32_16x16x32_bf16 v[56:59], v[170:173], v[186:189], v[56:59]
	v_mfma_f32_16x16x32_bf16 v[48:51], v[178:181], v[186:189], 0
	v_mfma_f32_16x16x32_bf16 v[48:51], v[174:177], v[182:185], v[48:51]
	v_mfma_f32_16x16x32_bf16 v[32:35], v[174:177], v[190:193], 0
	v_mfma_f32_16x16x32_bf16 v[32:35], v[178:181], v[194:197], v[32:35]
	v_mfma_f32_16x16x32_bf16 v[40:43], v[170:173], v[194:197], 0
	v_mfma_f32_16x16x32_bf16 v[40:43], v[164:167], v[190:193], v[40:43]
	v_mfma_f32_16x16x32_bf16 v[24:27], v[164:167], v[198:201], 0
	v_mfma_f32_16x16x32_bf16 v[24:27], v[170:173], v[202:205], v[24:27]
	v_mfma_f32_16x16x32_bf16 v[16:19], v[178:181], v[202:205], 0
	v_mfma_f32_16x16x32_bf16 v[16:19], v[174:177], v[198:201], v[16:19]
	v_mfma_f32_16x16x32_bf16 v[0:3], v[174:177], v[206:209], 0
	v_mfma_f32_16x16x32_bf16 v[0:3], v[178:181], v[210:213], v[0:3]
	v_mfma_f32_16x16x32_bf16 v[8:11], v[170:173], v[210:213], 0
	v_mfma_f32_16x16x32_bf16 v[8:11], v[164:167], v[206:209], v[8:11]
	s_setprio 0
	s_barrier
	s_add_i32 s56, 0, 0x18000
	s_add_i32 s57, 0, 0x1c000
	v_add_u32_e32 v160, s56, v133
	v_add_u32_e32 v168, s57, v133
	ds_read_b128 v[148:151], v160
	ds_read_b128 v[152:155], v160 offset:1024
	ds_read_b128 v[156:159], v160 offset:2048
	ds_read_b128 v[160:163], v160 offset:3072
	ds_read_b128 v[164:167], v168
	ds_read_b128 v[170:173], v168 offset:1024
	ds_read_b128 v[174:177], v168 offset:2048
	ds_read_b128 v[178:181], v168 offset:3072
	s_add_u32 s34, s34, 0x2b0000
	s_addc_u32 s35, s35, 0
	s_mov_b32 m0, s39
	v_lshl_add_u64 v[222:223], s[34:35], 0, v[128:129]
	ds_read_b128 v[182:185], v147 offset:32768
	ds_read_b128 v[186:189], v147 offset:33792
	ds_read_b128 v[190:193], v147 offset:34816
	ds_read_b128 v[194:197], v147 offset:35840
	ds_read_b128 v[198:201], v147 offset:36864
	ds_read_b128 v[202:205], v147 offset:37888
	ds_read_b128 v[206:209], v147 offset:38912
	ds_read_b128 v[210:213], v147 offset:39936
	global_load_lds_dwordx4 v[222:223], off
	v_lshl_add_u64 v[222:223], s[34:35], 0, v[136:137]
	s_mov_b32 m0, s40
	s_nop 0
	global_load_lds_dwordx4 v[222:223], off
	s_waitcnt vmcnt(8)
	s_waitcnt lgkmcnt(0)
	s_barrier
	s_setprio 1
	s_waitcnt lgkmcnt(0)
	v_mfma_f32_16x16x32_bf16 v[124:127], v[148:151], v[182:185], v[124:127]
	v_mfma_f32_16x16x32_bf16 v[124:127], v[152:155], v[186:189], v[124:127]
	v_mfma_f32_16x16x32_bf16 v[120:123], v[160:163], v[186:189], v[120:123]
	v_mfma_f32_16x16x32_bf16 v[120:123], v[156:159], v[182:185], v[120:123]
	v_mfma_f32_16x16x32_bf16 v[100:103], v[156:159], v[190:193], v[100:103]
	v_mfma_f32_16x16x32_bf16 v[100:103], v[160:163], v[194:197], v[100:103]
	v_mfma_f32_16x16x32_bf16 v[108:111], v[152:155], v[194:197], v[108:111]
	v_mfma_f32_16x16x32_bf16 v[108:111], v[148:151], v[190:193], v[108:111]
	v_mfma_f32_16x16x32_bf16 v[92:95], v[148:151], v[198:201], v[92:95]
	v_mfma_f32_16x16x32_bf16 v[92:95], v[152:155], v[202:205], v[92:95]
	v_mfma_f32_16x16x32_bf16 v[84:87], v[160:163], v[202:205], v[84:87]
	v_mfma_f32_16x16x32_bf16 v[84:87], v[156:159], v[198:201], v[84:87]
	v_mfma_f32_16x16x32_bf16 v[68:71], v[156:159], v[206:209], v[68:71]
	v_mfma_f32_16x16x32_bf16 v[68:71], v[160:163], v[210:213], v[68:71]
	v_mfma_f32_16x16x32_bf16 v[76:79], v[152:155], v[210:213], v[76:79]
	v_mfma_f32_16x16x32_bf16 v[76:79], v[148:151], v[206:209], v[76:79]
	s_setprio 0
	s_setprio 1
	v_mfma_f32_16x16x32_bf16 v[116:119], v[164:167], v[182:185], v[116:119]
	v_mfma_f32_16x16x32_bf16 v[116:119], v[170:173], v[186:189], v[116:119]
	v_mfma_f32_16x16x32_bf16 v[112:115], v[178:181], v[186:189], v[112:115]
	v_mfma_f32_16x16x32_bf16 v[112:115], v[174:177], v[182:185], v[112:115]
	v_mfma_f32_16x16x32_bf16 v[96:99], v[174:177], v[190:193], v[96:99]
	v_mfma_f32_16x16x32_bf16 v[96:99], v[178:181], v[194:197], v[96:99]
	v_mfma_f32_16x16x32_bf16 v[104:107], v[170:173], v[194:197], v[104:107]
	v_mfma_f32_16x16x32_bf16 v[104:107], v[164:167], v[190:193], v[104:107]
	v_mfma_f32_16x16x32_bf16 v[88:91], v[164:167], v[198:201], v[88:91]
	v_mfma_f32_16x16x32_bf16 v[88:91], v[170:173], v[202:205], v[88:91]
	v_mfma_f32_16x16x32_bf16 v[80:83], v[178:181], v[202:205], v[80:83]
	v_mfma_f32_16x16x32_bf16 v[80:83], v[174:177], v[198:201], v[80:83]
	v_mfma_f32_16x16x32_bf16 v[64:67], v[174:177], v[206:209], v[64:67]
	v_mfma_f32_16x16x32_bf16 v[64:67], v[178:181], v[210:213], v[64:67]
	v_mfma_f32_16x16x32_bf16 v[72:75], v[170:173], v[210:213], v[72:75]
	v_mfma_f32_16x16x32_bf16 v[72:75], v[164:167], v[206:209], v[72:75]
	s_setprio 0
	s_barrier
	s_add_i32 s34, s56, s33
	v_lshl_add_u64 v[214:215], v[214:215], 0, s[6:7]
	s_mov_b32 m0, s34
	ds_read_b128 v[182:185], v147 offset:49152
	ds_read_b128 v[186:189], v147 offset:50176
	ds_read_b128 v[190:193], v147 offset:51200
	ds_read_b128 v[194:197], v147 offset:52224
	ds_read_b128 v[198:201], v147 offset:53248
	ds_read_b128 v[202:205], v147 offset:54272
	ds_read_b128 v[206:209], v147 offset:55296
	ds_read_b128 v[210:213], v147 offset:56320
	global_load_lds_dwordx4 v[214:215], off
	s_add_i32 m0, s34, 0x2000
	s_add_u32 s2, s2, 0x2b0080
	v_lshl_add_u64 v[214:215], v[216:217], 0, s[6:7]
	s_addc_u32 s3, s3, 0
	s_add_i32 s34, s57, s33
	global_load_lds_dwordx4 v[214:215], off
	v_lshl_add_u64 v[214:215], s[2:3], 0, v[134:135]
	s_mov_b32 m0, s34
	s_nop 0
	global_load_lds_dwordx4 v[214:215], off
	v_lshl_add_u64 v[214:215], s[2:3], 0, v[138:139]
	s_add_i32 m0, s34, 0x2000
	s_nop 0
	global_load_lds_dwordx4 v[214:215], off
	v_lshl_add_u64 v[214:215], v[218:219], 0, s[6:7]
	s_mov_b32 m0, s42
	s_nop 0
	global_load_lds_dwordx4 v[214:215], off
	v_lshl_add_u64 v[214:215], v[220:221], 0, s[6:7]
	s_mov_b32 m0, s43
	s_nop 0
	global_load_lds_dwordx4 v[214:215], off
	s_waitcnt vmcnt(8)
	s_waitcnt lgkmcnt(0)
	s_barrier
	s_setprio 1
	s_waitcnt lgkmcnt(0)
	v_mfma_f32_16x16x32_bf16 v[60:63], v[148:151], v[182:185], v[60:63]
	v_mfma_f32_16x16x32_bf16 v[60:63], v[152:155], v[186:189], v[60:63]
	v_mfma_f32_16x16x32_bf16 v[52:55], v[160:163], v[186:189], v[52:55]
	v_mfma_f32_16x16x32_bf16 v[52:55], v[156:159], v[182:185], v[52:55]
	v_mfma_f32_16x16x32_bf16 v[36:39], v[156:159], v[190:193], v[36:39]
	v_mfma_f32_16x16x32_bf16 v[36:39], v[160:163], v[194:197], v[36:39]
	v_mfma_f32_16x16x32_bf16 v[44:47], v[152:155], v[194:197], v[44:47]
	v_mfma_f32_16x16x32_bf16 v[44:47], v[148:151], v[190:193], v[44:47]
	v_mfma_f32_16x16x32_bf16 v[28:31], v[148:151], v[198:201], v[28:31]
	v_mfma_f32_16x16x32_bf16 v[28:31], v[152:155], v[202:205], v[28:31]
	v_mfma_f32_16x16x32_bf16 v[20:23], v[160:163], v[202:205], v[20:23]
	v_mfma_f32_16x16x32_bf16 v[20:23], v[156:159], v[198:201], v[20:23]
	v_mfma_f32_16x16x32_bf16 v[4:7], v[156:159], v[206:209], v[4:7]
	v_mfma_f32_16x16x32_bf16 v[4:7], v[160:163], v[210:213], v[4:7]
	v_mfma_f32_16x16x32_bf16 v[12:15], v[152:155], v[210:213], v[12:15]
	v_mfma_f32_16x16x32_bf16 v[12:15], v[148:151], v[206:209], v[12:15]
	s_setprio 0
	s_setprio 1
	v_mfma_f32_16x16x32_bf16 v[56:59], v[164:167], v[182:185], v[56:59]
	v_mfma_f32_16x16x32_bf16 v[56:59], v[170:173], v[186:189], v[56:59]
	v_mfma_f32_16x16x32_bf16 v[48:51], v[178:181], v[186:189], v[48:51]
	v_mfma_f32_16x16x32_bf16 v[48:51], v[174:177], v[182:185], v[48:51]
	v_mfma_f32_16x16x32_bf16 v[32:35], v[174:177], v[190:193], v[32:35]
	v_mfma_f32_16x16x32_bf16 v[32:35], v[178:181], v[194:197], v[32:35]
	v_mfma_f32_16x16x32_bf16 v[40:43], v[170:173], v[194:197], v[40:43]
	v_mfma_f32_16x16x32_bf16 v[40:43], v[164:167], v[190:193], v[40:43]
	v_mfma_f32_16x16x32_bf16 v[24:27], v[164:167], v[198:201], v[24:27]
	v_mfma_f32_16x16x32_bf16 v[24:27], v[170:173], v[202:205], v[24:27]
	v_mfma_f32_16x16x32_bf16 v[16:19], v[178:181], v[202:205], v[16:19]
	v_mfma_f32_16x16x32_bf16 v[16:19], v[174:177], v[198:201], v[16:19]
	v_mfma_f32_16x16x32_bf16 v[0:3], v[174:177], v[206:209], v[0:3]
	v_mfma_f32_16x16x32_bf16 v[0:3], v[178:181], v[210:213], v[0:3]
	v_mfma_f32_16x16x32_bf16 v[8:11], v[170:173], v[210:213], v[8:11]
	v_mfma_f32_16x16x32_bf16 v[8:11], v[164:167], v[206:209], v[8:11]
	s_setprio 0
	s_barrier
	s_add_u32 s30, s30, 0x100
	s_addc_u32 s31, s31, 0
	s_add_u32 s28, s28, 0x100
	s_addc_u32 s52, s52, 0
	s_cmp_ge_i32 s53, s29
	s_mov_b32 s2, s53
	s_cbranch_scc1 .Lkpeel_exit_6
.LBB0_1128:
	ds_read_b128 v[148:151], v145
	ds_read_b128 v[152:155], v145 offset:1024
	ds_read_b128 v[156:159], v145 offset:2048
	ds_read_b128 v[160:163], v145 offset:3072
	ds_read_b128 v[164:167], v146
	ds_read_b128 v[170:173], v146 offset:1024
	ds_read_b128 v[174:177], v146 offset:2048
	ds_read_b128 v[178:181], v146 offset:3072
	s_add_i32 s53, s2, 2
	s_add_u32 s3, s30, 0xffd50080
	s_addc_u32 s34, s31, -1
	s_cmp_eq_u32 s18, s2
	s_cselect_b32 s2, s26, s28
	s_cselect_b32 s35, s25, s34
	s_cselect_b32 s34, s24, s3
	s_cselect_b32 s3, s27, s52
	v_lshl_add_u64 v[214:215], s[30:31], 0, v[140:141]
	s_add_i32 m0, s37, 0xc000
	ds_read_b128 v[182:185], v147
	ds_read_b128 v[186:189], v147 offset:1024
	ds_read_b128 v[190:193], v147 offset:2048
	ds_read_b128 v[194:197], v147 offset:3072
	ds_read_b128 v[198:201], v147 offset:4096
	ds_read_b128 v[202:205], v147 offset:5120
	ds_read_b128 v[206:209], v147 offset:6144
	ds_read_b128 v[210:213], v147 offset:7168
	global_load_lds_dwordx4 v[214:215], off
	v_lshl_add_u64 v[214:215], s[30:31], 0, v[142:143]
	s_add_i32 m0, s37, 0xe000
	s_nop 0
	global_load_lds_dwordx4 v[214:215], off
	s_waitcnt vmcnt(8)
	s_waitcnt lgkmcnt(0)
	s_barrier
	s_setprio 1
	s_waitcnt lgkmcnt(0)
	v_mfma_f32_16x16x32_bf16 v[124:127], v[148:151], v[182:185], v[124:127]
	v_mfma_f32_16x16x32_bf16 v[124:127], v[152:155], v[186:189], v[124:127]
	v_mfma_f32_16x16x32_bf16 v[120:123], v[160:163], v[186:189], v[120:123]
	v_mfma_f32_16x16x32_bf16 v[120:123], v[156:159], v[182:185], v[120:123]
	v_mfma_f32_16x16x32_bf16 v[100:103], v[156:159], v[190:193], v[100:103]
	v_mfma_f32_16x16x32_bf16 v[100:103], v[160:163], v[194:197], v[100:103]
	v_mfma_f32_16x16x32_bf16 v[108:111], v[152:155], v[194:197], v[108:111]
	v_mfma_f32_16x16x32_bf16 v[108:111], v[148:151], v[190:193], v[108:111]
	v_mfma_f32_16x16x32_bf16 v[92:95], v[148:151], v[198:201], v[92:95]
	v_mfma_f32_16x16x32_bf16 v[92:95], v[152:155], v[202:205], v[92:95]
	v_mfma_f32_16x16x32_bf16 v[84:87], v[160:163], v[202:205], v[84:87]
	v_mfma_f32_16x16x32_bf16 v[84:87], v[156:159], v[198:201], v[84:87]
	v_mfma_f32_16x16x32_bf16 v[68:71], v[156:159], v[206:209], v[68:71]
	v_mfma_f32_16x16x32_bf16 v[68:71], v[160:163], v[210:213], v[68:71]
	v_mfma_f32_16x16x32_bf16 v[76:79], v[152:155], v[210:213], v[76:79]
	v_mfma_f32_16x16x32_bf16 v[76:79], v[148:151], v[206:209], v[76:79]
	s_setprio 0
	s_setprio 1
	v_mfma_f32_16x16x32_bf16 v[116:119], v[164:167], v[182:185], v[116:119]
	v_mfma_f32_16x16x32_bf16 v[116:119], v[170:173], v[186:189], v[116:119]
	v_mfma_f32_16x16x32_bf16 v[112:115], v[178:181], v[186:189], v[112:115]
	v_mfma_f32_16x16x32_bf16 v[112:115], v[174:177], v[182:185], v[112:115]
	v_mfma_f32_16x16x32_bf16 v[96:99], v[174:177], v[190:193], v[96:99]
	v_mfma_f32_16x16x32_bf16 v[96:99], v[178:181], v[194:197], v[96:99]
	v_mfma_f32_16x16x32_bf16 v[104:107], v[170:173], v[194:197], v[104:107]
	v_mfma_f32_16x16x32_bf16 v[104:107], v[164:167], v[190:193], v[104:107]
	v_mfma_f32_16x16x32_bf16 v[88:91], v[164:167], v[198:201], v[88:91]
	v_mfma_f32_16x16x32_bf16 v[88:91], v[170:173], v[202:205], v[88:91]
	v_mfma_f32_16x16x32_bf16 v[80:83], v[178:181], v[202:205], v[80:83]
	v_mfma_f32_16x16x32_bf16 v[80:83], v[174:177], v[198:201], v[80:83]
	v_mfma_f32_16x16x32_bf16 v[64:67], v[174:177], v[206:209], v[64:67]
	v_mfma_f32_16x16x32_bf16 v[64:67], v[178:181], v[210:213], v[64:67]
	v_mfma_f32_16x16x32_bf16 v[72:75], v[170:173], v[210:213], v[72:75]
	v_mfma_f32_16x16x32_bf16 v[72:75], v[164:167], v[206:209], v[72:75]
	s_setprio 0
	s_barrier
	s_add_i32 s56, s46, s33
	v_lshl_add_u64 v[214:215], s[2:3], 0, v[134:135]
	s_mov_b32 m0, s56
	ds_read_b128 v[182:185], v147 offset:16384
	ds_read_b128 v[186:189], v147 offset:17408
	ds_read_b128 v[190:193], v147 offset:18432
	ds_read_b128 v[194:197], v147 offset:19456
	ds_read_b128 v[198:201], v147 offset:20480
	ds_read_b128 v[202:205], v147 offset:21504
	ds_read_b128 v[206:209], v147 offset:22528
	ds_read_b128 v[210:213], v147 offset:23552
	global_load_lds_dwordx4 v[214:215], off
	s_add_i32 m0, s56, 0x2000
	s_add_u32 s56, s2, 0x2b0000
	v_lshl_add_u64 v[216:217], s[2:3], 0, v[138:139]
	s_addc_u32 s57, s3, 0
	s_add_i32 s58, s47, s33
	global_load_lds_dwordx4 v[216:217], off
	v_lshl_add_u64 v[218:219], s[56:57], 0, v[134:135]
	s_mov_b32 m0, s58
	v_lshl_add_u64 v[220:221], s[34:35], 0, v[136:137]
	global_load_lds_dwordx4 v[218:219], off
	v_lshl_add_u64 v[218:219], s[56:57], 0, v[138:139]
	s_add_i32 m0, s58, 0x2000
	s_nop 0
	global_load_lds_dwordx4 v[218:219], off
	v_lshl_add_u64 v[218:219], s[34:35], 0, v[128:129]
	s_mov_b32 m0, s37
	s_nop 0
	global_load_lds_dwordx4 v[218:219], off
	s_mov_b32 m0, s38
	s_nop 0
	global_load_lds_dwordx4 v[220:221], off
	s_waitcnt vmcnt(8)
	s_waitcnt lgkmcnt(0)
	s_barrier
	s_setprio 1
	s_waitcnt lgkmcnt(0)
	v_mfma_f32_16x16x32_bf16 v[60:63], v[148:151], v[182:185], v[60:63]
	v_mfma_f32_16x16x32_bf16 v[60:63], v[152:155], v[186:189], v[60:63]
	v_mfma_f32_16x16x32_bf16 v[52:55], v[160:163], v[186:189], v[52:55]
	v_mfma_f32_16x16x32_bf16 v[52:55], v[156:159], v[182:185], v[52:55]
	v_mfma_f32_16x16x32_bf16 v[36:39], v[156:159], v[190:193], v[36:39]
	v_mfma_f32_16x16x32_bf16 v[36:39], v[160:163], v[194:197], v[36:39]
	v_mfma_f32_16x16x32_bf16 v[44:47], v[152:155], v[194:197], v[44:47]
	v_mfma_f32_16x16x32_bf16 v[44:47], v[148:151], v[190:193], v[44:47]
	v_mfma_f32_16x16x32_bf16 v[28:31], v[148:151], v[198:201], v[28:31]
	v_mfma_f32_16x16x32_bf16 v[28:31], v[152:155], v[202:205], v[28:31]
	v_mfma_f32_16x16x32_bf16 v[20:23], v[160:163], v[202:205], v[20:23]
	v_mfma_f32_16x16x32_bf16 v[20:23], v[156:159], v[198:201], v[20:23]
	v_mfma_f32_16x16x32_bf16 v[4:7], v[156:159], v[206:209], v[4:7]
	v_mfma_f32_16x16x32_bf16 v[4:7], v[160:163], v[210:213], v[4:7]
	v_mfma_f32_16x16x32_bf16 v[12:15], v[152:155], v[210:213], v[12:15]
	v_mfma_f32_16x16x32_bf16 v[12:15], v[148:151], v[206:209], v[12:15]
	s_setprio 0
	s_setprio 1
	v_mfma_f32_16x16x32_bf16 v[56:59], v[164:167], v[182:185], v[56:59]
	v_mfma_f32_16x16x32_bf16 v[56:59], v[170:173], v[186:189], v[56:59]
	v_mfma_f32_16x16x32_bf16 v[48:51], v[178:181], v[186:189], v[48:51]
	v_mfma_f32_16x16x32_bf16 v[48:51], v[174:177], v[182:185], v[48:51]
	v_mfma_f32_16x16x32_bf16 v[32:35], v[174:177], v[190:193], v[32:35]
	v_mfma_f32_16x16x32_bf16 v[32:35], v[178:181], v[194:197], v[32:35]
	v_mfma_f32_16x16x32_bf16 v[40:43], v[170:173], v[194:197], v[40:43]
	v_mfma_f32_16x16x32_bf16 v[40:43], v[164:167], v[190:193], v[40:43]
	v_mfma_f32_16x16x32_bf16 v[24:27], v[164:167], v[198:201], v[24:27]
	v_mfma_f32_16x16x32_bf16 v[24:27], v[170:173], v[202:205], v[24:27]
	v_mfma_f32_16x16x32_bf16 v[16:19], v[178:181], v[202:205], v[16:19]
	v_mfma_f32_16x16x32_bf16 v[16:19], v[174:177], v[198:201], v[16:19]
	v_mfma_f32_16x16x32_bf16 v[0:3], v[174:177], v[206:209], v[0:3]
	v_mfma_f32_16x16x32_bf16 v[0:3], v[178:181], v[210:213], v[0:3]
	v_mfma_f32_16x16x32_bf16 v[8:11], v[170:173], v[210:213], v[8:11]
	v_mfma_f32_16x16x32_bf16 v[8:11], v[164:167], v[206:209], v[8:11]
	s_setprio 0
	s_barrier
	s_add_i32 s56, 0, 0x18000
	s_add_i32 s57, 0, 0x1c000
	v_add_u32_e32 v160, s56, v133
	v_add_u32_e32 v168, s57, v133
	ds_read_b128 v[148:151], v160
	ds_read_b128 v[152:155], v160 offset:1024
	ds_read_b128 v[156:159], v160 offset:2048
	ds_read_b128 v[160:163], v160 offset:3072
	ds_read_b128 v[164:167], v168
	ds_read_b128 v[170:173], v168 offset:1024
	ds_read_b128 v[174:177], v168 offset:2048
	ds_read_b128 v[178:181], v168 offset:3072
	s_add_u32 s34, s34, 0x2b0000
	s_addc_u32 s35, s35, 0
	s_mov_b32 m0, s39
	v_lshl_add_u64 v[222:223], s[34:35], 0, v[128:129]
	ds_read_b128 v[182:185], v147 offset:32768
	ds_read_b128 v[186:189], v147 offset:33792
	ds_read_b128 v[190:193], v147 offset:34816
	ds_read_b128 v[194:197], v147 offset:35840
	ds_read_b128 v[198:201], v147 offset:36864
	ds_read_b128 v[202:205], v147 offset:37888
	ds_read_b128 v[206:209], v147 offset:38912
	ds_read_b128 v[210:213], v147 offset:39936
	global_load_lds_dwordx4 v[222:223], off
	v_lshl_add_u64 v[222:223], s[34:35], 0, v[136:137]
	s_mov_b32 m0, s40
	s_nop 0
	global_load_lds_dwordx4 v[222:223], off
	s_waitcnt vmcnt(8)
	s_waitcnt lgkmcnt(0)
	s_barrier
	s_setprio 1
	s_waitcnt lgkmcnt(0)
	v_mfma_f32_16x16x32_bf16 v[124:127], v[148:151], v[182:185], v[124:127]
	v_mfma_f32_16x16x32_bf16 v[124:127], v[152:155], v[186:189], v[124:127]
	v_mfma_f32_16x16x32_bf16 v[120:123], v[160:163], v[186:189], v[120:123]
	v_mfma_f32_16x16x32_bf16 v[120:123], v[156:159], v[182:185], v[120:123]
	v_mfma_f32_16x16x32_bf16 v[100:103], v[156:159], v[190:193], v[100:103]
	v_mfma_f32_16x16x32_bf16 v[100:103], v[160:163], v[194:197], v[100:103]
	v_mfma_f32_16x16x32_bf16 v[108:111], v[152:155], v[194:197], v[108:111]
	v_mfma_f32_16x16x32_bf16 v[108:111], v[148:151], v[190:193], v[108:111]
	v_mfma_f32_16x16x32_bf16 v[92:95], v[148:151], v[198:201], v[92:95]
	v_mfma_f32_16x16x32_bf16 v[92:95], v[152:155], v[202:205], v[92:95]
	v_mfma_f32_16x16x32_bf16 v[84:87], v[160:163], v[202:205], v[84:87]
	v_mfma_f32_16x16x32_bf16 v[84:87], v[156:159], v[198:201], v[84:87]
	v_mfma_f32_16x16x32_bf16 v[68:71], v[156:159], v[206:209], v[68:71]
	v_mfma_f32_16x16x32_bf16 v[68:71], v[160:163], v[210:213], v[68:71]
	v_mfma_f32_16x16x32_bf16 v[76:79], v[152:155], v[210:213], v[76:79]
	v_mfma_f32_16x16x32_bf16 v[76:79], v[148:151], v[206:209], v[76:79]
	s_setprio 0
	s_setprio 1
	v_mfma_f32_16x16x32_bf16 v[116:119], v[164:167], v[182:185], v[116:119]
	v_mfma_f32_16x16x32_bf16 v[116:119], v[170:173], v[186:189], v[116:119]
	v_mfma_f32_16x16x32_bf16 v[112:115], v[178:181], v[186:189], v[112:115]
	v_mfma_f32_16x16x32_bf16 v[112:115], v[174:177], v[182:185], v[112:115]
	v_mfma_f32_16x16x32_bf16 v[96:99], v[174:177], v[190:193], v[96:99]
	v_mfma_f32_16x16x32_bf16 v[96:99], v[178:181], v[194:197], v[96:99]
	v_mfma_f32_16x16x32_bf16 v[104:107], v[170:173], v[194:197], v[104:107]
	v_mfma_f32_16x16x32_bf16 v[104:107], v[164:167], v[190:193], v[104:107]
	v_mfma_f32_16x16x32_bf16 v[88:91], v[164:167], v[198:201], v[88:91]
	v_mfma_f32_16x16x32_bf16 v[88:91], v[170:173], v[202:205], v[88:91]
	v_mfma_f32_16x16x32_bf16 v[80:83], v[178:181], v[202:205], v[80:83]
	v_mfma_f32_16x16x32_bf16 v[80:83], v[174:177], v[198:201], v[80:83]
	v_mfma_f32_16x16x32_bf16 v[64:67], v[174:177], v[206:209], v[64:67]
	v_mfma_f32_16x16x32_bf16 v[64:67], v[178:181], v[210:213], v[64:67]
	v_mfma_f32_16x16x32_bf16 v[72:75], v[170:173], v[210:213], v[72:75]
	v_mfma_f32_16x16x32_bf16 v[72:75], v[164:167], v[206:209], v[72:75]
	s_setprio 0
	s_barrier
	s_add_i32 s34, s56, s33
	v_lshl_add_u64 v[214:215], v[214:215], 0, s[6:7]
	s_mov_b32 m0, s34
	ds_read_b128 v[182:185], v147 offset:49152
	ds_read_b128 v[186:189], v147 offset:50176
	ds_read_b128 v[190:193], v147 offset:51200
	ds_read_b128 v[194:197], v147 offset:52224
	ds_read_b128 v[198:201], v147 offset:53248
	ds_read_b128 v[202:205], v147 offset:54272
	ds_read_b128 v[206:209], v147 offset:55296
	ds_read_b128 v[210:213], v147 offset:56320
	global_load_lds_dwordx4 v[214:215], off
	s_add_i32 m0, s34, 0x2000
	s_add_u32 s2, s2, 0x2b0080
	v_lshl_add_u64 v[214:215], v[216:217], 0, s[6:7]
	s_addc_u32 s3, s3, 0
	s_add_i32 s34, s57, s33
	global_load_lds_dwordx4 v[214:215], off
	v_lshl_add_u64 v[214:215], s[2:3], 0, v[134:135]
	s_mov_b32 m0, s34
	s_nop 0
	global_load_lds_dwordx4 v[214:215], off
	v_lshl_add_u64 v[214:215], s[2:3], 0, v[138:139]
	s_add_i32 m0, s34, 0x2000
	s_nop 0
	global_load_lds_dwordx4 v[214:215], off
	v_lshl_add_u64 v[214:215], v[218:219], 0, s[6:7]
	s_mov_b32 m0, s42
	s_nop 0
	global_load_lds_dwordx4 v[214:215], off
	v_lshl_add_u64 v[214:215], v[220:221], 0, s[6:7]
	s_mov_b32 m0, s43
	s_nop 0
	global_load_lds_dwordx4 v[214:215], off
	s_waitcnt vmcnt(8)
	s_waitcnt lgkmcnt(0)
	s_barrier
	s_setprio 1
	s_waitcnt lgkmcnt(0)
	v_mfma_f32_16x16x32_bf16 v[60:63], v[148:151], v[182:185], v[60:63]
	v_mfma_f32_16x16x32_bf16 v[60:63], v[152:155], v[186:189], v[60:63]
	v_mfma_f32_16x16x32_bf16 v[52:55], v[160:163], v[186:189], v[52:55]
	v_mfma_f32_16x16x32_bf16 v[52:55], v[156:159], v[182:185], v[52:55]
	v_mfma_f32_16x16x32_bf16 v[36:39], v[156:159], v[190:193], v[36:39]
	v_mfma_f32_16x16x32_bf16 v[36:39], v[160:163], v[194:197], v[36:39]
	v_mfma_f32_16x16x32_bf16 v[44:47], v[152:155], v[194:197], v[44:47]
	v_mfma_f32_16x16x32_bf16 v[44:47], v[148:151], v[190:193], v[44:47]
	v_mfma_f32_16x16x32_bf16 v[28:31], v[148:151], v[198:201], v[28:31]
	v_mfma_f32_16x16x32_bf16 v[28:31], v[152:155], v[202:205], v[28:31]
	v_mfma_f32_16x16x32_bf16 v[20:23], v[160:163], v[202:205], v[20:23]
	v_mfma_f32_16x16x32_bf16 v[20:23], v[156:159], v[198:201], v[20:23]
	v_mfma_f32_16x16x32_bf16 v[4:7], v[156:159], v[206:209], v[4:7]
	v_mfma_f32_16x16x32_bf16 v[4:7], v[160:163], v[210:213], v[4:7]
	v_mfma_f32_16x16x32_bf16 v[12:15], v[152:155], v[210:213], v[12:15]
	v_mfma_f32_16x16x32_bf16 v[12:15], v[148:151], v[206:209], v[12:15]
	s_setprio 0
	s_setprio 1
	v_mfma_f32_16x16x32_bf16 v[56:59], v[164:167], v[182:185], v[56:59]
	v_mfma_f32_16x16x32_bf16 v[56:59], v[170:173], v[186:189], v[56:59]
	v_mfma_f32_16x16x32_bf16 v[48:51], v[178:181], v[186:189], v[48:51]
	v_mfma_f32_16x16x32_bf16 v[48:51], v[174:177], v[182:185], v[48:51]
	v_mfma_f32_16x16x32_bf16 v[32:35], v[174:177], v[190:193], v[32:35]
	v_mfma_f32_16x16x32_bf16 v[32:35], v[178:181], v[194:197], v[32:35]
	v_mfma_f32_16x16x32_bf16 v[40:43], v[170:173], v[194:197], v[40:43]
	v_mfma_f32_16x16x32_bf16 v[40:43], v[164:167], v[190:193], v[40:43]
	v_mfma_f32_16x16x32_bf16 v[24:27], v[164:167], v[198:201], v[24:27]
	v_mfma_f32_16x16x32_bf16 v[24:27], v[170:173], v[202:205], v[24:27]
	v_mfma_f32_16x16x32_bf16 v[16:19], v[178:181], v[202:205], v[16:19]
	v_mfma_f32_16x16x32_bf16 v[16:19], v[174:177], v[198:201], v[16:19]
	v_mfma_f32_16x16x32_bf16 v[0:3], v[174:177], v[206:209], v[0:3]
	v_mfma_f32_16x16x32_bf16 v[0:3], v[178:181], v[210:213], v[0:3]
	v_mfma_f32_16x16x32_bf16 v[8:11], v[170:173], v[210:213], v[8:11]
	v_mfma_f32_16x16x32_bf16 v[8:11], v[164:167], v[206:209], v[8:11]
	s_setprio 0
	s_barrier
	s_add_u32 s30, s30, 0x100
	s_addc_u32 s31, s31, 0
	s_add_u32 s28, s28, 0x100
	s_addc_u32 s52, s52, 0
	s_cmp_ge_i32 s53, s29
	s_mov_b32 s2, s53
	s_cbranch_scc0 .LBB0_1128
